# merged blocks + mid-block B1 wait + last STAGE of slots B/D issued inside the following MFMA block (race-free overwrite ordering), vmcnt(6)
# speedup vs baseline: 1.0027x; 1.0027x over previous
; #define PG8_STAGE(bufoff, gbase, voff) do { _Pragma("unroll") for (int _i = 0; _i < 2; ++_i) \
;     __builtin_amdgcn_global_load_lds((const unsigned*)((const char*)(gbase) + (voff)[_i]), (LAS unsigned*)(lds + (bufoff) + ldsw + _i * 8192), 16, 0, 0); } while (0)
; #define PG8_LDA(dst, b, h) do { _Pragma("unroll") for (int m = 0; m < 4; ++m) _Pragma("unroll") for (int k = 0; k < 2; ++k) dst[m][k] = *(const LAS bf16x8*)(lds + PG8_SA(b, h) + aoff + m * 2048 + k * 1024); } while (0)
; #define PG8_LDB(dst, b, h) do { _Pragma("unroll") for (int n = 0; n < 2; ++n) _Pragma("unroll") for (int k = 0; k < 2; ++k) dst[n][k] = *(const LAS bf16x8*)(lds + PG8_SB(b, h) + boff + n * 2048 + k * 1024); } while (0)
; #define PG8_MMA(ai, bj, At, Bt) do { __builtin_amdgcn_s_setprio(1); _Pragma("unroll") for (int m = 0; m < 4; ++m) _Pragma("unroll") for (int n = 0; n < 2; ++n) _Pragma("unroll") for (int k = 0; k < 2; ++k) \
;     acc[ai][bj][m][n] = __builtin_amdgcn_mfma_f32_16x16x32_bf16(Bt[n][k], At[m][k], acc[ai][bj][m][n], 0, 0, 0); __builtin_amdgcn_s_setprio(0); } while (0)
; #define PG8_WAIT_V(n) asm volatile("s_waitcnt vmcnt(" #n ")" ::: "memory")
; #define PG8_WAIT_L(n) asm volatile("s_waitcnt lgkmcnt(" #n ")" ::: "memory")
; #define PG8_BAR __builtin_amdgcn_s_barrier()
; #define PG8_SCHED __builtin_amdgcn_sched_barrier(0)
; template <class Epi, class Sched = StaticOrder>
; DI void gemm_phase(LAS unsigned char* lds, const Gemm g, const Sched& S, const Epi& E) {
;     ...
;       PG8_LDB(B0, 0, 0); PG8_SCHED; PG8_LDA(At, 0, 0); PG8_STAGE(PG8_SA(1, 1), a1 + hstep, voffA);
;       PG8_WAIT_L(8); PG8_BAR; PG8_WAIT_L(0); PG8_MMA(0, 0, At, B0); PG8_BAR; PG8_SCHED;
;       PG8_LDB(B1, 0, 1); PG8_STAGE(PG8_SB(0, 0), b2, voffB);
;       PG8_BAR; PG8_WAIT_L(0); PG8_MMA(0, 1, At, B1); PG8_BAR;
;       PG8_LDA(At, 0, 1); PG8_STAGE(PG8_SA(0, 0), a2, voffA);
;       PG8_BAR; PG8_WAIT_L(0); PG8_MMA(1, 0, At, B0); PG8_BAR; PG8_SCHED;
;       PG8_STAGE(PG8_SB(0, 1), b2 + hstep, voffB);
;       PG8_WAIT_V(6); PG8_BAR; PG8_MMA(1, 1, At, B1); PG8_BAR;
.LBB0_346:
	ds_read_b128 v[128:131], v173
	ds_read_b128 v[132:135], v173 offset:1024
	ds_read_b128 v[154:157], v173 offset:2048
	ds_read_b128 v[158:161], v173 offset:3072
	s_add_u32 s8, s6, 0xfff80080
	s_addc_u32 s9, s7, -1
	s_cmp_eq_u32 s52, 28
	s_cselect_b32 s11, s31, s9
	s_cselect_b32 s10, s42, s8
	s_cselect_b32 s9, s29, s45
	s_cselect_b32 s8, s43, s44
	s_add_i32 m0, s48, 0xc000
	ds_read_b128 v[162:165], v174
	ds_read_b128 v[166:169], v174 offset:1024
	ds_read_b128 v[178:181], v174 offset:2048
	ds_read_b128 v[182:185], v174 offset:3072
	ds_read_b128 v[186:189], v174 offset:4096
	ds_read_b128 v[190:193], v174 offset:5120
	ds_read_b128 v[194:197], v174 offset:6144
	ds_read_b128 v[198:201], v174 offset:7168
	global_load_lds_dwordx4 v146, s[6:7]
	s_add_i32 m0, s48, 0xe000
	s_nop 0
	global_load_lds_dwordx4 v148, s[6:7]
	ds_read_b128 v[202:205], v175
	ds_read_b128 v[206:209], v175 offset:1024
	ds_read_b128 v[212:215], v175 offset:2048
	ds_read_b128 v[216:219], v175 offset:3072
	s_waitcnt vmcnt(8)
	s_waitcnt lgkmcnt(4)
	s_setprio 1
	s_barrier
	v_mfma_f32_16x16x32_bf16 v[124:127], v[128:131], v[162:165], v[124:127]
	v_mfma_f32_16x16x32_bf16 v[120:123], v[154:157], v[162:165], v[120:123]
	v_mfma_f32_16x16x32_bf16 v[108:111], v[128:131], v[178:181], v[108:111]
	v_mfma_f32_16x16x32_bf16 v[104:107], v[154:157], v[178:181], v[104:107]
	v_mfma_f32_16x16x32_bf16 v[100:103], v[128:131], v[186:189], v[100:103]
	v_mfma_f32_16x16x32_bf16 v[92:95], v[154:157], v[186:189], v[92:95]
	v_mfma_f32_16x16x32_bf16 v[84:87], v[128:131], v[194:197], v[84:87]
	v_mfma_f32_16x16x32_bf16 v[76:79], v[154:157], v[194:197], v[76:79]
	v_mfma_f32_16x16x32_bf16 v[124:127], v[132:135], v[166:169], v[124:127]
	v_mfma_f32_16x16x32_bf16 v[120:123], v[158:161], v[166:169], v[120:123]
	v_mfma_f32_16x16x32_bf16 v[108:111], v[132:135], v[182:185], v[108:111]
	v_mfma_f32_16x16x32_bf16 v[104:107], v[158:161], v[182:185], v[104:107]
	v_mfma_f32_16x16x32_bf16 v[100:103], v[132:135], v[190:193], v[100:103]
	v_mfma_f32_16x16x32_bf16 v[92:95], v[158:161], v[190:193], v[92:95]
	v_mfma_f32_16x16x32_bf16 v[84:87], v[132:135], v[198:201], v[84:87]
	v_mfma_f32_16x16x32_bf16 v[76:79], v[158:161], v[198:201], v[76:79]
	s_waitcnt lgkmcnt(0)
	v_mfma_f32_16x16x32_bf16 v[116:119], v[202:205], v[162:165], v[116:119]
	v_mfma_f32_16x16x32_bf16 v[112:115], v[212:215], v[162:165], v[112:115]
	v_mfma_f32_16x16x32_bf16 v[96:99], v[202:205], v[178:181], v[96:99]
	v_mfma_f32_16x16x32_bf16 v[88:91], v[212:215], v[178:181], v[88:91]
	v_mfma_f32_16x16x32_bf16 v[80:83], v[202:205], v[186:189], v[80:83]
	v_mfma_f32_16x16x32_bf16 v[72:75], v[212:215], v[186:189], v[72:75]
	v_mfma_f32_16x16x32_bf16 v[68:71], v[202:205], v[194:197], v[68:71]
	v_mfma_f32_16x16x32_bf16 v[64:67], v[212:215], v[194:197], v[64:67]
	v_mfma_f32_16x16x32_bf16 v[116:119], v[206:209], v[166:169], v[116:119]
	v_mfma_f32_16x16x32_bf16 v[112:115], v[216:219], v[166:169], v[112:115]
	v_mfma_f32_16x16x32_bf16 v[96:99], v[206:209], v[182:185], v[96:99]
	v_mfma_f32_16x16x32_bf16 v[88:91], v[216:219], v[182:185], v[88:91]
	v_mfma_f32_16x16x32_bf16 v[80:83], v[206:209], v[190:193], v[80:83]
	v_mfma_f32_16x16x32_bf16 v[72:75], v[216:219], v[190:193], v[72:75]
	v_mfma_f32_16x16x32_bf16 v[68:71], v[206:209], v[198:201], v[68:71]
	v_mfma_f32_16x16x32_bf16 v[64:67], v[216:219], v[198:201], v[64:67]
	s_barrier
	s_setprio 0
	s_add_i32 s53, s65, s41
	s_add_u32 s98, s8, 0x80
	s_addc_u32 s99, s9, 0
	s_add_u32 s100, s10, 0x80
	s_addc_u32 s101, s11, 0
	s_mov_b32 m0, s53
	s_nop 0
	global_load_lds_dwordx4 v140, s[8:9]
	s_add_i32 m0, s53, 0x2000
	s_nop 0
	global_load_lds_dwordx4 v136, s[8:9]
	s_mov_b32 m0, s48
	ds_read_b128 v[162:165], v174 offset:16384
	ds_read_b128 v[166:169], v174 offset:17408
	ds_read_b128 v[178:181], v174 offset:18432
	ds_read_b128 v[182:185], v174 offset:19456
	ds_read_b128 v[186:189], v174 offset:20480
	ds_read_b128 v[190:193], v174 offset:21504
	ds_read_b128 v[194:197], v174 offset:22528
	ds_read_b128 v[198:201], v174 offset:23552
	global_load_lds_dwordx4 v142, s[10:11]
	s_mov_b32 m0, s49
	s_nop 0
	global_load_lds_dwordx4 v138, s[10:11]
	s_add_u32 s54, s8, 0x80000
	s_addc_u32 s55, s9, 0
	s_add_i32 s53, s72, s41
	s_waitcnt vmcnt(6)
	s_waitcnt lgkmcnt(0)
	s_setprio 1
	s_barrier
	v_mfma_f32_16x16x32_bf16 v[60:63], v[128:131], v[162:165], v[60:63]
	s_mov_b32 m0, s53
	v_mfma_f32_16x16x32_bf16 v[56:59], v[154:157], v[162:165], v[56:59]
	global_load_lds_dwordx4 v140, s[54:55]
	v_mfma_f32_16x16x32_bf16 v[52:55], v[128:131], v[178:181], v[52:55]
	s_bitset1_b32 m0, 13
	v_mfma_f32_16x16x32_bf16 v[44:47], v[154:157], v[178:181], v[44:47]
	global_load_lds_dwordx4 v136, s[54:55]
	v_mfma_f32_16x16x32_bf16 v[36:39], v[128:131], v[186:189], v[36:39]
	v_mfma_f32_16x16x32_bf16 v[28:31], v[154:157], v[186:189], v[28:31]
	v_mfma_f32_16x16x32_bf16 v[20:23], v[128:131], v[194:197], v[20:23]
	v_mfma_f32_16x16x32_bf16 v[12:15], v[154:157], v[194:197], v[12:15]
	v_mfma_f32_16x16x32_bf16 v[60:63], v[132:135], v[166:169], v[60:63]
	v_mfma_f32_16x16x32_bf16 v[56:59], v[158:161], v[166:169], v[56:59]
	v_mfma_f32_16x16x32_bf16 v[52:55], v[132:135], v[182:185], v[52:55]
	v_mfma_f32_16x16x32_bf16 v[44:47], v[158:161], v[182:185], v[44:47]
	v_mfma_f32_16x16x32_bf16 v[36:39], v[132:135], v[190:193], v[36:39]
	v_mfma_f32_16x16x32_bf16 v[28:31], v[158:161], v[190:193], v[28:31]
	v_mfma_f32_16x16x32_bf16 v[20:23], v[132:135], v[198:201], v[20:23]
	v_mfma_f32_16x16x32_bf16 v[12:15], v[158:161], v[198:201], v[12:15]
	v_mfma_f32_16x16x32_bf16 v[48:51], v[202:205], v[162:165], v[48:51]
	v_mfma_f32_16x16x32_bf16 v[40:43], v[212:215], v[162:165], v[40:43]
	v_mfma_f32_16x16x32_bf16 v[32:35], v[202:205], v[178:181], v[32:35]
	v_mfma_f32_16x16x32_bf16 v[24:27], v[212:215], v[178:181], v[24:27]
	v_mfma_f32_16x16x32_bf16 v[16:19], v[202:205], v[186:189], v[16:19]
	v_mfma_f32_16x16x32_bf16 v[8:11], v[212:215], v[186:189], v[8:11]
	v_mfma_f32_16x16x32_bf16 v[4:7], v[202:205], v[194:197], v[4:7]
	v_mfma_f32_16x16x32_bf16 v[0:3], v[212:215], v[194:197], v[0:3]
	v_mfma_f32_16x16x32_bf16 v[48:51], v[206:209], v[166:169], v[48:51]
	v_mfma_f32_16x16x32_bf16 v[40:43], v[216:219], v[166:169], v[40:43]
	v_mfma_f32_16x16x32_bf16 v[32:35], v[206:209], v[182:185], v[32:35]
	v_mfma_f32_16x16x32_bf16 v[24:27], v[216:219], v[182:185], v[24:27]
	v_mfma_f32_16x16x32_bf16 v[16:19], v[206:209], v[190:193], v[16:19]
	v_mfma_f32_16x16x32_bf16 v[8:11], v[216:219], v[190:193], v[8:11]
	v_mfma_f32_16x16x32_bf16 v[4:7], v[206:209], v[198:201], v[4:7]
	v_mfma_f32_16x16x32_bf16 v[0:3], v[216:219], v[198:201], v[0:3]
	s_barrier
; #define PG8_STAGE(bufoff, gbase, voff) do { _Pragma("unroll") for (int _i = 0; _i < 2; ++_i) \
;     __builtin_amdgcn_global_load_lds((const unsigned*)((const char*)(gbase) + (voff)[_i]), (LAS unsigned*)(lds + (bufoff) + ldsw + _i * 8192), 16, 0, 0); } while (0)
; #define PG8_LDA(dst, b, h) do { _Pragma("unroll") for (int m = 0; m < 4; ++m) _Pragma("unroll") for (int k = 0; k < 2; ++k) dst[m][k] = *(const LAS bf16x8*)(lds + PG8_SA(b, h) + aoff + m * 2048 + k * 1024); } while (0)
; #define PG8_LDB(dst, b, h) do { _Pragma("unroll") for (int n = 0; n < 2; ++n) _Pragma("unroll") for (int k = 0; k < 2; ++k) dst[n][k] = *(const LAS bf16x8*)(lds + PG8_SB(b, h) + boff + n * 2048 + k * 1024); } while (0)
; #define PG8_MMA(ai, bj, At, Bt) do { __builtin_amdgcn_s_setprio(1); _Pragma("unroll") for (int m = 0; m < 4; ++m) _Pragma("unroll") for (int n = 0; n < 2; ++n) _Pragma("unroll") for (int k = 0; k < 2; ++k) \
;     acc[ai][bj][m][n] = __builtin_amdgcn_mfma_f32_16x16x32_bf16(Bt[n][k], At[m][k], acc[ai][bj][m][n], 0, 0, 0); __builtin_amdgcn_s_setprio(0); } while (0)
; #define PG8_WAIT_V(n) asm volatile("s_waitcnt vmcnt(" #n ")" ::: "memory")
; #define PG8_WAIT_L(n) asm volatile("s_waitcnt lgkmcnt(" #n ")" ::: "memory")
; #define PG8_BAR __builtin_amdgcn_s_barrier()
; #define PG8_SCHED __builtin_amdgcn_sched_barrier(0)
; template <class Epi, class Sched = StaticOrder>
; DI void gemm_phase(LAS unsigned char* lds, const Gemm g, const Sched& S, const Epi& E) {
;     ...
;       PG8_LDB(B0, 1, 0); PG8_SCHED; PG8_LDA(At, 1, 0); PG8_STAGE(PG8_SA(0, 1), a2 + hstep, voffA);
;       PG8_WAIT_L(8); PG8_BAR; PG8_WAIT_L(0); PG8_MMA(0, 0, At, B0); PG8_BAR; PG8_SCHED;
;       PG8_LDB(B1, 1, 1); PG8_STAGE(PG8_SB(1, 0), b3, voffB);
;       PG8_BAR; PG8_WAIT_L(0); PG8_MMA(0, 1, At, B1); PG8_BAR;
;       PG8_LDA(At, 1, 1); PG8_STAGE(PG8_SA(1, 0), a3, voffA);
;       PG8_BAR; PG8_WAIT_L(0); PG8_MMA(1, 0, At, B0); PG8_BAR; PG8_SCHED;
;       PG8_STAGE(PG8_SB(1, 1), b3 + hstep, voffB);
;       PG8_WAIT_V(6); PG8_BAR; PG8_MMA(1, 1, At, B1); PG8_BAR;
	s_setprio 0
	s_add_i32 s53, 0, 0x18000
	v_add_u32_e32 v158, s53, v171
	ds_read_b128 v[128:131], v158
	ds_read_b128 v[132:135], v158 offset:1024
	ds_read_b128 v[154:157], v158 offset:2048
	ds_read_b128 v[158:161], v158 offset:3072
	s_add_u32 s10, s10, 0x80000
	s_addc_u32 s11, s11, 0
	s_mov_b32 m0, s50
	ds_read_b128 v[162:165], v174 offset:32768
	ds_read_b128 v[166:169], v174 offset:33792
	ds_read_b128 v[178:181], v174 offset:34816
	ds_read_b128 v[182:185], v174 offset:35840
	ds_read_b128 v[186:189], v174 offset:36864
	ds_read_b128 v[190:193], v174 offset:37888
	ds_read_b128 v[194:197], v174 offset:38912
	ds_read_b128 v[198:201], v174 offset:39936
	global_load_lds_dwordx4 v142, s[10:11]
	s_mov_b32 m0, s51
	s_nop 0
	global_load_lds_dwordx4 v138, s[10:11]
	s_add_i32 s10, 0, 0x1c000
	v_add_u32_e32 v177, s10, v171
	ds_read_b128 v[202:205], v177
	ds_read_b128 v[206:209], v177 offset:1024
	ds_read_b128 v[212:215], v177 offset:2048
	ds_read_b128 v[216:219], v177 offset:3072
	s_waitcnt vmcnt(8)
	s_waitcnt lgkmcnt(4)
	s_setprio 1
	s_barrier
	v_mfma_f32_16x16x32_bf16 v[124:127], v[128:131], v[162:165], v[124:127]
	v_mfma_f32_16x16x32_bf16 v[120:123], v[154:157], v[162:165], v[120:123]
	v_mfma_f32_16x16x32_bf16 v[108:111], v[128:131], v[178:181], v[108:111]
	v_mfma_f32_16x16x32_bf16 v[104:107], v[154:157], v[178:181], v[104:107]
	v_mfma_f32_16x16x32_bf16 v[100:103], v[128:131], v[186:189], v[100:103]
	v_mfma_f32_16x16x32_bf16 v[92:95], v[154:157], v[186:189], v[92:95]
	v_mfma_f32_16x16x32_bf16 v[84:87], v[128:131], v[194:197], v[84:87]
	v_mfma_f32_16x16x32_bf16 v[76:79], v[154:157], v[194:197], v[76:79]
	v_mfma_f32_16x16x32_bf16 v[124:127], v[132:135], v[166:169], v[124:127]
	v_mfma_f32_16x16x32_bf16 v[120:123], v[158:161], v[166:169], v[120:123]
	v_mfma_f32_16x16x32_bf16 v[108:111], v[132:135], v[182:185], v[108:111]
	v_mfma_f32_16x16x32_bf16 v[104:107], v[158:161], v[182:185], v[104:107]
	v_mfma_f32_16x16x32_bf16 v[100:103], v[132:135], v[190:193], v[100:103]
	v_mfma_f32_16x16x32_bf16 v[92:95], v[158:161], v[190:193], v[92:95]
	v_mfma_f32_16x16x32_bf16 v[84:87], v[132:135], v[198:201], v[84:87]
	v_mfma_f32_16x16x32_bf16 v[76:79], v[158:161], v[198:201], v[76:79]
	s_waitcnt lgkmcnt(0)
	v_mfma_f32_16x16x32_bf16 v[116:119], v[202:205], v[162:165], v[116:119]
	v_mfma_f32_16x16x32_bf16 v[112:115], v[212:215], v[162:165], v[112:115]
	v_mfma_f32_16x16x32_bf16 v[96:99], v[202:205], v[178:181], v[96:99]
	v_mfma_f32_16x16x32_bf16 v[88:91], v[212:215], v[178:181], v[88:91]
	v_mfma_f32_16x16x32_bf16 v[80:83], v[202:205], v[186:189], v[80:83]
	v_mfma_f32_16x16x32_bf16 v[72:75], v[212:215], v[186:189], v[72:75]
	v_mfma_f32_16x16x32_bf16 v[68:71], v[202:205], v[194:197], v[68:71]
	v_mfma_f32_16x16x32_bf16 v[64:67], v[212:215], v[194:197], v[64:67]
	v_mfma_f32_16x16x32_bf16 v[116:119], v[206:209], v[166:169], v[116:119]
	v_mfma_f32_16x16x32_bf16 v[112:115], v[216:219], v[166:169], v[112:115]
	v_mfma_f32_16x16x32_bf16 v[96:99], v[206:209], v[182:185], v[96:99]
	v_mfma_f32_16x16x32_bf16 v[88:91], v[216:219], v[182:185], v[88:91]
	v_mfma_f32_16x16x32_bf16 v[80:83], v[206:209], v[190:193], v[80:83]
	v_mfma_f32_16x16x32_bf16 v[72:75], v[216:219], v[190:193], v[72:75]
	v_mfma_f32_16x16x32_bf16 v[68:71], v[206:209], v[198:201], v[68:71]
	v_mfma_f32_16x16x32_bf16 v[64:67], v[216:219], v[198:201], v[64:67]
	s_barrier
	s_setprio 0
	s_add_i32 s11, s53, s41
	s_mov_b32 m0, s11
	s_nop 0
	global_load_lds_dwordx4 v140, s[98:99]
	s_add_i32 m0, s11, 0x2000
	s_nop 0
	global_load_lds_dwordx4 v136, s[98:99]
	s_mov_b32 m0, s56
	ds_read_b128 v[162:165], v174 offset:49152
	ds_read_b128 v[166:169], v174 offset:50176
	ds_read_b128 v[178:181], v174 offset:51200
	ds_read_b128 v[182:185], v174 offset:52224
	ds_read_b128 v[186:189], v174 offset:53248
	ds_read_b128 v[190:193], v174 offset:54272
	ds_read_b128 v[194:197], v174 offset:55296
	ds_read_b128 v[198:201], v174 offset:56320
	global_load_lds_dwordx4 v142, s[100:101]
	s_mov_b32 m0, s57
	s_nop 0
	global_load_lds_dwordx4 v138, s[100:101]
	s_add_u32 s8, s8, 0x80080
	s_addc_u32 s9, s9, 0
	s_add_i32 s10, s10, s41
	s_add_i32 s52, s52, 2
	s_add_u32 s6, s6, 0x100
	s_addc_u32 s7, s7, 0
	s_add_u32 s44, s44, 0x100
	s_addc_u32 s45, s45, 0
	s_cmp_gt_u32 s52, 29
	s_waitcnt vmcnt(6)
	s_waitcnt lgkmcnt(0)
	s_setprio 1
	s_barrier
	v_mfma_f32_16x16x32_bf16 v[60:63], v[128:131], v[162:165], v[60:63]
	s_mov_b32 m0, s10
	v_mfma_f32_16x16x32_bf16 v[56:59], v[154:157], v[162:165], v[56:59]
	global_load_lds_dwordx4 v140, s[8:9]
	v_mfma_f32_16x16x32_bf16 v[52:55], v[128:131], v[178:181], v[52:55]
	s_bitset1_b32 m0, 13
	v_mfma_f32_16x16x32_bf16 v[44:47], v[154:157], v[178:181], v[44:47]
	global_load_lds_dwordx4 v136, s[8:9]
	v_mfma_f32_16x16x32_bf16 v[36:39], v[128:131], v[186:189], v[36:39]
	v_mfma_f32_16x16x32_bf16 v[28:31], v[154:157], v[186:189], v[28:31]
	v_mfma_f32_16x16x32_bf16 v[20:23], v[128:131], v[194:197], v[20:23]
	v_mfma_f32_16x16x32_bf16 v[12:15], v[154:157], v[194:197], v[12:15]
	v_mfma_f32_16x16x32_bf16 v[60:63], v[132:135], v[166:169], v[60:63]
	v_mfma_f32_16x16x32_bf16 v[56:59], v[158:161], v[166:169], v[56:59]
	v_mfma_f32_16x16x32_bf16 v[52:55], v[132:135], v[182:185], v[52:55]
	v_mfma_f32_16x16x32_bf16 v[44:47], v[158:161], v[182:185], v[44:47]
	v_mfma_f32_16x16x32_bf16 v[36:39], v[132:135], v[190:193], v[36:39]
	v_mfma_f32_16x16x32_bf16 v[28:31], v[158:161], v[190:193], v[28:31]
	v_mfma_f32_16x16x32_bf16 v[20:23], v[132:135], v[198:201], v[20:23]
	v_mfma_f32_16x16x32_bf16 v[12:15], v[158:161], v[198:201], v[12:15]
	v_mfma_f32_16x16x32_bf16 v[48:51], v[202:205], v[162:165], v[48:51]
	v_mfma_f32_16x16x32_bf16 v[40:43], v[212:215], v[162:165], v[40:43]
	v_mfma_f32_16x16x32_bf16 v[32:35], v[202:205], v[178:181], v[32:35]
	v_mfma_f32_16x16x32_bf16 v[24:27], v[212:215], v[178:181], v[24:27]
	v_mfma_f32_16x16x32_bf16 v[16:19], v[202:205], v[186:189], v[16:19]
	v_mfma_f32_16x16x32_bf16 v[8:11], v[212:215], v[186:189], v[8:11]
	v_mfma_f32_16x16x32_bf16 v[4:7], v[202:205], v[194:197], v[4:7]
	v_mfma_f32_16x16x32_bf16 v[0:3], v[212:215], v[194:197], v[0:3]
	v_mfma_f32_16x16x32_bf16 v[48:51], v[206:209], v[166:169], v[48:51]
	v_mfma_f32_16x16x32_bf16 v[40:43], v[216:219], v[166:169], v[40:43]
	v_mfma_f32_16x16x32_bf16 v[32:35], v[206:209], v[182:185], v[32:35]
	v_mfma_f32_16x16x32_bf16 v[24:27], v[216:219], v[182:185], v[24:27]
	v_mfma_f32_16x16x32_bf16 v[16:19], v[206:209], v[190:193], v[16:19]
	v_mfma_f32_16x16x32_bf16 v[8:11], v[216:219], v[190:193], v[8:11]
	v_mfma_f32_16x16x32_bf16 v[4:7], v[206:209], v[198:201], v[4:7]
	v_mfma_f32_16x16x32_bf16 v[0:3], v[216:219], v[198:201], v[0:3]
	s_barrier
; DI unsigned pack2(float lo, float hi) { f32x2 v = {lo, hi}; bf16v2 r = __builtin_convertvector(v, bf16v2); return __builtin_bit_cast(unsigned, r); }
; DI float row_rstd(const float* ssq, int row, int fq) {
;   const f32x4 a = *(const f32x4*)(ssq + (size_t)row * 32 + fq * 8), b = *(const f32x4*)(ssq + (size_t)row * 32 + fq * 8 + 4);
;   float sm = ((a[0] + a[1]) + (a[2] + a[3])) + ((b[0] + b[1]) + (b[2] + b[3]));
;   sm += __shfl_xor(sm, 16); sm += __shfl_xor(sm, 32);
;   return rsqrtf(sm * (1.0f / 2048.f) + 1e-6f);
; }
;   DI void operator()(const f32x4 (&acc)[2][2][4][2], const Unit& u, int wr, int wc, int fr, int fq) const {
;     const int row0 = u.pm * BM + wr * 64 + fr, col0 = u.pn * BM + wc * 32 + 8 * fq;
;     float rsv[2][4];
; #pragma unroll
;     for (int ai = 0; ai < 2; ++ai)
; #pragma unroll
;       for (int m = 0; m < 4; ++m) rsv[ai][m] = row_rstd(ssq, row0 + ai * HALF + m * 16, fq);
; #pragma unroll
;     for (int ai = 0; ai < 2; ++ai)
; #pragma unroll
;       for (int m = 0; m < 4; ++m) {
;         const int row = row0 + ai * HALF + m * 16;
;         const float rs = rsv[ai][m];
;         bf16_t* rowp = O + (size_t)row * ldc + col0;
; #pragma unroll
;         for (int bj = 0; bj < 2; ++bj) {
;           const f32x4 v0 = acc[ai][bj][m][0] * rs, v1 = acc[ai][bj][m][1] * rs;
;           u32x4 w; w.x = pack2(v0[0], v0[1]); w.y = pack2(v0[2], v0[3]); w.z = pack2(v1[0], v1[1]); w.w = pack2(v1[2], v1[3]);
;           *(u32x4*)(rowp + bj * HALF) = w;
;         }
;       }
;   }
	s_setprio 0
	s_cbranch_scc0 .LBB0_346
	v_lshl_add_u32 v168, s4, 8, v170
	v_ashrrev_i32_e32 v169, 31, v168
	v_or_b32_e32 v154, 16, v168
	v_lshlrev_b64 v[128:129], 7, v[168:169]
	v_ashrrev_i32_e32 v155, 31, v154
	v_lshl_add_u64 v[128:129], v[144:145], 0, v[128:129]
	v_lshlrev_b64 v[156:157], 7, v[154:155]
	global_load_dwordx4 v[132:135], v[128:129], off
	s_nop 0
	global_load_dwordx4 v[128:131], v[128:129], off offset:16
	v_lshl_add_u64 v[156:157], v[144:145], 0, v[156:157]
	global_load_dwordx4 v[178:181], v[156:157], off
	global_load_dwordx4 v[182:185], v[156:157], off offset:16
	v_or_b32_e32 v160, 32, v168
	v_ashrrev_i32_e32 v161, 31, v160
	v_lshlrev_b64 v[156:157], 7, v[160:161]
	v_lshl_add_u64 v[156:157], v[144:145], 0, v[156:157]
	global_load_dwordx4 v[186:189], v[156:157], off
	global_load_dwordx4 v[190:193], v[156:157], off offset:16
	v_or_b32_e32 v156, 48, v168
	v_ashrrev_i32_e32 v157, 31, v156
	v_lshlrev_b64 v[158:159], 7, v[156:157]
	v_lshl_add_u64 v[158:159], v[144:145], 0, v[158:159]
	global_load_dwordx4 v[194:197], v[158:159], off
	global_load_dwordx4 v[198:201], v[158:159], off offset:16
	v_add_u32_e32 v164, 0x80, v168
	v_ashrrev_i32_e32 v165, 31, v164
	v_lshlrev_b64 v[158:159], 7, v[164:165]
	v_lshl_add_u64 v[158:159], v[144:145], 0, v[158:159]
	global_load_dwordx4 v[202:205], v[158:159], off
	global_load_dwordx4 v[206:209], v[158:159], off offset:16
	v_add_u32_e32 v158, 0x90, v168
	v_ashrrev_i32_e32 v159, 31, v158
	v_lshlrev_b64 v[162:163], 7, v[158:159]
	v_lshl_add_u64 v[162:163], v[144:145], 0, v[162:163]
	global_load_dwordx4 v[212:215], v[162:163], off
	global_load_dwordx4 v[216:219], v[162:163], off offset:16
	v_add_u32_e32 v166, 0xa0, v168
	v_ashrrev_i32_e32 v167, 31, v166
	v_lshlrev_b64 v[162:163], 7, v[166:167]
	v_lshl_add_u64 v[162:163], v[144:145], 0, v[162:163]
	global_load_dwordx4 v[220:223], v[162:163], off
	global_load_dwordx4 v[224:227], v[162:163], off offset:16
	v_add_u32_e32 v162, 0xb0, v168
	v_ashrrev_i32_e32 v163, 31, v162
	v_lshlrev_b64 v[228:229], 7, v[162:163]
	v_lshl_add_u64 v[232:233], v[144:145], 0, v[228:229]
	global_load_dwordx4 v[228:231], v[232:233], off
	s_nop 0
	global_load_dwordx4 v[232:235], v[232:233], off offset:16
	s_waitcnt vmcnt(0)
	v_mov_b32_e32 v236, v132
	v_mov_b32_e32 v237, v128
	v_mov_b32_e32 v128, v133
	v_mov_b32_e32 v132, v134
	v_mov_b32_e32 v133, v130
	v_mov_b32_e32 v130, v135
	v_pk_add_f32 v[130:131], v[132:133], v[130:131]
	v_mov_b32_e32 v132, v178
	v_mov_b32_e32 v133, v182
	v_mov_b32_e32 v182, v179
	v_mov_b32_e32 v134, v180
	v_mov_b32_e32 v135, v184
	v_mov_b32_e32 v184, v181
	v_pk_add_f32 v[128:129], v[236:237], v[128:129]
	v_pk_add_f32 v[132:133], v[132:133], v[182:183]
	v_pk_add_f32 v[134:135], v[134:135], v[184:185]
	v_pk_add_f32 v[128:129], v[128:129], v[130:131]
	v_pk_add_f32 v[130:131], v[132:133], v[134:135]
	v_mov_b32_e32 v133, v128
	v_mov_b32_e32 v132, v130
	v_and_b32_e32 v130, 64, v176
	v_add_u32_e32 v155, 64, v130
	v_xor_b32_e32 v130, 16, v176
	v_cmp_lt_i32_e32 vcc, v130, v155
	v_mov_b32_e32 v128, v131
	v_pk_add_f32 v[128:129], v[132:133], v[128:129]
	v_cndmask_b32_e32 v130, v176, v130, vcc
	v_lshlrev_b32_e32 v157, 2, v130
	ds_bpermute_b32 v131, v157, v129
	ds_bpermute_b32 v130, v157, v128
	v_mov_b32_e32 v178, v186
	v_mov_b32_e32 v179, v190
	v_mov_b32_e32 v190, v187
	v_mov_b32_e32 v186, v194
	s_waitcnt lgkmcnt(0)
	v_pk_add_f32 v[128:129], v[128:129], v[130:131]
	v_xor_b32_e32 v130, 32, v176
	v_cmp_lt_i32_e32 vcc, v130, v155
	v_mov_b32_e32 v187, v198
	v_mov_b32_e32 v198, v195
	v_cndmask_b32_e32 v130, v176, v130, vcc
	v_lshlrev_b32_e32 v155, 2, v130
	ds_bpermute_b32 v131, v155, v129
	ds_bpermute_b32 v130, v155, v128
	v_pk_add_f32 v[182:183], v[186:187], v[198:199]
	v_mov_b32_e32 v180, v188
	v_mov_b32_e32 v181, v192
	v_mov_b32_e32 v192, v189
	s_waitcnt lgkmcnt(0)
	v_pk_add_f32 v[128:129], v[128:129], v[130:131]
	v_mov_b64_e32 v[130:131], s[26:27]
	v_pk_fma_f32 v[128:129], v[128:129], s[24:25], v[130:131] op_sel_hi:[1,0,0]
	v_mov_b32_e32 v188, v196
	v_mul_f32_e32 v159, 0x4b800000, v129
	v_cmp_gt_f32_e32 vcc, s73, v129
	v_mov_b32_e32 v189, v200
	v_mov_b32_e32 v200, v197
	v_cndmask_b32_e32 v129, v129, v159, vcc
	v_rsq_f32_e32 v129, v129
	v_pk_add_f32 v[178:179], v[178:179], v[190:191]
	v_pk_add_f32 v[180:181], v[180:181], v[192:193]
	v_pk_add_f32 v[184:185], v[188:189], v[200:201]
	v_mul_f32_e32 v159, 0x45800000, v129
	v_cndmask_b32_e32 v198, v129, v159, vcc
	v_pk_mul_f32 v[126:127], v[126:127], v[198:199] op_sel_hi:[1,0]
	v_pk_mul_f32 v[124:125], v[124:125], v[198:199] op_sel_hi:[1,0]
	v_pk_mul_f32 v[122:123], v[122:123], v[198:199] op_sel_hi:[1,0]
	v_pk_mul_f32 v[120:121], v[120:121], v[198:199] op_sel_hi:[1,0]
	v_cvt_pk_bf16_f32 v124, v124, v125
	v_cvt_pk_bf16_f32 v125, v126, v127
	v_cvt_pk_bf16_f32 v127, v122, v123
	v_lshl_or_b32 v122, s5, 8, v172
	v_cvt_pk_bf16_f32 v126, v120, v121
	v_ashrrev_i32_e32 v123, 31, v122
	v_mov_b64_e32 v[120:121], s[2:3]
	v_mad_i64_i32 v[168:169], s[4:5], v168, s76, v[120:121]
	v_lshlrev_b64 v[122:123], 1, v[122:123]
	v_lshl_add_u64 v[168:169], v[168:169], 0, v[122:123]
	global_store_dwordx4 v[168:169], v[124:127], off
	v_mov_b32_e32 v194, v202
	v_mov_b32_e32 v195, v206
	v_pk_add_f32 v[124:125], v[178:179], v[180:181]
	v_pk_add_f32 v[126:127], v[182:183], v[184:185]
	v_mov_b32_e32 v179, v124
	v_mov_b32_e32 v178, v126
	v_mov_b32_e32 v124, v127
	v_pk_add_f32 v[124:125], v[178:179], v[124:125]
	ds_bpermute_b32 v127, v157, v125
	ds_bpermute_b32 v126, v157, v124
	v_mov_b32_e32 v206, v203
	v_mov_b32_e32 v196, v204
	v_mov_b32_e32 v197, v208
	v_mov_b32_e32 v208, v205
	v_mov_b32_e32 v202, v212
	v_mov_b32_e32 v203, v216
	v_mov_b32_e32 v216, v213
	v_mov_b32_e32 v204, v214
	v_mov_b32_e32 v205, v218
	v_mov_b32_e32 v218, v215
	v_pk_add_f32 v[186:187], v[194:195], v[206:207]
	v_pk_add_f32 v[188:189], v[196:197], v[208:209]
	v_pk_add_f32 v[190:191], v[202:203], v[216:217]
	v_pk_add_f32 v[192:193], v[204:205], v[218:219]
	v_pk_mul_f32 v[178:179], v[114:115], v[198:199] op_sel_hi:[1,0]
	s_waitcnt lgkmcnt(0)
; DI unsigned pack2(float lo, float hi) { f32x2 v = {lo, hi}; bf16v2 r = __builtin_convertvector(v, bf16v2); return __builtin_bit_cast(unsigned, r); }
;   DI void operator()(const f32x4 (&acc)[2][2][4][2], const Unit& u, int wr, int wc, int fr, int fq) const {
;     const int row0 = u.pm * BM + wr * 64 + fr, col0 = u.pn * BM + wc * 32 + 8 * fq;
;     float rsv[2][4];
; #pragma unroll
;     for (int ai = 0; ai < 2; ++ai)
; #pragma unroll
;       for (int m = 0; m < 4; ++m) rsv[ai][m] = row_rstd(ssq, row0 + ai * HALF + m * 16, fq);
; #pragma unroll
;     for (int ai = 0; ai < 2; ++ai)
; #pragma unroll
;       for (int m = 0; m < 4; ++m) {
;         const int row = row0 + ai * HALF + m * 16;
;         const float rs = rsv[ai][m];
;         bf16_t* rowp = O + (size_t)row * ldc + col0;
; #pragma unroll
;         for (int bj = 0; bj < 2; ++bj) {
;           const f32x4 v0 = acc[ai][bj][m][0] * rs, v1 = acc[ai][bj][m][1] * rs;
;           u32x4 w; w.x = pack2(v0[0], v0[1]); w.y = pack2(v0[2], v0[3]); w.z = pack2(v1[0], v1[1]); w.w = pack2(v1[2], v1[3]);
;           *(u32x4*)(rowp + bj * HALF) = w;
;         }
;       }
;   }
	v_pk_add_f32 v[114:115], v[124:125], v[126:127]
	v_pk_add_f32 v[126:127], v[186:187], v[188:189]
	v_pk_add_f32 v[180:181], v[190:191], v[192:193]
	v_mov_b32_e32 v183, v126
	v_mov_b32_e32 v182, v180
	v_mov_b32_e32 v126, v181
	v_pk_add_f32 v[126:127], v[182:183], v[126:127]
	ds_bpermute_b32 v125, v155, v115
	ds_bpermute_b32 v124, v155, v114
	ds_bpermute_b32 v181, v157, v127
	ds_bpermute_b32 v180, v157, v126
	v_mul_f32_e32 v129, 0x4b800000, v128
	v_cmp_gt_f32_e32 vcc, s73, v128
	s_waitcnt lgkmcnt(2)
	v_pk_add_f32 v[114:115], v[114:115], v[124:125]
	v_mov_b32_e32 v194, v220
	s_waitcnt lgkmcnt(0)
	v_pk_add_f32 v[124:125], v[126:127], v[180:181]
	ds_bpermute_b32 v127, v155, v125
	ds_bpermute_b32 v126, v155, v124
	v_pk_fma_f32 v[114:115], v[114:115], s[24:25], v[130:131] op_sel_hi:[1,0,0]
	v_cndmask_b32_e32 v159, v128, v129, vcc
	v_mul_f32_e32 v128, 0x4b800000, v115
	v_cmp_gt_f32_e64 s[4:5], s73, v115
	v_cmp_gt_f32_e64 s[6:7], s73, v114
	v_mov_b32_e32 v195, v224
	v_cndmask_b32_e64 v161, v115, v128, s[4:5]
	v_mul_f32_e32 v115, 0x4b800000, v114
	v_mov_b32_e32 v224, v221
	v_mov_b32_e32 v196, v222
	v_mov_b32_e32 v197, v226
	v_mov_b32_e32 v226, v223
	v_cndmask_b32_e64 v163, v114, v115, s[6:7]
	s_waitcnt lgkmcnt(0)
	v_pk_add_f32 v[114:115], v[124:125], v[126:127]
	v_pk_add_f32 v[132:133], v[194:195], v[224:225]
	v_pk_add_f32 v[134:135], v[196:197], v[226:227]
	v_mov_b32_e32 v194, v228
	v_mov_b32_e32 v195, v232
	v_mov_b32_e32 v232, v229
	v_mov_b32_e32 v196, v230
	v_mov_b32_e32 v197, v234
	v_mov_b32_e32 v234, v231
	v_pk_fma_f32 v[114:115], v[114:115], s[24:25], v[130:131] op_sel_hi:[1,0,0]
	v_pk_add_f32 v[194:195], v[194:195], v[232:233]
	v_pk_add_f32 v[196:197], v[196:197], v[234:235]
	v_mul_f32_e32 v124, 0x4b800000, v115
	v_cmp_gt_f32_e64 s[8:9], s73, v115
	v_pk_add_f32 v[126:127], v[194:195], v[196:197]
	v_cmp_gt_f32_e64 s[10:11], s73, v114
	v_cndmask_b32_e64 v165, v115, v124, s[8:9]
	v_pk_add_f32 v[124:125], v[132:133], v[134:135]
	v_mov_b32_e32 v128, v126
	v_mov_b32_e32 v129, v124
	v_mov_b32_e32 v124, v127
	v_pk_add_f32 v[124:125], v[128:129], v[124:125]
	ds_bpermute_b32 v127, v157, v125
	ds_bpermute_b32 v126, v157, v124
	v_rsq_f32_e32 v128, v159
	v_mul_f32_e32 v115, 0x4b800000, v114
	v_cndmask_b32_e64 v129, v114, v115, s[10:11]
	v_pk_mul_f32 v[116:117], v[116:117], v[198:199] op_sel_hi:[1,0]
	s_waitcnt lgkmcnt(0)
	v_pk_add_f32 v[114:115], v[124:125], v[126:127]
	ds_bpermute_b32 v125, v155, v115
	ds_bpermute_b32 v124, v155, v114
	v_mul_f32_e32 v126, 0x45800000, v128
	v_rsq_f32_e32 v127, v161
	v_cndmask_b32_e32 v126, v128, v126, vcc
	v_rsq_f32_e32 v128, v163
	s_waitcnt lgkmcnt(0)
	v_pk_add_f32 v[114:115], v[114:115], v[124:125]
	v_mul_f32_e32 v124, 0x45800000, v127
	v_cndmask_b32_e64 v124, v127, v124, s[4:5]
	v_mul_f32_e32 v127, 0x45800000, v128
	v_pk_fma_f32 v[114:115], v[114:115], s[24:25], v[130:131] op_sel_hi:[1,0,0]
	v_rsq_f32_e32 v125, v165
	v_cndmask_b32_e64 v128, v128, v127, s[6:7]
	v_rsq_f32_e32 v127, v129
	v_mul_f32_e32 v129, 0x4b800000, v115
	v_cmp_gt_f32_e32 vcc, s73, v115
	v_cmp_gt_f32_e64 s[4:5], s73, v114
	v_pk_mul_f32 v[118:119], v[118:119], v[198:199] op_sel_hi:[1,0]
	v_cndmask_b32_e32 v129, v115, v129, vcc
	v_mul_f32_e32 v115, 0x4b800000, v114
	v_cndmask_b32_e64 v131, v114, v115, s[4:5]
	v_cvt_pk_bf16_f32 v114, v116, v117
	v_rsq_f32_e32 v117, v129
	v_cvt_pk_bf16_f32 v115, v118, v119
	v_rsq_f32_e32 v119, v131
	v_mul_f32_e32 v116, 0x45800000, v125
	v_pk_mul_f32 v[112:113], v[112:113], v[198:199] op_sel_hi:[1,0]
	v_cndmask_b32_e64 v118, v125, v116, s[8:9]
	v_mul_f32_e32 v116, 0x45800000, v127
	v_cndmask_b32_e64 v130, v127, v116, s[10:11]
	v_cvt_pk_bf16_f32 v116, v112, v113
	v_mul_f32_e32 v112, 0x45800000, v117
	v_cndmask_b32_e32 v132, v117, v112, vcc
	v_mul_f32_e32 v112, 0x45800000, v119
	v_cvt_pk_bf16_f32 v117, v178, v179
	v_cndmask_b32_e64 v112, v119, v112, s[4:5]
	global_store_dwordx4 v[168:169], v[114:117], off offset:256
	v_pk_mul_f32 v[110:111], v[110:111], v[126:127] op_sel_hi:[1,0]
	v_pk_mul_f32 v[108:109], v[108:109], v[126:127] op_sel_hi:[1,0]
	v_mad_i64_i32 v[114:115], s[4:5], v154, s76, v[120:121]
	v_pk_mul_f32 v[116:117], v[106:107], v[126:127] op_sel_hi:[1,0]
	v_pk_mul_f32 v[106:107], v[104:105], v[126:127] op_sel_hi:[1,0]
	v_lshl_add_u64 v[114:115], v[114:115], 0, v[122:123]
	v_cvt_pk_bf16_f32 v104, v108, v109
	v_cvt_pk_bf16_f32 v105, v110, v111
	v_cvt_pk_bf16_f32 v106, v106, v107
	v_cvt_pk_bf16_f32 v107, v116, v117
	global_store_dwordx4 v[114:115], v[104:107], off
	v_pk_mul_f32 v[98:99], v[98:99], v[126:127] op_sel_hi:[1,0]
	v_pk_mul_f32 v[96:97], v[96:97], v[126:127] op_sel_hi:[1,0]
	v_pk_mul_f32 v[104:105], v[90:91], v[126:127] op_sel_hi:[1,0]
	v_pk_mul_f32 v[90:91], v[88:89], v[126:127] op_sel_hi:[1,0]
	v_cvt_pk_bf16_f32 v88, v96, v97
	v_cvt_pk_bf16_f32 v89, v98, v99
	v_cvt_pk_bf16_f32 v90, v90, v91
	v_cvt_pk_bf16_f32 v91, v104, v105
	global_store_dwordx4 v[114:115], v[88:91], off offset:256
	v_pk_mul_f32 v[94:95], v[94:95], v[124:125] op_sel_hi:[1,0]
	v_pk_mul_f32 v[92:93], v[92:93], v[124:125] op_sel_hi:[1,0]
	v_mad_i64_i32 v[88:89], s[4:5], v160, s76, v[120:121]
	v_lshl_add_u64 v[96:97], v[88:89], 0, v[122:123]
	v_pk_mul_f32 v[90:91], v[102:103], v[124:125] op_sel_hi:[1,0]
	v_pk_mul_f32 v[88:89], v[100:101], v[124:125] op_sel_hi:[1,0]
	v_pk_mul_f32 v[82:83], v[82:83], v[124:125] op_sel_hi:[1,0]
	v_cvt_pk_bf16_f32 v88, v88, v89
	v_cvt_pk_bf16_f32 v89, v90, v91
	v_cvt_pk_bf16_f32 v90, v92, v93
; DI unsigned pack2(float lo, float hi) { f32x2 v = {lo, hi}; bf16v2 r = __builtin_convertvector(v, bf16v2); return __builtin_bit_cast(unsigned, r); }
; #define PG8_WAIT_V(n) asm volatile("s_waitcnt vmcnt(" #n ")" ::: "memory")
; #define PG8_BAR __builtin_amdgcn_s_barrier()
;   DI void operator()(const f32x4 (&acc)[2][2][4][2], const Unit& u, int wr, int wc, int fr, int fq) const {
;     ...
;     for (int ai = 0; ai < 2; ++ai)
; #pragma unroll
;       for (int m = 0; m < 4; ++m) {
;         const int row = row0 + ai * HALF + m * 16;
;         const float rs = rsv[ai][m];
;         bf16_t* rowp = O + (size_t)row * ldc + col0;
; #pragma unroll
;         for (int bj = 0; bj < 2; ++bj) {
;           const f32x4 v0 = acc[ai][bj][m][0] * rs, v1 = acc[ai][bj][m][1] * rs;
;           u32x4 w; w.x = pack2(v0[0], v0[1]); w.y = pack2(v0[2], v0[3]); w.z = pack2(v1[0], v1[1]); w.w = pack2(v1[2], v1[3]);
;           *(u32x4*)(rowp + bj * HALF) = w;
;         }
;       }
;   }
; template <class Epi, class Sched = StaticOrder>
; DI void gemm_phase(LAS unsigned char* lds, const Gemm g, const Sched& S, const Epi& E) {
;     ...
;     E(acc, cur, wr, wc, fr, fq);
;     if (!has_next) break;
; #pragma unroll
;     for (int a = 0; a < 2; ++a)
; #pragma unroll
;       for (int b = 0; b < 2; ++b)
; #pragma unroll
;         for (int m = 0; m < 4; ++m)
; #pragma unroll
;           for (int n = 0; n < 2; ++n) acc[a][b][m][n] = (f32x4){0.f, 0.f, 0.f, 0.f};
;     cur = nxt; cA = nA; cB = nB; ++ui;
;   }
;   PG8_WAIT_V(0);
;   if (wr == 0) PG8_BAR;
	v_cvt_pk_bf16_f32 v91, v94, v95
	global_store_dwordx4 v[96:97], v[88:91], off
	v_pk_mul_f32 v[80:81], v[80:81], v[124:125] op_sel_hi:[1,0]
	v_pk_mul_f32 v[78:79], v[78:79], v[128:129] op_sel_hi:[1,0]
	v_pk_mul_f32 v[88:89], v[74:75], v[124:125] op_sel_hi:[1,0]
	v_pk_mul_f32 v[74:75], v[72:73], v[124:125] op_sel_hi:[1,0]
	v_cvt_pk_bf16_f32 v72, v80, v81
	v_cvt_pk_bf16_f32 v73, v82, v83
	v_cvt_pk_bf16_f32 v74, v74, v75
	v_cvt_pk_bf16_f32 v75, v88, v89
	global_store_dwordx4 v[96:97], v[72:75], off offset:256
	v_pk_mul_f32 v[76:77], v[76:77], v[128:129] op_sel_hi:[1,0]
	v_pk_mul_f32 v[70:71], v[70:71], v[128:129] op_sel_hi:[1,0]
	v_mad_i64_i32 v[72:73], s[4:5], v156, s76, v[120:121]
	v_lshl_add_u64 v[80:81], v[72:73], 0, v[122:123]
	v_pk_mul_f32 v[74:75], v[86:87], v[128:129] op_sel_hi:[1,0]
	v_pk_mul_f32 v[72:73], v[84:85], v[128:129] op_sel_hi:[1,0]
	v_pk_mul_f32 v[68:69], v[68:69], v[128:129] op_sel_hi:[1,0]
	v_cvt_pk_bf16_f32 v72, v72, v73
	v_cvt_pk_bf16_f32 v73, v74, v75
	v_cvt_pk_bf16_f32 v74, v76, v77
	v_cvt_pk_bf16_f32 v75, v78, v79
	global_store_dwordx4 v[80:81], v[72:75], off
	v_pk_mul_f32 v[62:63], v[62:63], v[118:119] op_sel_hi:[1,0]
	v_pk_mul_f32 v[60:61], v[60:61], v[118:119] op_sel_hi:[1,0]
	v_pk_mul_f32 v[72:73], v[66:67], v[128:129] op_sel_hi:[1,0]
	v_pk_mul_f32 v[66:67], v[64:65], v[128:129] op_sel_hi:[1,0]
	v_cvt_pk_bf16_f32 v64, v68, v69
	v_cvt_pk_bf16_f32 v65, v70, v71
	v_cvt_pk_bf16_f32 v66, v66, v67
	v_cvt_pk_bf16_f32 v67, v72, v73
	global_store_dwordx4 v[80:81], v[64:67], off offset:256
	v_pk_mul_f32 v[50:51], v[50:51], v[118:119] op_sel_hi:[1,0]
	v_pk_mul_f32 v[48:49], v[48:49], v[118:119] op_sel_hi:[1,0]
	v_mad_i64_i32 v[64:65], s[4:5], v164, s76, v[120:121]
	v_pk_mul_f32 v[66:67], v[58:59], v[118:119] op_sel_hi:[1,0]
	v_pk_mul_f32 v[58:59], v[56:57], v[118:119] op_sel_hi:[1,0]
	v_lshl_add_u64 v[64:65], v[64:65], 0, v[122:123]
	v_cvt_pk_bf16_f32 v56, v60, v61
	v_cvt_pk_bf16_f32 v57, v62, v63
	v_cvt_pk_bf16_f32 v58, v58, v59
	v_cvt_pk_bf16_f32 v59, v66, v67
	global_store_dwordx4 v[64:65], v[56:59], off
	v_pk_mul_f32 v[46:47], v[46:47], v[130:131] op_sel_hi:[1,0]
	v_pk_mul_f32 v[44:45], v[44:45], v[130:131] op_sel_hi:[1,0]
	v_pk_mul_f32 v[56:57], v[42:43], v[118:119] op_sel_hi:[1,0]
	v_pk_mul_f32 v[42:43], v[40:41], v[118:119] op_sel_hi:[1,0]
	v_cvt_pk_bf16_f32 v40, v48, v49
	v_cvt_pk_bf16_f32 v41, v50, v51
	v_cvt_pk_bf16_f32 v42, v42, v43
	v_cvt_pk_bf16_f32 v43, v56, v57
	global_store_dwordx4 v[64:65], v[40:43], off offset:256
	v_pk_mul_f32 v[34:35], v[34:35], v[130:131] op_sel_hi:[1,0]
	v_pk_mul_f32 v[32:33], v[32:33], v[130:131] op_sel_hi:[1,0]
	v_mad_i64_i32 v[40:41], s[4:5], v158, s76, v[120:121]
	v_lshl_add_u64 v[48:49], v[40:41], 0, v[122:123]
	v_pk_mul_f32 v[42:43], v[54:55], v[130:131] op_sel_hi:[1,0]
	v_pk_mul_f32 v[40:41], v[52:53], v[130:131] op_sel_hi:[1,0]
	v_pk_mul_f32 v[30:31], v[30:31], v[132:133] op_sel_hi:[1,0]
	v_cvt_pk_bf16_f32 v40, v40, v41
	v_cvt_pk_bf16_f32 v41, v42, v43
	v_cvt_pk_bf16_f32 v42, v44, v45
	v_cvt_pk_bf16_f32 v43, v46, v47
	global_store_dwordx4 v[48:49], v[40:43], off
	v_pk_mul_f32 v[28:29], v[28:29], v[132:133] op_sel_hi:[1,0]
	v_pk_mul_f32 v[18:19], v[18:19], v[132:133] op_sel_hi:[1,0]
	v_pk_mul_f32 v[40:41], v[26:27], v[130:131] op_sel_hi:[1,0]
	v_pk_mul_f32 v[26:27], v[24:25], v[130:131] op_sel_hi:[1,0]
	v_cvt_pk_bf16_f32 v24, v32, v33
	v_cvt_pk_bf16_f32 v25, v34, v35
	v_cvt_pk_bf16_f32 v26, v26, v27
	v_cvt_pk_bf16_f32 v27, v40, v41
	global_store_dwordx4 v[48:49], v[24:27], off offset:256
	v_pk_mul_f32 v[16:17], v[16:17], v[132:133] op_sel_hi:[1,0]
	v_pk_mul_f32 v[14:15], v[14:15], v[112:113] op_sel_hi:[1,0]
	v_mad_i64_i32 v[24:25], s[4:5], v166, s76, v[120:121]
	v_lshl_add_u64 v[32:33], v[24:25], 0, v[122:123]
	v_pk_mul_f32 v[26:27], v[38:39], v[132:133] op_sel_hi:[1,0]
	v_pk_mul_f32 v[24:25], v[36:37], v[132:133] op_sel_hi:[1,0]
	v_pk_mul_f32 v[12:13], v[12:13], v[112:113] op_sel_hi:[1,0]
	v_cvt_pk_bf16_f32 v24, v24, v25
	v_cvt_pk_bf16_f32 v25, v26, v27
	v_cvt_pk_bf16_f32 v26, v28, v29
	v_cvt_pk_bf16_f32 v27, v30, v31
	global_store_dwordx4 v[32:33], v[24:27], off
	v_pk_mul_f32 v[6:7], v[6:7], v[112:113] op_sel_hi:[1,0]
	v_pk_mul_f32 v[4:5], v[4:5], v[112:113] op_sel_hi:[1,0]
	v_pk_mul_f32 v[24:25], v[10:11], v[132:133] op_sel_hi:[1,0]
	v_pk_mul_f32 v[10:11], v[8:9], v[132:133] op_sel_hi:[1,0]
	v_cvt_pk_bf16_f32 v8, v16, v17
	v_cvt_pk_bf16_f32 v9, v18, v19
	v_cvt_pk_bf16_f32 v10, v10, v11
	v_cvt_pk_bf16_f32 v11, v24, v25
	global_store_dwordx4 v[32:33], v[8:11], off offset:256
	s_and_b64 vcc, exec, s[0:1]
	s_mov_b64 s[8:9], s[36:37]
	v_mad_i64_i32 v[8:9], s[4:5], v162, s76, v[120:121]
	v_lshl_add_u64 v[16:17], v[8:9], 0, v[122:123]
	v_pk_mul_f32 v[10:11], v[22:23], v[112:113] op_sel_hi:[1,0]
	v_pk_mul_f32 v[8:9], v[20:21], v[112:113] op_sel_hi:[1,0]
	s_mov_b32 s5, s28
	v_cvt_pk_bf16_f32 v8, v8, v9
	v_cvt_pk_bf16_f32 v9, v10, v11
	v_cvt_pk_bf16_f32 v10, v12, v13
	v_cvt_pk_bf16_f32 v11, v14, v15
	global_store_dwordx4 v[16:17], v[8:11], off
	s_mov_b32 s4, s30
	s_mov_b64 s[6:7], s[34:35]
	v_pk_mul_f32 v[8:9], v[2:3], v[112:113] op_sel_hi:[1,0]
	v_pk_mul_f32 v[2:3], v[0:1], v[112:113] op_sel_hi:[1,0]
	v_cvt_pk_bf16_f32 v0, v4, v5
	v_cvt_pk_bf16_f32 v1, v6, v7
	v_cvt_pk_bf16_f32 v2, v2, v3
	v_cvt_pk_bf16_f32 v3, v8, v9
	global_store_dwordx4 v[16:17], v[0:3], off offset:256
	s_cbranch_vccz .LBB0_343
	s_waitcnt vmcnt(0)
	s_cmpk_gt_u32 s27, 0xff
	s_cbranch_scc1 .LBB0_350
	s_barrier

; #define PG8_STAGE(bufoff, gbase, voff) do { _Pragma("unroll") for (int _i = 0; _i < 2; ++_i) \
;     __builtin_amdgcn_global_load_lds((const unsigned*)((const char*)(gbase) + (voff)[_i]), (LAS unsigned*)(lds + (bufoff) + ldsw + _i * 8192), 16, 0, 0); } while (0)
; #define PG8_LDA(dst, b, h) do { _Pragma("unroll") for (int m = 0; m < 4; ++m) _Pragma("unroll") for (int k = 0; k < 2; ++k) dst[m][k] = *(const LAS bf16x8*)(lds + PG8_SA(b, h) + aoff + m * 2048 + k * 1024); } while (0)
; #define PG8_LDB(dst, b, h) do { _Pragma("unroll") for (int n = 0; n < 2; ++n) _Pragma("unroll") for (int k = 0; k < 2; ++k) dst[n][k] = *(const LAS bf16x8*)(lds + PG8_SB(b, h) + boff + n * 2048 + k * 1024); } while (0)
; #define PG8_MMA(ai, bj, At, Bt) do { __builtin_amdgcn_s_setprio(1); _Pragma("unroll") for (int m = 0; m < 4; ++m) _Pragma("unroll") for (int n = 0; n < 2; ++n) _Pragma("unroll") for (int k = 0; k < 2; ++k) \
;     acc[ai][bj][m][n] = __builtin_amdgcn_mfma_f32_16x16x32_bf16(Bt[n][k], At[m][k], acc[ai][bj][m][n], 0, 0, 0); __builtin_amdgcn_s_setprio(0); } while (0)
; #define PG8_WAIT_V(n) asm volatile("s_waitcnt vmcnt(" #n ")" ::: "memory")
; #define PG8_WAIT_L(n) asm volatile("s_waitcnt lgkmcnt(" #n ")" ::: "memory")
; #define PG8_BAR __builtin_amdgcn_s_barrier()
; #define PG8_SCHED __builtin_amdgcn_sched_barrier(0)
; template <class Epi, class Sched = StaticOrder>
; DI void gemm_phase(LAS unsigned char* lds, const Gemm g, const Sched& S, const Epi& E) {
;     ...
;       const char* a1 = cA + (size_t)(t + 1) * kstep;
;       const char* a2 = last ? nA : cA + (size_t)(t + 2) * kstep; const char* b2 = last ? nB : cB + (size_t)(t + 2) * kstep;
;       const char* a3 = a2 + kstep; const char* b3 = b2 + kstep;
;       PG8_LDB(B0, 0, 0); PG8_SCHED; PG8_LDA(At, 0, 0); PG8_STAGE(PG8_SA(1, 1), a1 + hstep, voffA);
;       PG8_WAIT_L(8); PG8_BAR; PG8_WAIT_L(0); PG8_MMA(0, 0, At, B0); PG8_BAR; PG8_SCHED;
;       PG8_LDB(B1, 0, 1); PG8_STAGE(PG8_SB(0, 0), b2, voffB);
;       PG8_BAR; PG8_WAIT_L(0); PG8_MMA(0, 1, At, B1); PG8_BAR;
;       PG8_LDA(At, 0, 1); PG8_STAGE(PG8_SA(0, 0), a2, voffA);
;       PG8_BAR; PG8_WAIT_L(0); PG8_MMA(1, 0, At, B0); PG8_BAR; PG8_SCHED;
;       PG8_STAGE(PG8_SB(0, 1), b2 + hstep, voffB);
;       PG8_WAIT_V(6); PG8_BAR; PG8_MMA(1, 1, At, B1); PG8_BAR;
.LBB0_728:
	ds_read_b128 v[128:131], v207
	ds_read_b128 v[132:135], v207 offset:1024
	ds_read_b128 v[136:139], v207 offset:2048
	ds_read_b128 v[140:143], v207 offset:3072
	s_add_u32 s24, s22, 0xfff80080
	s_addc_u32 s25, s23, -1
	s_cmp_eq_u32 s53, 28
	s_cselect_b32 s27, s17, s25
	s_cselect_b32 s26, s43, s24
	s_cselect_b32 s25, s15, s52
	s_cselect_b32 s24, s44, s45
	s_add_i32 m0, s37, 0xc000
	ds_read_b128 v[144:147], v208
	ds_read_b128 v[148:151], v208 offset:1024
	ds_read_b128 v[152:155], v208 offset:2048
	ds_read_b128 v[156:159], v208 offset:3072
	ds_read_b128 v[160:163], v208 offset:4096
	ds_read_b128 v[164:167], v208 offset:5120
	ds_read_b128 v[168:171], v208 offset:6144
	ds_read_b128 v[172:175], v208 offset:7168
	global_load_lds_dwordx4 v184, s[22:23]
	s_add_i32 m0, s37, 0xe000
	s_nop 0
	global_load_lds_dwordx4 v186, s[22:23]
	ds_read_b128 v[192:195], v209
	ds_read_b128 v[196:199], v209 offset:1024
	ds_read_b128 v[200:203], v209 offset:2048
	ds_read_b128 v[212:215], v209 offset:3072
	s_waitcnt vmcnt(8)
	s_waitcnt lgkmcnt(4)
	s_setprio 1
	s_barrier
	v_mfma_f32_16x16x32_bf16 v[124:127], v[128:131], v[144:147], v[124:127]
	v_mfma_f32_16x16x32_bf16 v[120:123], v[136:139], v[144:147], v[120:123]
	v_mfma_f32_16x16x32_bf16 v[108:111], v[128:131], v[152:155], v[108:111]
	v_mfma_f32_16x16x32_bf16 v[104:107], v[136:139], v[152:155], v[104:107]
	v_mfma_f32_16x16x32_bf16 v[92:95], v[128:131], v[160:163], v[92:95]
	v_mfma_f32_16x16x32_bf16 v[88:91], v[136:139], v[160:163], v[88:91]
	v_mfma_f32_16x16x32_bf16 v[76:79], v[128:131], v[168:171], v[76:79]
	v_mfma_f32_16x16x32_bf16 v[72:75], v[136:139], v[168:171], v[72:75]
	v_mfma_f32_16x16x32_bf16 v[124:127], v[132:135], v[148:151], v[124:127]
	v_mfma_f32_16x16x32_bf16 v[120:123], v[140:143], v[148:151], v[120:123]
	v_mfma_f32_16x16x32_bf16 v[108:111], v[132:135], v[156:159], v[108:111]
	v_mfma_f32_16x16x32_bf16 v[104:107], v[140:143], v[156:159], v[104:107]
	v_mfma_f32_16x16x32_bf16 v[92:95], v[132:135], v[164:167], v[92:95]
	v_mfma_f32_16x16x32_bf16 v[88:91], v[140:143], v[164:167], v[88:91]
	v_mfma_f32_16x16x32_bf16 v[76:79], v[132:135], v[172:175], v[76:79]
	v_mfma_f32_16x16x32_bf16 v[72:75], v[140:143], v[172:175], v[72:75]
	s_waitcnt lgkmcnt(0)
	v_mfma_f32_16x16x32_bf16 v[116:119], v[192:195], v[144:147], v[116:119]
	v_mfma_f32_16x16x32_bf16 v[112:115], v[200:203], v[144:147], v[112:115]
	v_mfma_f32_16x16x32_bf16 v[100:103], v[192:195], v[152:155], v[100:103]
	v_mfma_f32_16x16x32_bf16 v[96:99], v[200:203], v[152:155], v[96:99]
	v_mfma_f32_16x16x32_bf16 v[84:87], v[192:195], v[160:163], v[84:87]
	v_mfma_f32_16x16x32_bf16 v[80:83], v[200:203], v[160:163], v[80:83]
	v_mfma_f32_16x16x32_bf16 v[68:71], v[192:195], v[168:171], v[68:71]
	v_mfma_f32_16x16x32_bf16 v[64:67], v[200:203], v[168:171], v[64:67]
	v_mfma_f32_16x16x32_bf16 v[116:119], v[196:199], v[148:151], v[116:119]
	v_mfma_f32_16x16x32_bf16 v[112:115], v[212:215], v[148:151], v[112:115]
	v_mfma_f32_16x16x32_bf16 v[100:103], v[196:199], v[156:159], v[100:103]
	v_mfma_f32_16x16x32_bf16 v[96:99], v[212:215], v[156:159], v[96:99]
	v_mfma_f32_16x16x32_bf16 v[84:87], v[196:199], v[164:167], v[84:87]
	v_mfma_f32_16x16x32_bf16 v[80:83], v[212:215], v[164:167], v[80:83]
	v_mfma_f32_16x16x32_bf16 v[68:71], v[196:199], v[172:175], v[68:71]
	v_mfma_f32_16x16x32_bf16 v[64:67], v[212:215], v[172:175], v[64:67]
	s_barrier
	s_setprio 0
	s_add_i32 s54, s50, s35
	s_add_u32 s98, s24, 0x80
	s_addc_u32 s99, s25, 0
	s_add_u32 s100, s26, 0x80
	s_addc_u32 s101, s27, 0
	s_mov_b32 m0, s54
	s_nop 0
	global_load_lds_dwordx4 v180, s[24:25]
	s_add_i32 m0, s54, 0x2000
	s_nop 0
	global_load_lds_dwordx4 v176, s[24:25]
	s_mov_b32 m0, s37
	ds_read_b128 v[144:147], v208 offset:16384
	ds_read_b128 v[148:151], v208 offset:17408
	ds_read_b128 v[152:155], v208 offset:18432
	ds_read_b128 v[156:159], v208 offset:19456
	ds_read_b128 v[160:163], v208 offset:20480
	ds_read_b128 v[164:167], v208 offset:21504
	ds_read_b128 v[168:171], v208 offset:22528
	ds_read_b128 v[172:175], v208 offset:23552
	global_load_lds_dwordx4 v182, s[26:27]
	s_mov_b32 m0, s38
	s_nop 0
	global_load_lds_dwordx4 v178, s[26:27]
	s_add_u32 s54, s24, 0x80000
	s_addc_u32 s55, s25, 0
	s_add_i32 s57, s51, s35
	s_waitcnt vmcnt(6)
	s_waitcnt lgkmcnt(0)
	s_setprio 1
	s_barrier
	v_mfma_f32_16x16x32_bf16 v[60:63], v[128:131], v[144:147], v[60:63]
	s_mov_b32 m0, s57
	v_mfma_f32_16x16x32_bf16 v[56:59], v[136:139], v[144:147], v[56:59]
	global_load_lds_dwordx4 v180, s[54:55]
	v_mfma_f32_16x16x32_bf16 v[44:47], v[128:131], v[152:155], v[44:47]
	s_bitset1_b32 m0, 13
	v_mfma_f32_16x16x32_bf16 v[40:43], v[136:139], v[152:155], v[40:43]
	global_load_lds_dwordx4 v176, s[54:55]
	v_mfma_f32_16x16x32_bf16 v[28:31], v[128:131], v[160:163], v[28:31]
	v_mfma_f32_16x16x32_bf16 v[24:27], v[136:139], v[160:163], v[24:27]
	v_mfma_f32_16x16x32_bf16 v[12:15], v[128:131], v[168:171], v[12:15]
	v_mfma_f32_16x16x32_bf16 v[8:11], v[136:139], v[168:171], v[8:11]
	v_mfma_f32_16x16x32_bf16 v[60:63], v[132:135], v[148:151], v[60:63]
	v_mfma_f32_16x16x32_bf16 v[56:59], v[140:143], v[148:151], v[56:59]
	v_mfma_f32_16x16x32_bf16 v[44:47], v[132:135], v[156:159], v[44:47]
	v_mfma_f32_16x16x32_bf16 v[40:43], v[140:143], v[156:159], v[40:43]
	v_mfma_f32_16x16x32_bf16 v[28:31], v[132:135], v[164:167], v[28:31]
	v_mfma_f32_16x16x32_bf16 v[24:27], v[140:143], v[164:167], v[24:27]
	v_mfma_f32_16x16x32_bf16 v[12:15], v[132:135], v[172:175], v[12:15]
	v_mfma_f32_16x16x32_bf16 v[8:11], v[140:143], v[172:175], v[8:11]
	v_mfma_f32_16x16x32_bf16 v[52:55], v[192:195], v[144:147], v[52:55]
	v_mfma_f32_16x16x32_bf16 v[48:51], v[200:203], v[144:147], v[48:51]
	v_mfma_f32_16x16x32_bf16 v[36:39], v[192:195], v[152:155], v[36:39]
	v_mfma_f32_16x16x32_bf16 v[32:35], v[200:203], v[152:155], v[32:35]
	v_mfma_f32_16x16x32_bf16 v[20:23], v[192:195], v[160:163], v[20:23]
	v_mfma_f32_16x16x32_bf16 v[16:19], v[200:203], v[160:163], v[16:19]
	v_mfma_f32_16x16x32_bf16 v[4:7], v[192:195], v[168:171], v[4:7]
	v_mfma_f32_16x16x32_bf16 v[0:3], v[200:203], v[168:171], v[0:3]
	v_mfma_f32_16x16x32_bf16 v[52:55], v[196:199], v[148:151], v[52:55]
	v_mfma_f32_16x16x32_bf16 v[48:51], v[212:215], v[148:151], v[48:51]
	v_mfma_f32_16x16x32_bf16 v[36:39], v[196:199], v[156:159], v[36:39]
	v_mfma_f32_16x16x32_bf16 v[32:35], v[212:215], v[156:159], v[32:35]
	v_mfma_f32_16x16x32_bf16 v[20:23], v[196:199], v[164:167], v[20:23]
	v_mfma_f32_16x16x32_bf16 v[16:19], v[212:215], v[164:167], v[16:19]
	v_mfma_f32_16x16x32_bf16 v[4:7], v[196:199], v[172:175], v[4:7]
	v_mfma_f32_16x16x32_bf16 v[0:3], v[212:215], v[172:175], v[0:3]
	s_barrier
; #define PG8_STAGE(bufoff, gbase, voff) do { _Pragma("unroll") for (int _i = 0; _i < 2; ++_i) \
;     __builtin_amdgcn_global_load_lds((const unsigned*)((const char*)(gbase) + (voff)[_i]), (LAS unsigned*)(lds + (bufoff) + ldsw + _i * 8192), 16, 0, 0); } while (0)
; #define PG8_LDA(dst, b, h) do { _Pragma("unroll") for (int m = 0; m < 4; ++m) _Pragma("unroll") for (int k = 0; k < 2; ++k) dst[m][k] = *(const LAS bf16x8*)(lds + PG8_SA(b, h) + aoff + m * 2048 + k * 1024); } while (0)
; #define PG8_LDB(dst, b, h) do { _Pragma("unroll") for (int n = 0; n < 2; ++n) _Pragma("unroll") for (int k = 0; k < 2; ++k) dst[n][k] = *(const LAS bf16x8*)(lds + PG8_SB(b, h) + boff + n * 2048 + k * 1024); } while (0)
; #define PG8_MMA(ai, bj, At, Bt) do { __builtin_amdgcn_s_setprio(1); _Pragma("unroll") for (int m = 0; m < 4; ++m) _Pragma("unroll") for (int n = 0; n < 2; ++n) _Pragma("unroll") for (int k = 0; k < 2; ++k) \
;     acc[ai][bj][m][n] = __builtin_amdgcn_mfma_f32_16x16x32_bf16(Bt[n][k], At[m][k], acc[ai][bj][m][n], 0, 0, 0); __builtin_amdgcn_s_setprio(0); } while (0)
; #define PG8_WAIT_V(n) asm volatile("s_waitcnt vmcnt(" #n ")" ::: "memory")
; #define PG8_WAIT_L(n) asm volatile("s_waitcnt lgkmcnt(" #n ")" ::: "memory")
; #define PG8_BAR __builtin_amdgcn_s_barrier()
; #define PG8_SCHED __builtin_amdgcn_sched_barrier(0)
; template <class Epi, class Sched = StaticOrder>
; DI void gemm_phase(LAS unsigned char* lds, const Gemm g, const Sched& S, const Epi& E) {
;     ...
;       PG8_LDB(B0, 1, 0); PG8_SCHED; PG8_LDA(At, 1, 0); PG8_STAGE(PG8_SA(0, 1), a2 + hstep, voffA);
;       PG8_WAIT_L(8); PG8_BAR; PG8_WAIT_L(0); PG8_MMA(0, 0, At, B0); PG8_BAR; PG8_SCHED;
;       PG8_LDB(B1, 1, 1); PG8_STAGE(PG8_SB(1, 0), b3, voffB);
;       PG8_BAR; PG8_WAIT_L(0); PG8_MMA(0, 1, At, B1); PG8_BAR;
;       PG8_LDA(At, 1, 1); PG8_STAGE(PG8_SA(1, 0), a3, voffA);
;       PG8_BAR; PG8_WAIT_L(0); PG8_MMA(1, 0, At, B0); PG8_BAR; PG8_SCHED;
;       PG8_STAGE(PG8_SB(1, 1), b3 + hstep, voffB);
;       PG8_WAIT_V(6); PG8_BAR; PG8_MMA(1, 1, At, B1); PG8_BAR;
	s_setprio 0
	s_add_i32 s54, 0, 0x18000
	v_add_u32_e32 v140, s54, v205
	ds_read_b128 v[128:131], v140
	ds_read_b128 v[132:135], v140 offset:1024
	ds_read_b128 v[136:139], v140 offset:2048
	ds_read_b128 v[140:143], v140 offset:3072
	s_add_u32 s26, s26, 0x80000
	s_addc_u32 s27, s27, 0
	s_mov_b32 m0, s39
	ds_read_b128 v[144:147], v208 offset:32768
	ds_read_b128 v[148:151], v208 offset:33792
	ds_read_b128 v[152:155], v208 offset:34816
	ds_read_b128 v[156:159], v208 offset:35840
	ds_read_b128 v[160:163], v208 offset:36864
	ds_read_b128 v[164:167], v208 offset:37888
	ds_read_b128 v[168:171], v208 offset:38912
	ds_read_b128 v[172:175], v208 offset:39936
	global_load_lds_dwordx4 v182, s[26:27]
	s_mov_b32 m0, s40
	s_nop 0
	global_load_lds_dwordx4 v178, s[26:27]
	s_add_i32 s26, 0, 0x1c000
	v_add_u32_e32 v212, s26, v205
	ds_read_b128 v[192:195], v212
	ds_read_b128 v[196:199], v212 offset:1024
	ds_read_b128 v[200:203], v212 offset:2048
	ds_read_b128 v[212:215], v212 offset:3072
	s_waitcnt vmcnt(8)
	s_waitcnt lgkmcnt(4)
	s_setprio 1
	s_barrier
	v_mfma_f32_16x16x32_bf16 v[124:127], v[128:131], v[144:147], v[124:127]
	v_mfma_f32_16x16x32_bf16 v[120:123], v[136:139], v[144:147], v[120:123]
	v_mfma_f32_16x16x32_bf16 v[108:111], v[128:131], v[152:155], v[108:111]
	v_mfma_f32_16x16x32_bf16 v[104:107], v[136:139], v[152:155], v[104:107]
	v_mfma_f32_16x16x32_bf16 v[92:95], v[128:131], v[160:163], v[92:95]
	v_mfma_f32_16x16x32_bf16 v[88:91], v[136:139], v[160:163], v[88:91]
	v_mfma_f32_16x16x32_bf16 v[76:79], v[128:131], v[168:171], v[76:79]
	v_mfma_f32_16x16x32_bf16 v[72:75], v[136:139], v[168:171], v[72:75]
	v_mfma_f32_16x16x32_bf16 v[124:127], v[132:135], v[148:151], v[124:127]
	v_mfma_f32_16x16x32_bf16 v[120:123], v[140:143], v[148:151], v[120:123]
	v_mfma_f32_16x16x32_bf16 v[108:111], v[132:135], v[156:159], v[108:111]
	v_mfma_f32_16x16x32_bf16 v[104:107], v[140:143], v[156:159], v[104:107]
	v_mfma_f32_16x16x32_bf16 v[92:95], v[132:135], v[164:167], v[92:95]
	v_mfma_f32_16x16x32_bf16 v[88:91], v[140:143], v[164:167], v[88:91]
	v_mfma_f32_16x16x32_bf16 v[76:79], v[132:135], v[172:175], v[76:79]
	v_mfma_f32_16x16x32_bf16 v[72:75], v[140:143], v[172:175], v[72:75]
	s_waitcnt lgkmcnt(0)
	v_mfma_f32_16x16x32_bf16 v[116:119], v[192:195], v[144:147], v[116:119]
	v_mfma_f32_16x16x32_bf16 v[112:115], v[200:203], v[144:147], v[112:115]
	v_mfma_f32_16x16x32_bf16 v[100:103], v[192:195], v[152:155], v[100:103]
	v_mfma_f32_16x16x32_bf16 v[96:99], v[200:203], v[152:155], v[96:99]
	v_mfma_f32_16x16x32_bf16 v[84:87], v[192:195], v[160:163], v[84:87]
	v_mfma_f32_16x16x32_bf16 v[80:83], v[200:203], v[160:163], v[80:83]
	v_mfma_f32_16x16x32_bf16 v[68:71], v[192:195], v[168:171], v[68:71]
	v_mfma_f32_16x16x32_bf16 v[64:67], v[200:203], v[168:171], v[64:67]
	v_mfma_f32_16x16x32_bf16 v[116:119], v[196:199], v[148:151], v[116:119]
	v_mfma_f32_16x16x32_bf16 v[112:115], v[212:215], v[148:151], v[112:115]
	v_mfma_f32_16x16x32_bf16 v[100:103], v[196:199], v[156:159], v[100:103]
	v_mfma_f32_16x16x32_bf16 v[96:99], v[212:215], v[156:159], v[96:99]
	v_mfma_f32_16x16x32_bf16 v[84:87], v[196:199], v[164:167], v[84:87]
	v_mfma_f32_16x16x32_bf16 v[80:83], v[212:215], v[164:167], v[80:83]
	v_mfma_f32_16x16x32_bf16 v[68:71], v[196:199], v[172:175], v[68:71]
	v_mfma_f32_16x16x32_bf16 v[64:67], v[212:215], v[172:175], v[64:67]
	s_barrier
	s_setprio 0
	s_add_i32 s27, s54, s35
	s_mov_b32 m0, s27
	s_nop 0
	global_load_lds_dwordx4 v180, s[98:99]
	s_add_i32 m0, s27, 0x2000
	s_nop 0
	global_load_lds_dwordx4 v176, s[98:99]
	s_mov_b32 m0, s46
	ds_read_b128 v[144:147], v208 offset:49152
	ds_read_b128 v[148:151], v208 offset:50176
	ds_read_b128 v[152:155], v208 offset:51200
	ds_read_b128 v[156:159], v208 offset:52224
	ds_read_b128 v[160:163], v208 offset:53248
	ds_read_b128 v[164:167], v208 offset:54272
	ds_read_b128 v[168:171], v208 offset:55296
	ds_read_b128 v[172:175], v208 offset:56320
	global_load_lds_dwordx4 v182, s[100:101]
	s_mov_b32 m0, s47
	s_nop 0
	global_load_lds_dwordx4 v178, s[100:101]
	s_add_u32 s24, s24, 0x80080
	s_addc_u32 s25, s25, 0
	s_add_i32 s26, s26, s35
	s_add_i32 s53, s53, 2
	s_add_u32 s22, s22, 0x100
	s_addc_u32 s23, s23, 0
	s_add_u32 s45, s45, 0x100
	s_addc_u32 s52, s52, 0
	s_cmp_gt_u32 s53, 29
	s_waitcnt vmcnt(6)
	s_waitcnt lgkmcnt(0)
	s_setprio 1
	s_barrier
	v_mfma_f32_16x16x32_bf16 v[60:63], v[128:131], v[144:147], v[60:63]
	s_mov_b32 m0, s26
	v_mfma_f32_16x16x32_bf16 v[56:59], v[136:139], v[144:147], v[56:59]
	global_load_lds_dwordx4 v180, s[24:25]
	v_mfma_f32_16x16x32_bf16 v[44:47], v[128:131], v[152:155], v[44:47]
	s_bitset1_b32 m0, 13
	v_mfma_f32_16x16x32_bf16 v[40:43], v[136:139], v[152:155], v[40:43]
	global_load_lds_dwordx4 v176, s[24:25]
	v_mfma_f32_16x16x32_bf16 v[28:31], v[128:131], v[160:163], v[28:31]
	v_mfma_f32_16x16x32_bf16 v[24:27], v[136:139], v[160:163], v[24:27]
	v_mfma_f32_16x16x32_bf16 v[12:15], v[128:131], v[168:171], v[12:15]
	v_mfma_f32_16x16x32_bf16 v[8:11], v[136:139], v[168:171], v[8:11]
	v_mfma_f32_16x16x32_bf16 v[60:63], v[132:135], v[148:151], v[60:63]
	v_mfma_f32_16x16x32_bf16 v[56:59], v[140:143], v[148:151], v[56:59]
	v_mfma_f32_16x16x32_bf16 v[44:47], v[132:135], v[156:159], v[44:47]
	v_mfma_f32_16x16x32_bf16 v[40:43], v[140:143], v[156:159], v[40:43]
	v_mfma_f32_16x16x32_bf16 v[28:31], v[132:135], v[164:167], v[28:31]
	v_mfma_f32_16x16x32_bf16 v[24:27], v[140:143], v[164:167], v[24:27]
	v_mfma_f32_16x16x32_bf16 v[12:15], v[132:135], v[172:175], v[12:15]
	v_mfma_f32_16x16x32_bf16 v[8:11], v[140:143], v[172:175], v[8:11]
	v_mfma_f32_16x16x32_bf16 v[52:55], v[192:195], v[144:147], v[52:55]
	v_mfma_f32_16x16x32_bf16 v[48:51], v[200:203], v[144:147], v[48:51]
	v_mfma_f32_16x16x32_bf16 v[36:39], v[192:195], v[152:155], v[36:39]
	v_mfma_f32_16x16x32_bf16 v[32:35], v[200:203], v[152:155], v[32:35]
	v_mfma_f32_16x16x32_bf16 v[20:23], v[192:195], v[160:163], v[20:23]
	v_mfma_f32_16x16x32_bf16 v[16:19], v[200:203], v[160:163], v[16:19]
	v_mfma_f32_16x16x32_bf16 v[4:7], v[192:195], v[168:171], v[4:7]
	v_mfma_f32_16x16x32_bf16 v[0:3], v[200:203], v[168:171], v[0:3]
	v_mfma_f32_16x16x32_bf16 v[52:55], v[196:199], v[148:151], v[52:55]
	v_mfma_f32_16x16x32_bf16 v[48:51], v[212:215], v[148:151], v[48:51]
	v_mfma_f32_16x16x32_bf16 v[36:39], v[196:199], v[156:159], v[36:39]
	v_mfma_f32_16x16x32_bf16 v[32:35], v[212:215], v[156:159], v[32:35]
	v_mfma_f32_16x16x32_bf16 v[20:23], v[196:199], v[164:167], v[20:23]
	v_mfma_f32_16x16x32_bf16 v[16:19], v[212:215], v[164:167], v[16:19]
	v_mfma_f32_16x16x32_bf16 v[4:7], v[196:199], v[172:175], v[4:7]
	v_mfma_f32_16x16x32_bf16 v[0:3], v[212:215], v[172:175], v[0:3]
	s_barrier
; DI unsigned pack2(float lo, float hi) { f32x2 v = {lo, hi}; bf16v2 r = __builtin_convertvector(v, bf16v2); return __builtin_bit_cast(unsigned, r); }
;   DI void operator()(const f32x4 (&acc)[2][2][4][2], const Unit& u, int wr, int wc, int fr, int fq) const {
;     const int row0 = u.pm * BM + wr * 64 + fr, col0 = u.pn * BM + wc * 32 + 8 * fq;
; #pragma unroll
;     for (int ai = 0; ai < 2; ++ai) {
;       f32x4 bv[4][2][2];
; #pragma unroll
;       for (int m = 0; m < 4; ++m)
; #pragma unroll
;         for (int bj = 0; bj < 2; ++bj) {
;           const float* bp = base + (size_t)(row0 + ai * HALF + m * 16) * 2048 + col0 + bj * HALF;
;           bv[m][bj][0] = *(const f32x4*)bp; bv[m][bj][1] = *(const f32x4*)(bp + 4);
;         }
; #pragma unroll
;       for (int m = 0; m < 4; ++m) {
;         const int row = row0 + ai * HALF + m * 16;
;         const size_t off = (size_t)row * 2048 + col0;
;         float ss = 0.f;
; #pragma unroll
;         for (int bj = 0; bj < 2; ++bj) {
;           const f32x4 v0 = acc[ai][bj][m][0] + bv[m][bj][0], v1 = acc[ai][bj][m][1] + bv[m][bj][1];
;           *(f32x4*)(C + off + bj * HALF) = v0; *(f32x4*)(C + off + bj * HALF + 4) = v1;
;           if (xb) {
;             u32x4 w; w.x = pack2(v0[0], v0[1]); w.y = pack2(v0[2], v0[3]); w.z = pack2(v1[0], v1[1]); w.w = pack2(v1[2], v1[3]);
;             *(u32x4*)(xb + off + bj * HALF) = w;
;             ss += v0[0] * v0[0] + v0[1] * v0[1] + v0[2] * v0[2] + v0[3] * v0[3] + v1[0] * v1[0] + v1[1] * v1[1] + v1[2] * v1[2] + v1[3] * v1[3];
;           }
;         }
;         if (xb) {
;           ss += __shfl_xor(ss, 16); ss += __shfl_xor(ss, 32);
;           if (fq == 0) ssq[(size_t)row * 32 + u.pn * 4 + wc] = ss;
;         }
	s_setprio 0
	s_cbranch_scc0 .LBB0_728
	v_lshl_add_u32 v196, s12, 8, v204
	v_lshl_or_b32 v192, s42, 8, v206
	v_ashrrev_i32_e32 v193, 31, v192
	v_ashrrev_i32_e32 v197, 31, v196
	v_lshl_add_u64 v[194:195], v[192:193], 2, s[60:61]
	v_lshlrev_b64 v[128:129], 13, v[196:197]
	v_lshl_add_u64 v[128:129], v[194:195], 0, v[128:129]
	global_load_dwordx4 v[214:217], v[128:129], off
	global_load_dwordx4 v[218:221], v[128:129], off offset:16
	global_load_dwordx4 v[222:225], v[128:129], off offset:512
	global_load_dwordx4 v[226:229], v[128:129], off offset:528
	v_or_b32_e32 v202, 16, v196
	v_or_b32_e32 v200, 32, v196
	v_or_b32_e32 v198, 48, v196
	v_ashrrev_i32_e32 v203, 31, v202
	v_ashrrev_i32_e32 v201, 31, v200
	v_ashrrev_i32_e32 v199, 31, v198
	v_lshlrev_b64 v[128:129], 13, v[202:203]
	v_lshlrev_b64 v[130:131], 13, v[200:201]
	v_lshlrev_b64 v[132:133], 13, v[198:199]
	v_lshl_add_u64 v[128:129], v[194:195], 0, v[128:129]
	v_lshl_add_u64 v[130:131], v[194:195], 0, v[130:131]
	v_lshl_add_u64 v[132:133], v[194:195], 0, v[132:133]
	global_load_dwordx4 v[168:171], v[128:129], off offset:16
	global_load_dwordx4 v[172:175], v[128:129], off
	global_load_dwordx4 v[160:163], v[128:129], off offset:528
	global_load_dwordx4 v[164:167], v[128:129], off offset:512
	global_load_dwordx4 v[152:155], v[130:131], off offset:16
	global_load_dwordx4 v[156:159], v[130:131], off
	global_load_dwordx4 v[144:147], v[130:131], off offset:528
	global_load_dwordx4 v[148:151], v[130:131], off offset:512
	global_load_dwordx4 v[136:139], v[132:133], off offset:16
	global_load_dwordx4 v[140:143], v[132:133], off
	s_nop 0
	global_load_dwordx4 v[128:131], v[132:133], off offset:528
	s_nop 0
	global_load_dwordx4 v[132:135], v[132:133], off offset:512
	v_and_b32_e32 v212, 64, v211
	v_xor_b32_e32 v230, 16, v211
	v_add_u32_e32 v232, 64, v212
	v_xor_b32_e32 v231, 32, v211
	v_cmp_lt_i32_e32 vcc, v230, v232
	v_lshlrev_b64 v[212:213], 11, v[196:197]
	v_readlane_b32 s64, v243, 3
	v_cndmask_b32_e32 v233, v211, v230, vcc
	v_cmp_lt_i32_e32 vcc, v231, v232
	v_readlane_b32 s78, v243, 17
	v_readlane_b32 s79, v243, 18
	v_cndmask_b32_e32 v234, v211, v231, vcc
	v_lshl_add_u64 v[230:231], v[212:213], 0, v[192:193]
	v_lshlrev_b32_e32 v212, 2, v233
	v_lshl_add_u64 v[232:233], v[230:231], 2, s[78:79]
	v_lshl_add_u64 v[230:231], v[230:231], 1, s[2:3]
	s_lshl_b32 s22, s42, 2
	s_ashr_i32 s23, s22, 31
	v_readlane_b32 s65, v243, 4
	v_readlane_b32 s66, v243, 5
	v_readlane_b32 s67, v243, 6
	v_readlane_b32 s68, v243, 7
	v_readlane_b32 s69, v243, 8
	v_readlane_b32 s70, v243, 9
	v_readlane_b32 s71, v243, 10
	v_readlane_b32 s72, v243, 11
	v_readlane_b32 s73, v243, 12
	v_readlane_b32 s74, v243, 13
	v_readlane_b32 s75, v243, 14
	v_readlane_b32 s76, v243, 15
	v_readlane_b32 s77, v243, 16
	s_waitcnt vmcnt(0)
	v_pk_add_f32 v[126:127], v[126:127], v[216:217]
	v_pk_add_f32 v[124:125], v[124:125], v[214:215]
	v_pk_add_f32 v[116:117], v[116:117], v[222:223]
	v_pk_add_f32 v[122:123], v[122:123], v[220:221]
	v_pk_add_f32 v[120:121], v[120:121], v[218:219]
	v_pk_add_f32 v[214:215], v[112:113], v[226:227]
	global_store_dwordx4 v[232:233], v[124:127], off
	global_store_dwordx4 v[232:233], v[120:123], off offset:16
	v_cvt_pk_bf16_f32 v112, v124, v125
	v_mul_f32_e32 v125, v125, v125
	v_mul_f32_e32 v213, v117, v117
	v_pk_add_f32 v[118:119], v[118:119], v[224:225]
	v_fmac_f32_e32 v125, v124, v124
	v_fmac_f32_e32 v213, v116, v116
	v_fmac_f32_e32 v125, v126, v126
	v_fmac_f32_e32 v213, v118, v118
	v_fmac_f32_e32 v125, v127, v127
	v_fmac_f32_e32 v213, v119, v119
	v_fmac_f32_e32 v125, v120, v120
	v_fmac_f32_e32 v213, v214, v214
	v_pk_add_f32 v[216:217], v[114:115], v[228:229]
	v_fmac_f32_e32 v125, v121, v121
	v_fmac_f32_e32 v213, v215, v215
	v_fmac_f32_e32 v125, v122, v122
	v_fmac_f32_e32 v213, v216, v216
	v_fmac_f32_e32 v125, v123, v123
	v_fmac_f32_e32 v213, v217, v217
	v_cvt_pk_bf16_f32 v114, v120, v121
	v_add_f32_e32 v120, v125, v213
	ds_bpermute_b32 v121, v212, v120
	v_cvt_pk_bf16_f32 v113, v126, v127
	v_cvt_pk_bf16_f32 v115, v122, v123
	global_store_dwordx4 v[230:231], v[112:115], off
	global_store_dwordx4 v[232:233], v[116:119], off offset:512
	global_store_dwordx4 v[232:233], v[214:217], off offset:528
	v_cvt_pk_bf16_f32 v122, v116, v117
	s_waitcnt lgkmcnt(0)
	v_add_f32_e32 v112, v120, v121
	v_lshlrev_b32_e32 v120, 2, v234
	ds_bpermute_b32 v113, v120, v112
	v_cvt_pk_bf16_f32 v123, v118, v119
	v_cvt_pk_bf16_f32 v124, v214, v215
	v_cvt_pk_bf16_f32 v125, v216, v217
	global_store_dwordx4 v[230:231], v[122:125], off offset:256
	s_and_saveexec_b64 s[24:25], s[0:1]
	s_cbranch_execz .LBB0_731
	s_waitcnt lgkmcnt(0)
	v_add_f32_e32 v114, v112, v113
	v_lshlrev_b64 v[112:113], 7, v[196:197]
	v_lshl_add_u64 v[112:113], s[8:9], 0, v[112:113]
	v_lshl_add_u64 v[112:113], s[22:23], 2, v[112:113]
	s_lshl_b32 s12, s41, 2
	v_lshl_add_u64 v[112:113], v[112:113], 0, s[12:13]
	global_store_dword v[112:113], v114, off

; #define PG8_STAGE(bufoff, gbase, voff) do { _Pragma("unroll") for (int _i = 0; _i < 2; ++_i) \
;     __builtin_amdgcn_global_load_lds((const unsigned*)((const char*)(gbase) + (voff)[_i]), (LAS unsigned*)(lds + (bufoff) + ldsw + _i * 8192), 16, 0, 0); } while (0)
; #define PG8_LDA(dst, b, h) do { _Pragma("unroll") for (int m = 0; m < 4; ++m) _Pragma("unroll") for (int k = 0; k < 2; ++k) dst[m][k] = *(const LAS bf16x8*)(lds + PG8_SA(b, h) + aoff + m * 2048 + k * 1024); } while (0)
; #define PG8_LDB(dst, b, h) do { _Pragma("unroll") for (int n = 0; n < 2; ++n) _Pragma("unroll") for (int k = 0; k < 2; ++k) dst[n][k] = *(const LAS bf16x8*)(lds + PG8_SB(b, h) + boff + n * 2048 + k * 1024); } while (0)
; #define PG8_MMA(ai, bj, At, Bt) do { __builtin_amdgcn_s_setprio(1); _Pragma("unroll") for (int m = 0; m < 4; ++m) _Pragma("unroll") for (int n = 0; n < 2; ++n) _Pragma("unroll") for (int k = 0; k < 2; ++k) \
;     acc[ai][bj][m][n] = __builtin_amdgcn_mfma_f32_16x16x32_bf16(Bt[n][k], At[m][k], acc[ai][bj][m][n], 0, 0, 0); __builtin_amdgcn_s_setprio(0); } while (0)
; #define PG8_WAIT_V(n) asm volatile("s_waitcnt vmcnt(" #n ")" ::: "memory")
; #define PG8_WAIT_L(n) asm volatile("s_waitcnt lgkmcnt(" #n ")" ::: "memory")
; #define PG8_BAR __builtin_amdgcn_s_barrier()
; #define PG8_SCHED __builtin_amdgcn_sched_barrier(0)
; template <class Epi, class Sched = StaticOrder>
; DI void gemm_phase(LAS unsigned char* lds, const Gemm g, const Sched& S, const Epi& E) {
;     ...
;       const char* a1 = cA + (size_t)(t + 1) * kstep;
;       const char* a2 = last ? nA : cA + (size_t)(t + 2) * kstep; const char* b2 = last ? nB : cB + (size_t)(t + 2) * kstep;
;       const char* a3 = a2 + kstep; const char* b3 = b2 + kstep;
;       PG8_LDB(B0, 0, 0); PG8_SCHED; PG8_LDA(At, 0, 0); PG8_STAGE(PG8_SA(1, 1), a1 + hstep, voffA);
;       PG8_WAIT_L(8); PG8_BAR; PG8_WAIT_L(0); PG8_MMA(0, 0, At, B0); PG8_BAR; PG8_SCHED;
;       PG8_LDB(B1, 0, 1); PG8_STAGE(PG8_SB(0, 0), b2, voffB);
;       PG8_BAR; PG8_WAIT_L(0); PG8_MMA(0, 1, At, B1); PG8_BAR;
;       PG8_LDA(At, 0, 1); PG8_STAGE(PG8_SA(0, 0), a2, voffA);
;       PG8_BAR; PG8_WAIT_L(0); PG8_MMA(1, 0, At, B0); PG8_BAR; PG8_SCHED;
;       PG8_STAGE(PG8_SB(0, 1), b2 + hstep, voffB);
;       PG8_WAIT_V(6); PG8_BAR; PG8_MMA(1, 1, At, B1); PG8_BAR;
.LBB0_811:
	ds_read_b128 v[64:67], v201
	ds_read_b128 v[68:71], v201 offset:1024
	ds_read_b128 v[72:75], v201 offset:2048
	ds_read_b128 v[76:79], v201 offset:3072
	s_add_u32 s46, s14, 0xfff80080
	s_addc_u32 s47, s15, -1
	s_cmp_eq_u32 s52, 28
	s_cselect_b32 s49, s37, s47
	s_cselect_b32 s48, s42, s46
	s_cselect_b32 s47, s35, s45
	s_cselect_b32 s46, s43, s44
	s_add_i32 m0, s62, 0xc000
	ds_read_b128 v[80:83], v202
	ds_read_b128 v[84:87], v202 offset:1024
	ds_read_b128 v[92:95], v202 offset:2048
	ds_read_b128 v[96:99], v202 offset:3072
	ds_read_b128 v[180:183], v202 offset:4096
	ds_read_b128 v[184:187], v202 offset:5120
	ds_read_b128 v[188:191], v202 offset:6144
	ds_read_b128 v[192:195], v202 offset:7168
	global_load_lds_dwordx4 v170, s[14:15]
	s_add_i32 m0, s62, 0xe000
	s_nop 0
	global_load_lds_dwordx4 v172, s[14:15]
	ds_read_b128 v[206:209], v203
	ds_read_b128 v[212:215], v203 offset:1024
	ds_read_b128 v[216:219], v203 offset:2048
	ds_read_b128 v[220:223], v203 offset:3072
	s_waitcnt vmcnt(8)
	s_waitcnt lgkmcnt(4)
	s_setprio 1
	s_barrier
	v_mfma_f32_16x16x32_bf16 v[156:159], v[64:67], v[80:83], v[156:159]
	v_mfma_f32_16x16x32_bf16 v[144:147], v[72:75], v[80:83], v[144:147]
	v_mfma_f32_16x16x32_bf16 v[140:143], v[64:67], v[92:95], v[140:143]
	v_mfma_f32_16x16x32_bf16 v[132:135], v[72:75], v[92:95], v[132:135]
	v_mfma_f32_16x16x32_bf16 v[124:127], v[64:67], v[180:183], v[124:127]
	v_mfma_f32_16x16x32_bf16 v[116:119], v[72:75], v[180:183], v[116:119]
	v_mfma_f32_16x16x32_bf16 v[112:115], v[64:67], v[188:191], v[112:115]
	v_mfma_f32_16x16x32_bf16 v[108:111], v[72:75], v[188:191], v[108:111]
	v_mfma_f32_16x16x32_bf16 v[156:159], v[68:71], v[84:87], v[156:159]
	v_mfma_f32_16x16x32_bf16 v[144:147], v[76:79], v[84:87], v[144:147]
	v_mfma_f32_16x16x32_bf16 v[140:143], v[68:71], v[96:99], v[140:143]
	v_mfma_f32_16x16x32_bf16 v[132:135], v[76:79], v[96:99], v[132:135]
	v_mfma_f32_16x16x32_bf16 v[124:127], v[68:71], v[184:187], v[124:127]
	v_mfma_f32_16x16x32_bf16 v[116:119], v[76:79], v[184:187], v[116:119]
	v_mfma_f32_16x16x32_bf16 v[112:115], v[68:71], v[192:195], v[112:115]
	v_mfma_f32_16x16x32_bf16 v[108:111], v[76:79], v[192:195], v[108:111]
	s_waitcnt lgkmcnt(0)
	v_mfma_f32_16x16x32_bf16 v[152:155], v[206:209], v[80:83], v[152:155]
	v_mfma_f32_16x16x32_bf16 v[80:83], v[216:219], v[80:83], v[148:151]
	v_mfma_f32_16x16x32_bf16 v[152:155], v[212:215], v[84:87], v[152:155]
	v_mfma_f32_16x16x32_bf16 v[80:83], v[220:223], v[84:87], v[80:83]
	v_mfma_f32_16x16x32_bf16 v[84:87], v[206:209], v[92:95], v[136:139]
	v_mfma_f32_16x16x32_bf16 v[92:95], v[216:219], v[92:95], v[128:131]
	v_mfma_f32_16x16x32_bf16 v[104:107], v[216:219], v[180:183], v[104:107]
	v_mfma_f32_16x16x32_bf16 v[100:103], v[206:209], v[188:191], v[100:103]
	v_mfma_f32_16x16x32_bf16 v[88:91], v[216:219], v[188:191], v[88:91]
	v_mfma_f32_16x16x32_bf16 v[84:87], v[212:215], v[96:99], v[84:87]
	v_mfma_f32_16x16x32_bf16 v[92:95], v[220:223], v[96:99], v[92:95]
	v_mfma_f32_16x16x32_bf16 v[96:99], v[206:209], v[180:183], v[120:123]
	v_mfma_f32_16x16x32_bf16 v[104:107], v[220:223], v[184:187], v[104:107]
	v_mfma_f32_16x16x32_bf16 v[100:103], v[212:215], v[192:195], v[100:103]
	v_mfma_f32_16x16x32_bf16 v[88:91], v[220:223], v[192:195], v[88:91]
	v_mfma_f32_16x16x32_bf16 v[96:99], v[212:215], v[184:187], v[96:99]
	s_barrier
	s_setprio 0
	s_add_i32 s53, s72, s60
	s_add_u32 s98, s46, 0x80
	s_addc_u32 s99, s47, 0
	s_add_u32 s100, s48, 0x80
	s_addc_u32 s101, s49, 0
	s_mov_b32 m0, s53
	s_nop 0
	global_load_lds_dwordx4 v164, s[46:47]
	s_add_i32 m0, s53, 0x2000
	s_nop 0
	global_load_lds_dwordx4 v160, s[46:47]
	s_mov_b32 m0, s62
	ds_read_b128 v[120:123], v202 offset:16384
	ds_read_b128 v[128:131], v202 offset:17408
	ds_read_b128 v[136:139], v202 offset:18432
	ds_read_b128 v[148:151], v202 offset:19456
	ds_read_b128 v[180:183], v202 offset:20480
	ds_read_b128 v[184:187], v202 offset:21504
	ds_read_b128 v[188:191], v202 offset:22528
	ds_read_b128 v[192:195], v202 offset:23552
	global_load_lds_dwordx4 v166, s[48:49]
	s_mov_b32 m0, s63
	s_nop 0
	global_load_lds_dwordx4 v162, s[48:49]
	s_add_u32 s54, s46, 0x80000
	s_addc_u32 s55, s47, 0
	s_add_i32 s53, s73, s60
	s_waitcnt vmcnt(6)
	s_waitcnt lgkmcnt(0)
	s_setprio 1
	s_barrier
	v_mfma_f32_16x16x32_bf16 v[60:63], v[64:67], v[120:123], v[60:63]
	s_mov_b32 m0, s53
	v_mfma_f32_16x16x32_bf16 v[48:51], v[72:75], v[120:123], v[48:51]
	global_load_lds_dwordx4 v164, s[54:55]
	v_mfma_f32_16x16x32_bf16 v[44:47], v[64:67], v[136:139], v[44:47]
	s_bitset1_b32 m0, 13
	v_mfma_f32_16x16x32_bf16 v[36:39], v[72:75], v[136:139], v[36:39]
	global_load_lds_dwordx4 v160, s[54:55]
	v_mfma_f32_16x16x32_bf16 v[28:31], v[64:67], v[180:183], v[28:31]
	v_mfma_f32_16x16x32_bf16 v[20:23], v[72:75], v[180:183], v[20:23]
	v_mfma_f32_16x16x32_bf16 v[16:19], v[64:67], v[188:191], v[16:19]
	v_mfma_f32_16x16x32_bf16 v[12:15], v[72:75], v[188:191], v[12:15]
	v_mfma_f32_16x16x32_bf16 v[60:63], v[68:71], v[128:131], v[60:63]
	v_mfma_f32_16x16x32_bf16 v[48:51], v[76:79], v[128:131], v[48:51]
	v_mfma_f32_16x16x32_bf16 v[44:47], v[68:71], v[148:151], v[44:47]
	v_mfma_f32_16x16x32_bf16 v[36:39], v[76:79], v[148:151], v[36:39]
	v_mfma_f32_16x16x32_bf16 v[28:31], v[68:71], v[184:187], v[28:31]
	v_mfma_f32_16x16x32_bf16 v[20:23], v[76:79], v[184:187], v[20:23]
	v_mfma_f32_16x16x32_bf16 v[16:19], v[68:71], v[192:195], v[16:19]
	v_mfma_f32_16x16x32_bf16 v[12:15], v[76:79], v[192:195], v[12:15]
	v_mfma_f32_16x16x32_bf16 v[56:59], v[206:209], v[120:123], v[56:59]
	v_mfma_f32_16x16x32_bf16 v[52:55], v[216:219], v[120:123], v[52:55]
	v_mfma_f32_16x16x32_bf16 v[40:43], v[206:209], v[136:139], v[40:43]
	v_mfma_f32_16x16x32_bf16 v[32:35], v[216:219], v[136:139], v[32:35]
	v_mfma_f32_16x16x32_bf16 v[24:27], v[206:209], v[180:183], v[24:27]
	v_mfma_f32_16x16x32_bf16 v[8:11], v[216:219], v[180:183], v[8:11]
	v_mfma_f32_16x16x32_bf16 v[4:7], v[206:209], v[188:191], v[4:7]
	v_mfma_f32_16x16x32_bf16 v[0:3], v[216:219], v[188:191], v[0:3]
	v_mfma_f32_16x16x32_bf16 v[56:59], v[212:215], v[128:131], v[56:59]
	v_mfma_f32_16x16x32_bf16 v[52:55], v[220:223], v[128:131], v[52:55]
	v_mfma_f32_16x16x32_bf16 v[40:43], v[212:215], v[148:151], v[40:43]
	v_mfma_f32_16x16x32_bf16 v[32:35], v[220:223], v[148:151], v[32:35]
	v_mfma_f32_16x16x32_bf16 v[24:27], v[212:215], v[184:187], v[24:27]
	v_mfma_f32_16x16x32_bf16 v[8:11], v[220:223], v[184:187], v[8:11]
	v_mfma_f32_16x16x32_bf16 v[4:7], v[212:215], v[192:195], v[4:7]
	v_mfma_f32_16x16x32_bf16 v[0:3], v[220:223], v[192:195], v[0:3]
	s_barrier
; #define PG8_STAGE(bufoff, gbase, voff) do { _Pragma("unroll") for (int _i = 0; _i < 2; ++_i) \
;     __builtin_amdgcn_global_load_lds((const unsigned*)((const char*)(gbase) + (voff)[_i]), (LAS unsigned*)(lds + (bufoff) + ldsw + _i * 8192), 16, 0, 0); } while (0)
; #define PG8_LDA(dst, b, h) do { _Pragma("unroll") for (int m = 0; m < 4; ++m) _Pragma("unroll") for (int k = 0; k < 2; ++k) dst[m][k] = *(const LAS bf16x8*)(lds + PG8_SA(b, h) + aoff + m * 2048 + k * 1024); } while (0)
; #define PG8_LDB(dst, b, h) do { _Pragma("unroll") for (int n = 0; n < 2; ++n) _Pragma("unroll") for (int k = 0; k < 2; ++k) dst[n][k] = *(const LAS bf16x8*)(lds + PG8_SB(b, h) + boff + n * 2048 + k * 1024); } while (0)
; #define PG8_MMA(ai, bj, At, Bt) do { __builtin_amdgcn_s_setprio(1); _Pragma("unroll") for (int m = 0; m < 4; ++m) _Pragma("unroll") for (int n = 0; n < 2; ++n) _Pragma("unroll") for (int k = 0; k < 2; ++k) \
;     acc[ai][bj][m][n] = __builtin_amdgcn_mfma_f32_16x16x32_bf16(Bt[n][k], At[m][k], acc[ai][bj][m][n], 0, 0, 0); __builtin_amdgcn_s_setprio(0); } while (0)
; #define PG8_WAIT_V(n) asm volatile("s_waitcnt vmcnt(" #n ")" ::: "memory")
; #define PG8_WAIT_L(n) asm volatile("s_waitcnt lgkmcnt(" #n ")" ::: "memory")
; #define PG8_BAR __builtin_amdgcn_s_barrier()
; #define PG8_SCHED __builtin_amdgcn_sched_barrier(0)
; template <class Epi, class Sched = StaticOrder>
; DI void gemm_phase(LAS unsigned char* lds, const Gemm g, const Sched& S, const Epi& E) {
;     ...
;       PG8_LDB(B0, 1, 0); PG8_SCHED; PG8_LDA(At, 1, 0); PG8_STAGE(PG8_SA(0, 1), a2 + hstep, voffA);
;       PG8_WAIT_L(8); PG8_BAR; PG8_WAIT_L(0); PG8_MMA(0, 0, At, B0); PG8_BAR; PG8_SCHED;
;       PG8_LDB(B1, 1, 1); PG8_STAGE(PG8_SB(1, 0), b3, voffB);
;       PG8_BAR; PG8_WAIT_L(0); PG8_MMA(0, 1, At, B1); PG8_BAR;
;       PG8_LDA(At, 1, 1); PG8_STAGE(PG8_SA(1, 0), a3, voffA);
;       PG8_BAR; PG8_WAIT_L(0); PG8_MMA(1, 0, At, B0); PG8_BAR; PG8_SCHED;
;       PG8_STAGE(PG8_SB(1, 1), b3 + hstep, voffB);
;       PG8_WAIT_V(6); PG8_BAR; PG8_MMA(1, 1, At, B1); PG8_BAR;
	s_setprio 0
	s_add_i32 s53, 0, 0x18000
	v_add_u32_e32 v76, s53, v198
	ds_read_b128 v[64:67], v76
	ds_read_b128 v[68:71], v76 offset:1024
	ds_read_b128 v[72:75], v76 offset:2048
	ds_read_b128 v[76:79], v76 offset:3072
	s_add_u32 s48, s48, 0x80000
	s_addc_u32 s49, s49, 0
	s_mov_b32 m0, s64
	ds_read_b128 v[120:123], v202 offset:32768
	ds_read_b128 v[128:131], v202 offset:33792
	ds_read_b128 v[180:183], v202 offset:34816
	ds_read_b128 v[184:187], v202 offset:35840
	ds_read_b128 v[188:191], v202 offset:36864
	ds_read_b128 v[192:195], v202 offset:37888
	ds_read_b128 v[206:209], v202 offset:38912
	ds_read_b128 v[212:215], v202 offset:39936
	global_load_lds_dwordx4 v166, s[48:49]
	s_mov_b32 m0, s65
	s_nop 0
	global_load_lds_dwordx4 v162, s[48:49]
	s_add_i32 s48, 0, 0x1c000
	v_add_u32_e32 v244, s48, v198
	ds_read_b128 v[216:219], v244
	ds_read_b128 v[220:223], v244 offset:1024
	ds_read_b128 v[224:227], v244 offset:2048
	ds_read_b128 v[228:231], v244 offset:3072
	s_waitcnt vmcnt(8)
	s_waitcnt lgkmcnt(4)
	s_setprio 1
	s_barrier
	v_mfma_f32_16x16x32_bf16 v[136:139], v[64:67], v[120:123], v[156:159]
	v_mfma_f32_16x16x32_bf16 v[156:159], v[68:71], v[128:131], v[136:139]
	v_mfma_f32_16x16x32_bf16 v[136:139], v[72:75], v[120:123], v[144:147]
	v_mfma_f32_16x16x32_bf16 v[144:147], v[76:79], v[128:131], v[136:139]
	v_mfma_f32_16x16x32_bf16 v[136:139], v[64:67], v[180:183], v[140:143]
	v_mfma_f32_16x16x32_bf16 v[132:135], v[72:75], v[180:183], v[132:135]
	v_mfma_f32_16x16x32_bf16 v[124:127], v[64:67], v[188:191], v[124:127]
	v_mfma_f32_16x16x32_bf16 v[116:119], v[72:75], v[188:191], v[116:119]
	v_mfma_f32_16x16x32_bf16 v[112:115], v[64:67], v[206:209], v[112:115]
	v_mfma_f32_16x16x32_bf16 v[108:111], v[72:75], v[206:209], v[108:111]
	v_mfma_f32_16x16x32_bf16 v[140:143], v[68:71], v[184:187], v[136:139]
	v_mfma_f32_16x16x32_bf16 v[132:135], v[76:79], v[184:187], v[132:135]
	v_mfma_f32_16x16x32_bf16 v[124:127], v[68:71], v[192:195], v[124:127]
	v_mfma_f32_16x16x32_bf16 v[116:119], v[76:79], v[192:195], v[116:119]
	v_mfma_f32_16x16x32_bf16 v[112:115], v[68:71], v[212:215], v[112:115]
	v_mfma_f32_16x16x32_bf16 v[108:111], v[76:79], v[212:215], v[108:111]
	s_waitcnt lgkmcnt(0)
	v_mfma_f32_16x16x32_bf16 v[80:83], v[224:227], v[120:123], v[80:83]
	v_mfma_f32_16x16x32_bf16 v[136:139], v[216:219], v[120:123], v[152:155]
	v_mfma_f32_16x16x32_bf16 v[148:151], v[228:231], v[128:131], v[80:83]
	v_mfma_f32_16x16x32_bf16 v[80:83], v[216:219], v[180:183], v[84:87]
	v_mfma_f32_16x16x32_bf16 v[152:155], v[220:223], v[128:131], v[136:139]
	v_mfma_f32_16x16x32_bf16 v[136:139], v[220:223], v[184:187], v[80:83]
	v_mfma_f32_16x16x32_bf16 v[80:83], v[224:227], v[180:183], v[92:95]
	v_mfma_f32_16x16x32_bf16 v[128:131], v[228:231], v[184:187], v[80:83]
	v_mfma_f32_16x16x32_bf16 v[80:83], v[216:219], v[188:191], v[96:99]
	v_mfma_f32_16x16x32_bf16 v[120:123], v[220:223], v[192:195], v[80:83]
	v_mfma_f32_16x16x32_bf16 v[80:83], v[224:227], v[188:191], v[104:107]
	v_mfma_f32_16x16x32_bf16 v[104:107], v[228:231], v[192:195], v[80:83]
	v_mfma_f32_16x16x32_bf16 v[80:83], v[216:219], v[206:209], v[100:103]
	v_mfma_f32_16x16x32_bf16 v[100:103], v[220:223], v[212:215], v[80:83]
	v_mfma_f32_16x16x32_bf16 v[80:83], v[224:227], v[206:209], v[88:91]
	v_mfma_f32_16x16x32_bf16 v[88:91], v[228:231], v[212:215], v[80:83]
	s_barrier
	s_setprio 0
	s_add_i32 s49, s53, s60
	s_mov_b32 m0, s49
	s_nop 0
	global_load_lds_dwordx4 v164, s[98:99]
	s_add_i32 m0, s49, 0x2000
	s_nop 0
	global_load_lds_dwordx4 v160, s[98:99]
	s_mov_b32 m0, s67
	s_nop 2
	ds_read_b128 v[80:83], v202 offset:49152
	ds_read_b128 v[84:87], v202 offset:50176
	ds_read_b128 v[92:95], v202 offset:51200
	ds_read_b128 v[96:99], v202 offset:52224
	ds_read_b128 v[180:183], v202 offset:53248
	ds_read_b128 v[184:187], v202 offset:54272
	ds_read_b128 v[188:191], v202 offset:55296
	ds_read_b128 v[192:195], v202 offset:56320
	global_load_lds_dwordx4 v166, s[100:101]
	s_mov_b32 m0, s68
	s_nop 0
	global_load_lds_dwordx4 v162, s[100:101]
	s_add_u32 s46, s46, 0x80080
	s_addc_u32 s47, s47, 0
	s_add_i32 s48, s48, s60
	s_add_i32 s52, s52, 2
	s_add_u32 s14, s14, 0x100
	s_addc_u32 s15, s15, 0
	s_add_u32 s44, s44, 0x100
	s_addc_u32 s45, s45, 0
	s_cmp_gt_u32 s52, 29
	s_waitcnt vmcnt(6)
	s_waitcnt lgkmcnt(0)
	s_setprio 1
	s_barrier
	v_mfma_f32_16x16x32_bf16 v[60:63], v[64:67], v[80:83], v[60:63]
	s_mov_b32 m0, s48
	v_mfma_f32_16x16x32_bf16 v[48:51], v[72:75], v[80:83], v[48:51]
	global_load_lds_dwordx4 v164, s[46:47]
	v_mfma_f32_16x16x32_bf16 v[44:47], v[64:67], v[92:95], v[44:47]
	s_bitset1_b32 m0, 13
	v_mfma_f32_16x16x32_bf16 v[36:39], v[72:75], v[92:95], v[36:39]
	global_load_lds_dwordx4 v160, s[46:47]
	v_mfma_f32_16x16x32_bf16 v[28:31], v[64:67], v[180:183], v[28:31]
	v_mfma_f32_16x16x32_bf16 v[20:23], v[72:75], v[180:183], v[20:23]
	v_mfma_f32_16x16x32_bf16 v[16:19], v[64:67], v[188:191], v[16:19]
	v_mfma_f32_16x16x32_bf16 v[12:15], v[72:75], v[188:191], v[12:15]
	v_mfma_f32_16x16x32_bf16 v[60:63], v[68:71], v[84:87], v[60:63]
	v_mfma_f32_16x16x32_bf16 v[48:51], v[76:79], v[84:87], v[48:51]
	v_mfma_f32_16x16x32_bf16 v[44:47], v[68:71], v[96:99], v[44:47]
	v_mfma_f32_16x16x32_bf16 v[36:39], v[76:79], v[96:99], v[36:39]
	v_mfma_f32_16x16x32_bf16 v[28:31], v[68:71], v[184:187], v[28:31]
	v_mfma_f32_16x16x32_bf16 v[20:23], v[76:79], v[184:187], v[20:23]
	v_mfma_f32_16x16x32_bf16 v[16:19], v[68:71], v[192:195], v[16:19]
	v_mfma_f32_16x16x32_bf16 v[12:15], v[76:79], v[192:195], v[12:15]
	v_mfma_f32_16x16x32_bf16 v[56:59], v[216:219], v[80:83], v[56:59]
	v_mfma_f32_16x16x32_bf16 v[52:55], v[224:227], v[80:83], v[52:55]
	v_mfma_f32_16x16x32_bf16 v[40:43], v[216:219], v[92:95], v[40:43]
	v_mfma_f32_16x16x32_bf16 v[32:35], v[224:227], v[92:95], v[32:35]
	v_mfma_f32_16x16x32_bf16 v[24:27], v[216:219], v[180:183], v[24:27]
	v_mfma_f32_16x16x32_bf16 v[8:11], v[224:227], v[180:183], v[8:11]
	v_mfma_f32_16x16x32_bf16 v[4:7], v[216:219], v[188:191], v[4:7]
	v_mfma_f32_16x16x32_bf16 v[0:3], v[224:227], v[188:191], v[0:3]
	v_mfma_f32_16x16x32_bf16 v[56:59], v[220:223], v[84:87], v[56:59]
	v_mfma_f32_16x16x32_bf16 v[52:55], v[228:231], v[84:87], v[52:55]
	v_mfma_f32_16x16x32_bf16 v[40:43], v[220:223], v[96:99], v[40:43]
	v_mfma_f32_16x16x32_bf16 v[32:35], v[228:231], v[96:99], v[32:35]
	v_mfma_f32_16x16x32_bf16 v[24:27], v[220:223], v[184:187], v[24:27]
	v_mfma_f32_16x16x32_bf16 v[8:11], v[228:231], v[184:187], v[8:11]
	v_mfma_f32_16x16x32_bf16 v[4:7], v[220:223], v[192:195], v[4:7]
	v_mfma_f32_16x16x32_bf16 v[0:3], v[228:231], v[192:195], v[0:3]
	s_barrier
; DI float row_rstd(const float* ssq, int row, int fq) {
;   const f32x4 a = *(const f32x4*)(ssq + (size_t)row * 32 + fq * 8), b = *(const f32x4*)(ssq + (size_t)row * 32 + fq * 8 + 4);
;   float sm = ((a[0] + a[1]) + (a[2] + a[3])) + ((b[0] + b[1]) + (b[2] + b[3]));
;   sm += __shfl_xor(sm, 16); sm += __shfl_xor(sm, 32);
;   return rsqrtf(sm * (1.0f / 2048.f) + 1e-6f);
; }
;   DI void operator()(const f32x4 (&acc)[2][2][4][2], const Unit& u, int wr, int wc, int fr, int fq) const {
;     const int col = u.pn * 128 + wc * 32 + 8 * fq;
;     float w0[8], w1[8], w2[8], bb[8];
; #pragma unroll
;     for (int e = 0; e < 8; ++e) { w0[e] = cw[col + e]; w1[e] = cw[5632 + col + e]; w2[e] = cw[2 * 5632 + col + e]; bb[e] = cb[col + e]; }
; #pragma unroll
;     for (int ai = 0; ai < 2; ++ai) {
;       const int row0 = u.pm * BM + ai * HALF + wr * 64, span = row0 >> 6;
;       float rsv[4];
; #pragma unroll
;       for (int m = 0; m < 4; ++m) rsv[m] = row_rstd(ssq, row0 + 16 * m + fr, fq);
	s_setprio 0
	s_cbranch_scc0 .LBB0_811
	s_lshl_b32 s35, s12, 8
	s_add_i32 s35, s35, s66
	v_or_b32_e32 v190, s35, v179
	v_ashrrev_i32_e32 v191, 31, v190
	v_lshlrev_b64 v[64:65], 7, v[190:191]
	v_or_b32_e32 v188, 16, v190
	v_lshl_add_u64 v[64:65], v[168:169], 0, v[64:65]
	v_ashrrev_i32_e32 v189, 31, v188
	global_load_dwordx4 v[192:195], v[64:65], off
	global_load_dwordx4 v[206:209], v[64:65], off offset:16
	v_lshlrev_b64 v[64:65], 7, v[188:189]
	v_lshl_add_u64 v[64:65], v[168:169], 0, v[64:65]
	global_load_dwordx4 v[212:215], v[64:65], off
	global_load_dwordx4 v[216:219], v[64:65], off offset:16
	v_or_b32_e32 v186, 32, v190
	v_ashrrev_i32_e32 v187, 31, v186
	v_lshlrev_b64 v[64:65], 7, v[186:187]
	v_or_b32_e32 v184, 48, v190
	v_lshl_add_u64 v[64:65], v[168:169], 0, v[64:65]
	v_ashrrev_i32_e32 v185, 31, v184
	global_load_dwordx4 v[220:223], v[64:65], off
	global_load_dwordx4 v[224:227], v[64:65], off offset:16
	v_lshlrev_b64 v[64:65], 7, v[184:185]
	v_lshl_add_u64 v[64:65], v[168:169], 0, v[64:65]
	global_load_dwordx4 v[228:231], v[64:65], off
	global_load_dwordx4 v[232:235], v[64:65], off offset:16
	v_lshl_or_b32 v180, s13, 7, v200
	v_and_b32_e32 v65, 64, v204
	v_xor_b32_e32 v64, 16, v204
	v_ashrrev_i32_e32 v181, 31, v180
	v_add_u32_e32 v65, 64, v65
	v_readlane_b32 s44, v243, 3
	v_xor_b32_e32 v66, 32, v204
	v_lshlrev_b64 v[182:183], 2, v[180:181]
	v_cmp_lt_i32_e32 vcc, v64, v65
	v_readlane_b32 s52, v243, 11
	v_readlane_b32 s53, v243, 12
	v_cndmask_b32_e32 v64, v204, v64, vcc
	v_cmp_lt_i32_e32 vcc, v66, v65
	v_lshl_add_u64 v[92:93], s[52:53], 0, v[182:183]
	v_readlane_b32 s54, v243, 13
	v_cndmask_b32_e32 v65, v204, v66, vcc
	v_add_co_u32_e32 v94, vcc, 0x5000, v92
	v_readlane_b32 s55, v243, 14
	s_nop 0
	v_addc_co_u32_e32 v95, vcc, 0, v93, vcc
	v_add_co_u32_e32 v96, vcc, 0xb000, v92
	v_lshl_add_u64 v[72:73], s[54:55], 0, v[182:183]
	v_lshl_add_u64 v[74:75], v[92:93], 0, s[26:27]
	v_lshl_add_u64 v[76:77], v[92:93], 0, s[28:29]
	v_addc_co_u32_e32 v97, vcc, 0, v93, vcc
	v_lshlrev_b32_e32 v187, 2, v64
	v_lshlrev_b32_e32 v185, 2, v65
	global_load_dwordx4 v[64:67], v[92:93], off offset:16
	global_load_dwordx4 v[80:83], v[92:93], off
	global_load_dwordx4 v[68:71], v[72:73], off offset:16
	global_load_dwordx4 v[84:87], v[72:73], off
	s_nop 0
	global_load_dwordx4 v[72:75], v[74:75], off offset:16
	s_nop 0
	global_load_dwordx4 v[76:79], v[76:77], off offset:16
	s_nop 0
	global_load_dwordx4 v[92:95], v[94:95], off offset:2048
	s_nop 0
	global_load_dwordx4 v[96:99], v[96:97], off
	v_mov_b32_e32 v211, 0
	v_mov_b32_e32 v205, 0
	v_readlane_b32 s45, v243, 4
	v_readlane_b32 s46, v243, 5
	v_readlane_b32 s47, v243, 6
	v_readlane_b32 s48, v243, 7
	v_readlane_b32 s49, v243, 8
	v_readlane_b32 s50, v243, 9
	v_readlane_b32 s51, v243, 10
	v_readlane_b32 s56, v243, 15
	v_readlane_b32 s57, v243, 16
	v_readlane_b32 s58, v243, 17
	v_readlane_b32 s59, v243, 18
	s_waitcnt vmcnt(0)
	v_mov_b32_e32 v196, v192
	v_mov_b32_e32 v197, v206
	v_mov_b32_e32 v206, v193
	v_mov_b32_e32 v192, v194
	v_mov_b32_e32 v193, v208
	v_mov_b32_e32 v208, v195
	v_pk_add_f32 v[194:195], v[196:197], v[206:207]
	v_pk_add_f32 v[192:193], v[192:193], v[208:209]
	v_mov_b32_e32 v196, v212
	v_mov_b32_e32 v197, v216
	v_mov_b32_e32 v216, v213
	v_mov_b32_e32 v206, v214
	v_mov_b32_e32 v207, v218
	v_mov_b32_e32 v218, v215
	v_pk_add_f32 v[192:193], v[194:195], v[192:193]
	v_pk_add_f32 v[194:195], v[196:197], v[216:217]
	v_pk_add_f32 v[196:197], v[206:207], v[218:219]
	v_mov_b32_e32 v208, v220
	v_pk_add_f32 v[194:195], v[194:195], v[196:197]
	v_mov_b32_e32 v197, v192
	v_mov_b32_e32 v196, v194
	v_mov_b32_e32 v192, v195
	v_pk_add_f32 v[192:193], v[196:197], v[192:193]
	ds_bpermute_b32 v195, v187, v193
	ds_bpermute_b32 v194, v187, v192
	v_mov_b32_e32 v209, v224
	v_mov_b32_e32 v224, v221
	v_mov_b32_e32 v212, v222
	v_mov_b32_e32 v213, v226
	s_waitcnt lgkmcnt(0)
	v_pk_add_f32 v[192:193], v[192:193], v[194:195]
	ds_bpermute_b32 v195, v185, v193
	ds_bpermute_b32 v194, v185, v192
	v_mov_b32_e32 v226, v223
	v_mov_b32_e32 v196, v228
	v_mov_b32_e32 v197, v232
	v_mov_b32_e32 v232, v229
	s_waitcnt lgkmcnt(0)
; DI unsigned pack2(float lo, float hi) { f32x2 v = {lo, hi}; bf16v2 r = __builtin_convertvector(v, bf16v2); return __builtin_bit_cast(unsigned, r); }
; DI float silu_f(float x) { return x * sigmoid_f(x); }
; DI float dpp_ror1(float v) { return __int_as_float(__builtin_amdgcn_update_dpp(0, __float_as_int(v), 0x121, 0xf, 0xf, false)); }
; DI float dpp_ror2(float v) { return __int_as_float(__builtin_amdgcn_update_dpp(0, __float_as_int(v), 0x122, 0xf, 0xf, false)); }
;   DI void operator()(const f32x4 (&acc)[2][2][4][2], const Unit& u, int wr, int wc, int fr, int fq) const {
;     ...
;       float p1[8], p2[8];
; #pragma unroll
;       for (int e = 0; e < 8; ++e) { p1[e] = 0.f; p2[e] = 0.f; }
; #pragma unroll
;       for (int m = 0; m < 4; ++m) {
;         float g[8], uu[8], a[8];
;         const float rs = rsv[m];
; #pragma unroll
;         for (int e = 0; e < 4; ++e) { g[e] = acc[ai][0][m][0][e] * rs; g[4 + e] = acc[ai][0][m][1][e] * rs; uu[e] = acc[ai][1][m][0][e] * rs; uu[4 + e] = acc[ai][1][m][1][e] * rs; }
; #pragma unroll
;         for (int e = 0; e < 8; ++e) {
;           const float x1 = dpp_ror1(g[e]), x2 = dpp_ror2(g[e]);
;           const float pr1 = (fr == 0) ? p1[e] : x1, pr2 = (fr < 2) ? p2[e] : x2;
;           a[e] = w2[e] * g[e] + w1[e] * pr1 + w0[e] * pr2 + bb[e];
;           p1[e] = x1; p2[e] = x2;
;         }
;         if (m == 0 && fr < 2) {
;           float* ha = headA + (size_t)(span * 2 + fr) * 5632 + col; float* hu = headU + (size_t)(span * 2 + fr) * 5632 + col;
;           *(f32x4*)ha = (f32x4){a[0], a[1], a[2], a[3]}; *(f32x4*)(ha + 4) = (f32x4){a[4], a[5], a[6], a[7]};
;           *(f32x4*)hu = (f32x4){uu[0], uu[1], uu[2], uu[3]}; *(f32x4*)(hu + 4) = (f32x4){uu[4], uu[5], uu[6], uu[7]};
;         } else {
;           u32x4 w;
;           w.x = pack2(silu_f(a[0]) * uu[0], silu_f(a[1]) * uu[1]);
;           w.y = pack2(silu_f(a[2]) * uu[2], silu_f(a[3]) * uu[3]);
;           w.z = pack2(silu_f(a[4]) * uu[4], silu_f(a[5]) * uu[5]);
;           w.w = pack2(silu_f(a[6]) * uu[6], silu_f(a[7]) * uu[7]);
;           *(u32x4*)(H + (size_t)(row0 + 16 * m + fr) * 5632 + col) = w;
;         }
	v_pk_add_f32 v[192:193], v[192:193], v[194:195]
	v_mov_b32_e32 v206, v230
	v_pk_fma_f32 v[192:193], v[192:193], s[30:31], v[178:179] op_sel_hi:[1,0,0]
	v_mov_b32_e32 v207, v234
	v_mul_f32_e32 v189, 0x4b800000, v193
	v_cmp_gt_f32_e64 s[12:13], s74, v193
	v_mov_b32_e32 v234, v231
	v_pk_add_f32 v[208:209], v[208:209], v[224:225]
	v_cndmask_b32_e64 v189, v193, v189, s[12:13]
	v_rsq_f32_e32 v189, v189
	v_pk_add_f32 v[212:213], v[212:213], v[226:227]
	v_pk_add_f32 v[196:197], v[196:197], v[232:233]
	v_pk_add_f32 v[194:195], v[206:207], v[234:235]
	v_mul_f32_e32 v191, 0x45800000, v189
	v_cndmask_b32_e64 v220, v189, v191, s[12:13]
	v_pk_add_f32 v[208:209], v[208:209], v[212:213]
	v_pk_add_f32 v[194:195], v[196:197], v[194:195]
	v_pk_mul_f32 v[156:157], v[156:157], v[220:221] op_sel_hi:[1,0]
	v_mov_b32_e32 v216, 0
	v_mov_b32_e32 v218, 0
	v_mov_b32_e32 v196, v194
	v_mov_b32_e32 v197, v208
	v_mov_b32_e32 v208, v195
	v_mov_b32_dpp v216, v156 row_ror:1 row_mask:0xf bank_mask:0xf
	v_mov_b32_dpp v218, v157 row_ror:1 row_mask:0xf bank_mask:0xf
	v_pk_add_f32 v[194:195], v[196:197], v[208:209]
	v_cndmask_b32_e64 v207, v218, 0, s[0:1]
	v_cndmask_b32_e64 v206, v216, 0, s[0:1]
	v_pk_mul_f32 v[158:159], v[158:159], v[220:221] op_sel_hi:[1,0]
	v_mov_b32_e32 v212, 0
	v_mov_b32_e32 v214, 0
	ds_bpermute_b32 v197, v187, v195
	ds_bpermute_b32 v196, v187, v194
	v_mov_b32_e32 v215, 0
	v_mov_b32_e32 v217, 0
	v_pk_mul_f32 v[206:207], v[92:93], v[206:207]
	v_mov_b32_dpp v212, v158 row_ror:1 row_mask:0xf bank_mask:0xf
	v_mov_b32_dpp v214, v159 row_ror:1 row_mask:0xf bank_mask:0xf
	v_mov_b32_dpp v215, v156 row_ror:2 row_mask:0xf bank_mask:0xf
	v_mov_b32_dpp v217, v157 row_ror:2 row_mask:0xf bank_mask:0xf
	v_pk_fma_f32 v[156:157], v[96:97], v[156:157], v[206:207]
	v_mov_b32_e32 v213, 0
	v_cndmask_b32_e64 v207, v214, 0, s[0:1]
	v_cndmask_b32_e64 v206, v212, 0, s[0:1]
	v_cndmask_b32_e64 v209, v217, 0, s[4:5]
	v_cndmask_b32_e64 v208, v215, 0, s[4:5]
	v_mov_b32_dpp v211, v158 row_ror:2 row_mask:0xf bank_mask:0xf
	v_mov_b32_dpp v213, v159 row_ror:2 row_mask:0xf bank_mask:0xf
	v_pk_mul_f32 v[206:207], v[94:95], v[206:207]
	v_pk_fma_f32 v[156:157], v[80:81], v[208:209], v[156:157]
	v_cndmask_b32_e64 v209, v213, 0, s[4:5]
	v_cndmask_b32_e64 v208, v211, 0, s[4:5]
	v_pk_fma_f32 v[158:159], v[98:99], v[158:159], v[206:207]
	v_pk_mul_f32 v[144:145], v[144:145], v[220:221] op_sel_hi:[1,0]
	v_pk_fma_f32 v[158:159], v[82:83], v[208:209], v[158:159]
	v_mov_b32_e32 v207, 0
	v_mov_b32_e32 v209, 0
	v_pk_mul_f32 v[146:147], v[146:147], v[220:221] op_sel_hi:[1,0]
	v_mov_b32_e32 v191, 0
	s_waitcnt lgkmcnt(0)
	v_pk_add_f32 v[194:195], v[194:195], v[196:197]
	v_mov_b32_dpp v207, v144 row_ror:1 row_mask:0xf bank_mask:0xf
	v_mov_b32_dpp v209, v145 row_ror:1 row_mask:0xf bank_mask:0xf
	v_mov_b32_dpp v191, v146 row_ror:1 row_mask:0xf bank_mask:0xf
	v_mov_b32_dpp v205, v147 row_ror:1 row_mask:0xf bank_mask:0xf
	ds_bpermute_b32 v197, v185, v195
	ds_bpermute_b32 v196, v185, v194
	v_pk_mul_f32 v[152:153], v[152:153], v[220:221] op_sel_hi:[1,0]
	v_pk_mul_f32 v[148:149], v[148:149], v[220:221] op_sel_hi:[1,0]
	v_pk_mul_f32 v[154:155], v[154:155], v[220:221] op_sel_hi:[1,0]
	v_pk_mul_f32 v[150:151], v[150:151], v[220:221] op_sel_hi:[1,0]
	v_mov_b32_e32 v206, 0
	v_mov_b32_e32 v208, 0
	v_cndmask_b32_e64 v223, v209, 0, s[0:1]
	v_cndmask_b32_e64 v222, v207, 0, s[0:1]
	v_mov_b32_e32 v189, 0
	v_mov_b32_e32 v193, 0
	v_cndmask_b32_e64 v221, v205, 0, s[0:1]
	v_cndmask_b32_e64 v220, v191, 0, s[0:1]
	v_mov_b32_dpp v206, v144 row_ror:2 row_mask:0xf bank_mask:0xf
	v_mov_b32_dpp v208, v145 row_ror:2 row_mask:0xf bank_mask:0xf
	v_pk_mul_f32 v[222:223], v[72:73], v[222:223]
	v_mov_b32_dpp v189, v146 row_ror:2 row_mask:0xf bank_mask:0xf
	v_mov_b32_dpp v193, v147 row_ror:2 row_mask:0xf bank_mask:0xf
	v_pk_mul_f32 v[220:221], v[74:75], v[220:221]
	v_cndmask_b32_e64 v225, v208, 0, s[4:5]
	v_cndmask_b32_e64 v224, v206, 0, s[4:5]
	v_pk_fma_f32 v[144:145], v[76:77], v[144:145], v[222:223]
	v_cndmask_b32_e64 v223, v193, 0, s[4:5]
	v_cndmask_b32_e64 v222, v189, 0, s[4:5]
	v_pk_fma_f32 v[146:147], v[78:79], v[146:147], v[220:221]
	v_pk_fma_f32 v[144:145], v[64:65], v[224:225], v[144:145]
	v_pk_fma_f32 v[146:147], v[66:67], v[222:223], v[146:147]
	v_cmp_gt_f32_e32 vcc, s74, v192
	v_pk_add_f32 v[156:157], v[84:85], v[156:157]
	v_pk_add_f32 v[158:159], v[86:87], v[158:159]
	v_pk_add_f32 v[144:145], v[68:69], v[144:145]
	v_pk_add_f32 v[146:147], v[70:71], v[146:147]
	s_and_saveexec_b64 s[12:13], s[10:11]
	s_xor_b64 s[12:13], exec, s[12:13]
	s_cbranch_execz .LBB0_814
	v_mul_f32_e32 v219, 0xbfb8aa3b, v156
	v_exp_f32_e32 v219, v219
	v_mul_f32_e32 v220, 0xbfb8aa3b, v157
	v_exp_f32_e32 v220, v220
	v_mul_f32_e32 v222, 0xbfb8aa3b, v159
	v_add_f32_e32 v219, 1.0, v219
	v_exp_f32_e32 v223, v222
	v_add_f32_e32 v221, 1.0, v220
	v_rcp_f32_e32 v220, v219
	v_mul_f32_e32 v219, 0xbfb8aa3b, v158
	v_exp_f32_e32 v219, v219
	v_rcp_f32_e32 v221, v221
	v_add_f32_e32 v219, 1.0, v219
	v_rcp_f32_e32 v222, v219
	v_add_f32_e32 v219, 1.0, v223
	v_rcp_f32_e32 v223, v219
	v_pk_mul_f32 v[156:157], v[156:157], v[220:221]
	s_nop 0
	v_pk_mul_f32 v[152:153], v[152:153], v[156:157]
	v_pk_mul_f32 v[156:157], v[158:159], v[222:223]
	v_cvt_pk_bf16_f32 v152, v152, v153
	v_mul_f32_e32 v153, 0xbfb8aa3b, v144
	v_pk_mul_f32 v[154:155], v[154:155], v[156:157]
	v_exp_f32_e32 v156, v153
	v_mul_f32_e32 v153, 0xbfb8aa3b, v145
	v_exp_f32_e32 v157, v153
	v_cvt_pk_bf16_f32 v153, v154, v155
	v_add_f32_e32 v154, 1.0, v156
	v_mul_f32_e32 v156, 0xbfb8aa3b, v146
	v_add_f32_e32 v155, 1.0, v157
	v_mul_f32_e32 v157, 0xbfb8aa3b, v147
	v_exp_f32_e32 v156, v156
	v_exp_f32_e32 v157, v157
	v_rcp_f32_e32 v154, v154
	v_rcp_f32_e32 v155, v155
	v_add_f32_e32 v156, 1.0, v156
	v_add_f32_e32 v157, 1.0, v157
	v_rcp_f32_e32 v156, v156
	v_rcp_f32_e32 v157, v157
	v_pk_mul_f32 v[144:145], v[144:145], v[154:155]
	s_nop 0
	v_pk_mul_f32 v[144:145], v[148:149], v[144:145]
	s_nop 0
	v_cvt_pk_bf16_f32 v154, v144, v145
	v_pk_mul_f32 v[144:145], v[146:147], v[156:157]
	s_nop 0
	v_pk_mul_f32 v[144:145], v[150:151], v[144:145]
	s_nop 0
	v_cvt_pk_bf16_f32 v155, v144, v145
	v_mov_b64_e32 v[144:145], s[16:17]
	v_mad_i64_i32 v[144:145], s[14:15], v190, s75, v[144:145]
	v_lshl_add_u64 v[144:145], v[180:181], 1, v[144:145]
	global_store_dwordx4 v[144:145], v[152:155], off

; #define PG8_STAGE(bufoff, gbase, voff) do { _Pragma("unroll") for (int _i = 0; _i < 2; ++_i) \
;     __builtin_amdgcn_global_load_lds((const unsigned*)((const char*)(gbase) + (voff)[_i]), (LAS unsigned*)(lds + (bufoff) + ldsw + _i * 8192), 16, 0, 0); } while (0)
; #define PG8_LDA(dst, b, h) do { _Pragma("unroll") for (int m = 0; m < 4; ++m) _Pragma("unroll") for (int k = 0; k < 2; ++k) dst[m][k] = *(const LAS bf16x8*)(lds + PG8_SA(b, h) + aoff + m * 2048 + k * 1024); } while (0)
; #define PG8_LDB(dst, b, h) do { _Pragma("unroll") for (int n = 0; n < 2; ++n) _Pragma("unroll") for (int k = 0; k < 2; ++k) dst[n][k] = *(const LAS bf16x8*)(lds + PG8_SB(b, h) + boff + n * 2048 + k * 1024); } while (0)
; #define PG8_MMA(ai, bj, At, Bt) do { __builtin_amdgcn_s_setprio(1); _Pragma("unroll") for (int m = 0; m < 4; ++m) _Pragma("unroll") for (int n = 0; n < 2; ++n) _Pragma("unroll") for (int k = 0; k < 2; ++k) \
;     acc[ai][bj][m][n] = __builtin_amdgcn_mfma_f32_16x16x32_bf16(Bt[n][k], At[m][k], acc[ai][bj][m][n], 0, 0, 0); __builtin_amdgcn_s_setprio(0); } while (0)
; #define PG8_WAIT_V(n) asm volatile("s_waitcnt vmcnt(" #n ")" ::: "memory")
; #define PG8_WAIT_L(n) asm volatile("s_waitcnt lgkmcnt(" #n ")" ::: "memory")
; #define PG8_BAR __builtin_amdgcn_s_barrier()
; #define PG8_SCHED __builtin_amdgcn_sched_barrier(0)
; template <class Epi, class Sched = StaticOrder>
; DI void gemm_phase(LAS unsigned char* lds, const Gemm g, const Sched& S, const Epi& E) {
;     ...
;       const char* a1 = cA + (size_t)(t + 1) * kstep;
;       const char* a2 = last ? nA : cA + (size_t)(t + 2) * kstep; const char* b2 = last ? nB : cB + (size_t)(t + 2) * kstep;
;       const char* a3 = a2 + kstep; const char* b3 = b2 + kstep;
;       PG8_LDB(B0, 0, 0); PG8_SCHED; PG8_LDA(At, 0, 0); PG8_STAGE(PG8_SA(1, 1), a1 + hstep, voffA);
;       PG8_WAIT_L(8); PG8_BAR; PG8_WAIT_L(0); PG8_MMA(0, 0, At, B0); PG8_BAR; PG8_SCHED;
;       PG8_LDB(B1, 0, 1); PG8_STAGE(PG8_SB(0, 0), b2, voffB);
;       PG8_BAR; PG8_WAIT_L(0); PG8_MMA(0, 1, At, B1); PG8_BAR;
;       PG8_LDA(At, 0, 1); PG8_STAGE(PG8_SA(0, 0), a2, voffA);
;       PG8_BAR; PG8_WAIT_L(0); PG8_MMA(1, 0, At, B0); PG8_BAR; PG8_SCHED;
;       PG8_STAGE(PG8_SB(0, 1), b2 + hstep, voffB);
;       PG8_WAIT_V(6); PG8_BAR; PG8_MMA(1, 1, At, B1); PG8_BAR;
.LBB0_961:
	ds_read_b128 v[128:131], v214
	ds_read_b128 v[132:135], v214 offset:1024
	ds_read_b128 v[136:139], v214 offset:2048
	ds_read_b128 v[140:143], v214 offset:3072
	s_add_u32 s20, s18, 0xffea0080
	s_addc_u32 s21, s19, -1
	s_cmpk_eq_i32 s44, 0x54
	s_cselect_b32 s23, s5, s21
	s_cselect_b32 s22, s4, s20
	s_cselect_b32 s21, s7, s43
	s_cselect_b32 s20, s6, s42
	s_add_i32 m0, s31, 0xc000
	ds_read_b128 v[144:147], v215
	ds_read_b128 v[148:151], v215 offset:1024
	ds_read_b128 v[152:155], v215 offset:2048
	ds_read_b128 v[156:159], v215 offset:3072
	ds_read_b128 v[160:163], v215 offset:4096
	ds_read_b128 v[164:167], v215 offset:5120
	ds_read_b128 v[168:171], v215 offset:6144
	ds_read_b128 v[172:175], v215 offset:7168
	global_load_lds_dwordx4 v184, s[18:19]
	s_add_i32 m0, s31, 0xe000
	s_nop 0
	global_load_lds_dwordx4 v186, s[18:19]
	ds_read_b128 v[192:195], v216
	ds_read_b128 v[196:199], v216 offset:1024
	ds_read_b128 v[200:203], v216 offset:2048
	ds_read_b128 v[204:207], v216 offset:3072
	s_waitcnt vmcnt(8)
	s_waitcnt lgkmcnt(4)
	s_setprio 1
	s_barrier
	v_mfma_f32_16x16x32_bf16 v[124:127], v[128:131], v[144:147], v[124:127]
	v_mfma_f32_16x16x32_bf16 v[120:123], v[136:139], v[144:147], v[120:123]
	v_mfma_f32_16x16x32_bf16 v[108:111], v[128:131], v[152:155], v[108:111]
	v_mfma_f32_16x16x32_bf16 v[104:107], v[136:139], v[152:155], v[104:107]
	v_mfma_f32_16x16x32_bf16 v[92:95], v[128:131], v[160:163], v[92:95]
	v_mfma_f32_16x16x32_bf16 v[88:91], v[136:139], v[160:163], v[88:91]
	v_mfma_f32_16x16x32_bf16 v[76:79], v[128:131], v[168:171], v[76:79]
	v_mfma_f32_16x16x32_bf16 v[72:75], v[136:139], v[168:171], v[72:75]
	v_mfma_f32_16x16x32_bf16 v[124:127], v[132:135], v[148:151], v[124:127]
	v_mfma_f32_16x16x32_bf16 v[120:123], v[140:143], v[148:151], v[120:123]
	v_mfma_f32_16x16x32_bf16 v[108:111], v[132:135], v[156:159], v[108:111]
	v_mfma_f32_16x16x32_bf16 v[104:107], v[140:143], v[156:159], v[104:107]
	v_mfma_f32_16x16x32_bf16 v[92:95], v[132:135], v[164:167], v[92:95]
	v_mfma_f32_16x16x32_bf16 v[88:91], v[140:143], v[164:167], v[88:91]
	v_mfma_f32_16x16x32_bf16 v[76:79], v[132:135], v[172:175], v[76:79]
	v_mfma_f32_16x16x32_bf16 v[72:75], v[140:143], v[172:175], v[72:75]
	s_waitcnt lgkmcnt(0)
	v_mfma_f32_16x16x32_bf16 v[116:119], v[192:195], v[144:147], v[116:119]
	v_mfma_f32_16x16x32_bf16 v[112:115], v[200:203], v[144:147], v[112:115]
	v_mfma_f32_16x16x32_bf16 v[100:103], v[192:195], v[152:155], v[100:103]
	v_mfma_f32_16x16x32_bf16 v[96:99], v[200:203], v[152:155], v[96:99]
	v_mfma_f32_16x16x32_bf16 v[84:87], v[192:195], v[160:163], v[84:87]
	v_mfma_f32_16x16x32_bf16 v[80:83], v[200:203], v[160:163], v[80:83]
	v_mfma_f32_16x16x32_bf16 v[68:71], v[192:195], v[168:171], v[68:71]
	v_mfma_f32_16x16x32_bf16 v[64:67], v[200:203], v[168:171], v[64:67]
	v_mfma_f32_16x16x32_bf16 v[116:119], v[196:199], v[148:151], v[116:119]
	v_mfma_f32_16x16x32_bf16 v[112:115], v[204:207], v[148:151], v[112:115]
	v_mfma_f32_16x16x32_bf16 v[100:103], v[196:199], v[156:159], v[100:103]
	v_mfma_f32_16x16x32_bf16 v[96:99], v[204:207], v[156:159], v[96:99]
	v_mfma_f32_16x16x32_bf16 v[84:87], v[196:199], v[164:167], v[84:87]
	v_mfma_f32_16x16x32_bf16 v[80:83], v[204:207], v[164:167], v[80:83]
	v_mfma_f32_16x16x32_bf16 v[68:71], v[196:199], v[172:175], v[68:71]
	v_mfma_f32_16x16x32_bf16 v[64:67], v[204:207], v[172:175], v[64:67]
	s_barrier
	s_setprio 0
	s_add_i32 s45, s46, s30
	s_add_u32 s98, s20, 0x80
	s_addc_u32 s99, s21, 0
	s_add_u32 s100, s22, 0x80
	s_addc_u32 s101, s23, 0
	s_mov_b32 m0, s45
	s_nop 0
	global_load_lds_dwordx4 v178, s[20:21]
	s_add_i32 m0, s45, 0x2000
	s_nop 0
	global_load_lds_dwordx4 v182, s[20:21]
	s_mov_b32 m0, s31
	ds_read_b128 v[144:147], v215 offset:16384
	ds_read_b128 v[148:151], v215 offset:17408
	ds_read_b128 v[152:155], v215 offset:18432
	ds_read_b128 v[156:159], v215 offset:19456
	ds_read_b128 v[160:163], v215 offset:20480
	ds_read_b128 v[164:167], v215 offset:21504
	ds_read_b128 v[168:171], v215 offset:22528
	ds_read_b128 v[172:175], v215 offset:23552
	global_load_lds_dwordx4 v176, s[22:23]
	s_mov_b32 m0, s33
	s_nop 0
	global_load_lds_dwordx4 v180, s[22:23]
	s_add_u32 s52, s20, 0x160000
	s_addc_u32 s53, s21, 0
	s_add_i32 s45, s47, s30
	s_waitcnt vmcnt(6)
	s_waitcnt lgkmcnt(0)
	s_setprio 1
	s_barrier
	v_mfma_f32_16x16x32_bf16 v[60:63], v[128:131], v[144:147], v[60:63]
	s_mov_b32 m0, s45
	v_mfma_f32_16x16x32_bf16 v[56:59], v[136:139], v[144:147], v[56:59]
	global_load_lds_dwordx4 v178, s[52:53]
	v_mfma_f32_16x16x32_bf16 v[44:47], v[128:131], v[152:155], v[44:47]
	s_bitset1_b32 m0, 13
	v_mfma_f32_16x16x32_bf16 v[40:43], v[136:139], v[152:155], v[40:43]
	global_load_lds_dwordx4 v182, s[52:53]
	v_mfma_f32_16x16x32_bf16 v[28:31], v[128:131], v[160:163], v[28:31]
	v_mfma_f32_16x16x32_bf16 v[24:27], v[136:139], v[160:163], v[24:27]
	v_mfma_f32_16x16x32_bf16 v[12:15], v[128:131], v[168:171], v[12:15]
	v_mfma_f32_16x16x32_bf16 v[8:11], v[136:139], v[168:171], v[8:11]
	v_mfma_f32_16x16x32_bf16 v[60:63], v[132:135], v[148:151], v[60:63]
	v_mfma_f32_16x16x32_bf16 v[56:59], v[140:143], v[148:151], v[56:59]
	v_mfma_f32_16x16x32_bf16 v[44:47], v[132:135], v[156:159], v[44:47]
	v_mfma_f32_16x16x32_bf16 v[40:43], v[140:143], v[156:159], v[40:43]
	v_mfma_f32_16x16x32_bf16 v[28:31], v[132:135], v[164:167], v[28:31]
	v_mfma_f32_16x16x32_bf16 v[24:27], v[140:143], v[164:167], v[24:27]
	v_mfma_f32_16x16x32_bf16 v[12:15], v[132:135], v[172:175], v[12:15]
	v_mfma_f32_16x16x32_bf16 v[8:11], v[140:143], v[172:175], v[8:11]
	v_mfma_f32_16x16x32_bf16 v[52:55], v[192:195], v[144:147], v[52:55]
	v_mfma_f32_16x16x32_bf16 v[48:51], v[200:203], v[144:147], v[48:51]
	v_mfma_f32_16x16x32_bf16 v[36:39], v[192:195], v[152:155], v[36:39]
	v_mfma_f32_16x16x32_bf16 v[32:35], v[200:203], v[152:155], v[32:35]
	v_mfma_f32_16x16x32_bf16 v[20:23], v[192:195], v[160:163], v[20:23]
	v_mfma_f32_16x16x32_bf16 v[16:19], v[200:203], v[160:163], v[16:19]
	v_mfma_f32_16x16x32_bf16 v[4:7], v[192:195], v[168:171], v[4:7]
	v_mfma_f32_16x16x32_bf16 v[0:3], v[200:203], v[168:171], v[0:3]
	v_mfma_f32_16x16x32_bf16 v[52:55], v[196:199], v[148:151], v[52:55]
	v_mfma_f32_16x16x32_bf16 v[48:51], v[204:207], v[148:151], v[48:51]
	v_mfma_f32_16x16x32_bf16 v[36:39], v[196:199], v[156:159], v[36:39]
	v_mfma_f32_16x16x32_bf16 v[32:35], v[204:207], v[156:159], v[32:35]
	v_mfma_f32_16x16x32_bf16 v[20:23], v[196:199], v[164:167], v[20:23]
	v_mfma_f32_16x16x32_bf16 v[16:19], v[204:207], v[164:167], v[16:19]
	v_mfma_f32_16x16x32_bf16 v[4:7], v[196:199], v[172:175], v[4:7]
	v_mfma_f32_16x16x32_bf16 v[0:3], v[204:207], v[172:175], v[0:3]
	s_barrier
; #define PG8_STAGE(bufoff, gbase, voff) do { _Pragma("unroll") for (int _i = 0; _i < 2; ++_i) \
;     __builtin_amdgcn_global_load_lds((const unsigned*)((const char*)(gbase) + (voff)[_i]), (LAS unsigned*)(lds + (bufoff) + ldsw + _i * 8192), 16, 0, 0); } while (0)
; #define PG8_LDA(dst, b, h) do { _Pragma("unroll") for (int m = 0; m < 4; ++m) _Pragma("unroll") for (int k = 0; k < 2; ++k) dst[m][k] = *(const LAS bf16x8*)(lds + PG8_SA(b, h) + aoff + m * 2048 + k * 1024); } while (0)
; #define PG8_LDB(dst, b, h) do { _Pragma("unroll") for (int n = 0; n < 2; ++n) _Pragma("unroll") for (int k = 0; k < 2; ++k) dst[n][k] = *(const LAS bf16x8*)(lds + PG8_SB(b, h) + boff + n * 2048 + k * 1024); } while (0)
; #define PG8_MMA(ai, bj, At, Bt) do { __builtin_amdgcn_s_setprio(1); _Pragma("unroll") for (int m = 0; m < 4; ++m) _Pragma("unroll") for (int n = 0; n < 2; ++n) _Pragma("unroll") for (int k = 0; k < 2; ++k) \
;     acc[ai][bj][m][n] = __builtin_amdgcn_mfma_f32_16x16x32_bf16(Bt[n][k], At[m][k], acc[ai][bj][m][n], 0, 0, 0); __builtin_amdgcn_s_setprio(0); } while (0)
; #define PG8_WAIT_V(n) asm volatile("s_waitcnt vmcnt(" #n ")" ::: "memory")
; #define PG8_WAIT_L(n) asm volatile("s_waitcnt lgkmcnt(" #n ")" ::: "memory")
; #define PG8_BAR __builtin_amdgcn_s_barrier()
; #define PG8_SCHED __builtin_amdgcn_sched_barrier(0)
; template <class Epi, class Sched = StaticOrder>
; DI void gemm_phase(LAS unsigned char* lds, const Gemm g, const Sched& S, const Epi& E) {
;     ...
;       PG8_LDB(B0, 1, 0); PG8_SCHED; PG8_LDA(At, 1, 0); PG8_STAGE(PG8_SA(0, 1), a2 + hstep, voffA);
;       PG8_WAIT_L(8); PG8_BAR; PG8_WAIT_L(0); PG8_MMA(0, 0, At, B0); PG8_BAR; PG8_SCHED;
;       PG8_LDB(B1, 1, 1); PG8_STAGE(PG8_SB(1, 0), b3, voffB);
;       PG8_BAR; PG8_WAIT_L(0); PG8_MMA(0, 1, At, B1); PG8_BAR;
;       PG8_LDA(At, 1, 1); PG8_STAGE(PG8_SA(1, 0), a3, voffA);
;       PG8_BAR; PG8_WAIT_L(0); PG8_MMA(1, 0, At, B0); PG8_BAR; PG8_SCHED;
;       PG8_STAGE(PG8_SB(1, 1), b3 + hstep, voffB);
;       PG8_WAIT_V(6); PG8_BAR; PG8_MMA(1, 1, At, B1); PG8_BAR;
	s_setprio 0
	s_add_i32 s45, 0, 0x18000
	v_add_u32_e32 v140, s45, v212
	ds_read_b128 v[128:131], v140
	ds_read_b128 v[132:135], v140 offset:1024
	ds_read_b128 v[136:139], v140 offset:2048
	ds_read_b128 v[140:143], v140 offset:3072
	s_add_u32 s22, s22, 0x160000
	s_addc_u32 s23, s23, 0
	s_mov_b32 m0, s34
	ds_read_b128 v[144:147], v215 offset:32768
	ds_read_b128 v[148:151], v215 offset:33792
	ds_read_b128 v[152:155], v215 offset:34816
	ds_read_b128 v[156:159], v215 offset:35840
	ds_read_b128 v[160:163], v215 offset:36864
	ds_read_b128 v[164:167], v215 offset:37888
	ds_read_b128 v[168:171], v215 offset:38912
	ds_read_b128 v[172:175], v215 offset:39936
	global_load_lds_dwordx4 v176, s[22:23]
	s_mov_b32 m0, s35
	s_nop 0
	global_load_lds_dwordx4 v180, s[22:23]
	s_add_i32 s22, 0, 0x1c000
	v_add_u32_e32 v204, s22, v212
	ds_read_b128 v[192:195], v204
	ds_read_b128 v[196:199], v204 offset:1024
	ds_read_b128 v[200:203], v204 offset:2048
	ds_read_b128 v[204:207], v204 offset:3072
	s_waitcnt vmcnt(8)
	s_waitcnt lgkmcnt(4)
	s_setprio 1
	s_barrier
	v_mfma_f32_16x16x32_bf16 v[124:127], v[128:131], v[144:147], v[124:127]
	v_mfma_f32_16x16x32_bf16 v[120:123], v[136:139], v[144:147], v[120:123]
	v_mfma_f32_16x16x32_bf16 v[108:111], v[128:131], v[152:155], v[108:111]
	v_mfma_f32_16x16x32_bf16 v[104:107], v[136:139], v[152:155], v[104:107]
	v_mfma_f32_16x16x32_bf16 v[92:95], v[128:131], v[160:163], v[92:95]
	v_mfma_f32_16x16x32_bf16 v[88:91], v[136:139], v[160:163], v[88:91]
	v_mfma_f32_16x16x32_bf16 v[76:79], v[128:131], v[168:171], v[76:79]
	v_mfma_f32_16x16x32_bf16 v[72:75], v[136:139], v[168:171], v[72:75]
	v_mfma_f32_16x16x32_bf16 v[124:127], v[132:135], v[148:151], v[124:127]
	v_mfma_f32_16x16x32_bf16 v[120:123], v[140:143], v[148:151], v[120:123]
	v_mfma_f32_16x16x32_bf16 v[108:111], v[132:135], v[156:159], v[108:111]
	v_mfma_f32_16x16x32_bf16 v[104:107], v[140:143], v[156:159], v[104:107]
	v_mfma_f32_16x16x32_bf16 v[92:95], v[132:135], v[164:167], v[92:95]
	v_mfma_f32_16x16x32_bf16 v[88:91], v[140:143], v[164:167], v[88:91]
	v_mfma_f32_16x16x32_bf16 v[76:79], v[132:135], v[172:175], v[76:79]
	v_mfma_f32_16x16x32_bf16 v[72:75], v[140:143], v[172:175], v[72:75]
	s_waitcnt lgkmcnt(0)
	v_mfma_f32_16x16x32_bf16 v[116:119], v[192:195], v[144:147], v[116:119]
	v_mfma_f32_16x16x32_bf16 v[112:115], v[200:203], v[144:147], v[112:115]
	v_mfma_f32_16x16x32_bf16 v[100:103], v[192:195], v[152:155], v[100:103]
	v_mfma_f32_16x16x32_bf16 v[96:99], v[200:203], v[152:155], v[96:99]
	v_mfma_f32_16x16x32_bf16 v[84:87], v[192:195], v[160:163], v[84:87]
	v_mfma_f32_16x16x32_bf16 v[80:83], v[200:203], v[160:163], v[80:83]
	v_mfma_f32_16x16x32_bf16 v[68:71], v[192:195], v[168:171], v[68:71]
	v_mfma_f32_16x16x32_bf16 v[64:67], v[200:203], v[168:171], v[64:67]
	v_mfma_f32_16x16x32_bf16 v[116:119], v[196:199], v[148:151], v[116:119]
	v_mfma_f32_16x16x32_bf16 v[112:115], v[204:207], v[148:151], v[112:115]
	v_mfma_f32_16x16x32_bf16 v[100:103], v[196:199], v[156:159], v[100:103]
	v_mfma_f32_16x16x32_bf16 v[96:99], v[204:207], v[156:159], v[96:99]
	v_mfma_f32_16x16x32_bf16 v[84:87], v[196:199], v[164:167], v[84:87]
	v_mfma_f32_16x16x32_bf16 v[80:83], v[204:207], v[164:167], v[80:83]
	v_mfma_f32_16x16x32_bf16 v[68:71], v[196:199], v[172:175], v[68:71]
	v_mfma_f32_16x16x32_bf16 v[64:67], v[204:207], v[172:175], v[64:67]
	s_barrier
	s_setprio 0
	s_add_i32 s23, s45, s30
	s_mov_b32 m0, s23
	s_nop 0
	global_load_lds_dwordx4 v178, s[98:99]
	s_add_i32 m0, s23, 0x2000
	s_nop 0
	global_load_lds_dwordx4 v182, s[98:99]
	s_mov_b32 m0, s37
	ds_read_b128 v[144:147], v215 offset:49152
	ds_read_b128 v[148:151], v215 offset:50176
	ds_read_b128 v[152:155], v215 offset:51200
	ds_read_b128 v[156:159], v215 offset:52224
	ds_read_b128 v[160:163], v215 offset:53248
	ds_read_b128 v[164:167], v215 offset:54272
	ds_read_b128 v[168:171], v215 offset:55296
	ds_read_b128 v[172:175], v215 offset:56320
	global_load_lds_dwordx4 v176, s[100:101]
	s_mov_b32 m0, s38
	s_nop 0
	global_load_lds_dwordx4 v180, s[100:101]
	s_add_u32 s20, s20, 0x160080
	s_addc_u32 s21, s21, 0
	s_add_i32 s22, s22, s30
	s_add_i32 s44, s44, 2
	s_add_u32 s18, s18, 0x100
	s_addc_u32 s19, s19, 0
	s_add_u32 s42, s42, 0x100
	s_addc_u32 s43, s43, 0
	s_cmpk_gt_u32 s44, 0x55
	s_waitcnt vmcnt(6)
	s_waitcnt lgkmcnt(0)
	s_setprio 1
	s_barrier
	v_mfma_f32_16x16x32_bf16 v[60:63], v[128:131], v[144:147], v[60:63]
	s_mov_b32 m0, s22
	v_mfma_f32_16x16x32_bf16 v[56:59], v[136:139], v[144:147], v[56:59]
	global_load_lds_dwordx4 v178, s[20:21]
	v_mfma_f32_16x16x32_bf16 v[44:47], v[128:131], v[152:155], v[44:47]
	s_bitset1_b32 m0, 13
	v_mfma_f32_16x16x32_bf16 v[40:43], v[136:139], v[152:155], v[40:43]
	global_load_lds_dwordx4 v182, s[20:21]
	v_mfma_f32_16x16x32_bf16 v[28:31], v[128:131], v[160:163], v[28:31]
	v_mfma_f32_16x16x32_bf16 v[24:27], v[136:139], v[160:163], v[24:27]
	v_mfma_f32_16x16x32_bf16 v[12:15], v[128:131], v[168:171], v[12:15]
	v_mfma_f32_16x16x32_bf16 v[8:11], v[136:139], v[168:171], v[8:11]
	v_mfma_f32_16x16x32_bf16 v[60:63], v[132:135], v[148:151], v[60:63]
	v_mfma_f32_16x16x32_bf16 v[56:59], v[140:143], v[148:151], v[56:59]
	v_mfma_f32_16x16x32_bf16 v[44:47], v[132:135], v[156:159], v[44:47]
	v_mfma_f32_16x16x32_bf16 v[40:43], v[140:143], v[156:159], v[40:43]
	v_mfma_f32_16x16x32_bf16 v[28:31], v[132:135], v[164:167], v[28:31]
	v_mfma_f32_16x16x32_bf16 v[24:27], v[140:143], v[164:167], v[24:27]
	v_mfma_f32_16x16x32_bf16 v[12:15], v[132:135], v[172:175], v[12:15]
	v_mfma_f32_16x16x32_bf16 v[8:11], v[140:143], v[172:175], v[8:11]
	v_mfma_f32_16x16x32_bf16 v[52:55], v[192:195], v[144:147], v[52:55]
	v_mfma_f32_16x16x32_bf16 v[48:51], v[200:203], v[144:147], v[48:51]
	v_mfma_f32_16x16x32_bf16 v[36:39], v[192:195], v[152:155], v[36:39]
	v_mfma_f32_16x16x32_bf16 v[32:35], v[200:203], v[152:155], v[32:35]
	v_mfma_f32_16x16x32_bf16 v[20:23], v[192:195], v[160:163], v[20:23]
	v_mfma_f32_16x16x32_bf16 v[16:19], v[200:203], v[160:163], v[16:19]
	v_mfma_f32_16x16x32_bf16 v[4:7], v[192:195], v[168:171], v[4:7]
	v_mfma_f32_16x16x32_bf16 v[0:3], v[200:203], v[168:171], v[0:3]
	v_mfma_f32_16x16x32_bf16 v[52:55], v[196:199], v[148:151], v[52:55]
	v_mfma_f32_16x16x32_bf16 v[48:51], v[204:207], v[148:151], v[48:51]
	v_mfma_f32_16x16x32_bf16 v[36:39], v[196:199], v[156:159], v[36:39]
	v_mfma_f32_16x16x32_bf16 v[32:35], v[204:207], v[156:159], v[32:35]
	v_mfma_f32_16x16x32_bf16 v[20:23], v[196:199], v[164:167], v[20:23]
	v_mfma_f32_16x16x32_bf16 v[16:19], v[204:207], v[164:167], v[16:19]
	v_mfma_f32_16x16x32_bf16 v[4:7], v[196:199], v[172:175], v[4:7]
	v_mfma_f32_16x16x32_bf16 v[0:3], v[204:207], v[172:175], v[0:3]
	s_barrier
; DI unsigned pack2(float lo, float hi) { f32x2 v = {lo, hi}; bf16v2 r = __builtin_convertvector(v, bf16v2); return __builtin_bit_cast(unsigned, r); }
;   DI void operator()(const f32x4 (&acc)[2][2][4][2], const Unit& u, int wr, int wc, int fr, int fq) const {
;     const int row0 = u.pm * BM + wr * 64 + fr, col0 = u.pn * BM + wc * 32 + 8 * fq;
; #pragma unroll
;     for (int ai = 0; ai < 2; ++ai) {
;       f32x4 bv[4][2][2];
; #pragma unroll
;       for (int m = 0; m < 4; ++m)
; #pragma unroll
;         for (int bj = 0; bj < 2; ++bj) {
;           const float* bp = base + (size_t)(row0 + ai * HALF + m * 16) * 2048 + col0 + bj * HALF;
;           bv[m][bj][0] = *(const f32x4*)bp; bv[m][bj][1] = *(const f32x4*)(bp + 4);
;         }
; #pragma unroll
;       for (int m = 0; m < 4; ++m) {
;         const int row = row0 + ai * HALF + m * 16;
;         const size_t off = (size_t)row * 2048 + col0;
;         float ss = 0.f;
; #pragma unroll
;         for (int bj = 0; bj < 2; ++bj) {
;           const f32x4 v0 = acc[ai][bj][m][0] + bv[m][bj][0], v1 = acc[ai][bj][m][1] + bv[m][bj][1];
;           *(f32x4*)(C + off + bj * HALF) = v0; *(f32x4*)(C + off + bj * HALF + 4) = v1;
;           if (xb) {
;             u32x4 w; w.x = pack2(v0[0], v0[1]); w.y = pack2(v0[2], v0[3]); w.z = pack2(v1[0], v1[1]); w.w = pack2(v1[2], v1[3]);
;             *(u32x4*)(xb + off + bj * HALF) = w;
;             ss += v0[0] * v0[0] + v0[1] * v0[1] + v0[2] * v0[2] + v0[3] * v0[3] + v1[0] * v1[0] + v1[1] * v1[1] + v1[2] * v1[2] + v1[3] * v1[3];
;           }
;         }
;         if (xb) {
;           ss += __shfl_xor(ss, 16); ss += __shfl_xor(ss, 32);
;           if (fq == 0) ssq[(size_t)row * 32 + u.pn * 4 + wc] = ss;
;         }
	s_setprio 0
	s_cbranch_scc0 .LBB0_961
	v_lshl_add_u32 v194, s51, 8, v211
	v_lshl_or_b32 v192, s2, 8, v213
	v_readlane_b32 s52, v243, 3
	v_ashrrev_i32_e32 v193, 31, v192
	v_readlane_b32 s66, v243, 17
	v_readlane_b32 s67, v243, 18
	v_ashrrev_i32_e32 v195, 31, v194
	v_lshlrev_b64 v[128:129], 13, v[194:195]
	v_lshl_add_u64 v[196:197], v[192:193], 2, s[66:67]
	v_lshl_add_u64 v[236:237], v[196:197], 0, v[128:129]
	global_load_dwordx4 v[220:223], v[236:237], off
	global_load_dwordx4 v[224:227], v[236:237], off offset:16
	global_load_dwordx4 v[228:231], v[236:237], off offset:512
	global_load_dwordx4 v[232:235], v[236:237], off offset:528
	v_or_b32_e32 v206, 16, v194
	v_or_b32_e32 v202, 32, v194
	v_or_b32_e32 v198, 48, v194
	v_ashrrev_i32_e32 v207, 31, v206
	v_ashrrev_i32_e32 v203, 31, v202
	v_ashrrev_i32_e32 v199, 31, v198
	v_lshlrev_b64 v[128:129], 13, v[206:207]
	v_lshlrev_b64 v[130:131], 13, v[202:203]
	v_lshlrev_b64 v[132:133], 13, v[198:199]
	v_lshl_add_u64 v[208:209], v[196:197], 0, v[128:129]
	v_lshl_add_u64 v[204:205], v[196:197], 0, v[130:131]
	v_lshl_add_u64 v[200:201], v[196:197], 0, v[132:133]
	global_load_dwordx4 v[168:171], v[208:209], off offset:16
	global_load_dwordx4 v[172:175], v[208:209], off
	global_load_dwordx4 v[160:163], v[208:209], off offset:528
	global_load_dwordx4 v[164:167], v[208:209], off offset:512
	global_load_dwordx4 v[152:155], v[204:205], off offset:16
	global_load_dwordx4 v[156:159], v[204:205], off
	global_load_dwordx4 v[144:147], v[204:205], off offset:528
	global_load_dwordx4 v[148:151], v[204:205], off offset:512
	global_load_dwordx4 v[136:139], v[200:201], off offset:16
	global_load_dwordx4 v[140:143], v[200:201], off
	global_load_dwordx4 v[128:131], v[200:201], off offset:528
	global_load_dwordx4 v[132:135], v[200:201], off offset:512
	v_and_b32_e32 v218, 64, v217
	v_xor_b32_e32 v238, 16, v217
	v_add_u32_e32 v240, 64, v218
	v_xor_b32_e32 v239, 32, v217
	v_cmp_lt_i32_e32 vcc, v238, v240
	v_lshlrev_b64 v[218:219], 11, v[194:195]
	s_lshl_b32 s18, s2, 2
	v_cndmask_b32_e32 v241, v217, v238, vcc
	v_cmp_lt_i32_e32 vcc, v239, v240
	s_ashr_i32 s19, s18, 31
	v_readlane_b32 s53, v243, 4
	v_cndmask_b32_e32 v240, v217, v239, vcc
	v_lshl_add_u64 v[238:239], v[218:219], 0, v[192:193]
	v_lshlrev_b32_e32 v218, 2, v241
	v_lshl_add_u64 v[238:239], v[238:239], 1, s[12:13]
	v_readlane_b32 s54, v243, 5
	v_readlane_b32 s55, v243, 6
	v_readlane_b32 s56, v243, 7
	v_readlane_b32 s57, v243, 8
	v_readlane_b32 s58, v243, 9
	v_readlane_b32 s59, v243, 10
	v_readlane_b32 s60, v243, 11
	v_readlane_b32 s61, v243, 12
	v_readlane_b32 s62, v243, 13
	v_readlane_b32 s63, v243, 14
	v_readlane_b32 s64, v243, 15
	v_readlane_b32 s65, v243, 16
	s_waitcnt vmcnt(0)
	v_pk_add_f32 v[126:127], v[126:127], v[222:223]
	v_pk_add_f32 v[124:125], v[124:125], v[220:221]
	v_pk_add_f32 v[116:117], v[116:117], v[228:229]
	v_pk_add_f32 v[122:123], v[122:123], v[226:227]
	v_pk_add_f32 v[120:121], v[120:121], v[224:225]
	v_pk_add_f32 v[220:221], v[112:113], v[232:233]
	global_store_dwordx4 v[236:237], v[124:127], off
	global_store_dwordx4 v[236:237], v[120:123], off offset:16
	v_cvt_pk_bf16_f32 v112, v124, v125
	v_mul_f32_e32 v125, v125, v125
	v_mul_f32_e32 v219, v117, v117
	v_pk_add_f32 v[118:119], v[118:119], v[230:231]
	v_fmac_f32_e32 v125, v124, v124
	v_fmac_f32_e32 v219, v116, v116
	v_fmac_f32_e32 v125, v126, v126
	v_fmac_f32_e32 v219, v118, v118
	v_fmac_f32_e32 v125, v127, v127
	v_fmac_f32_e32 v219, v119, v119
	v_fmac_f32_e32 v125, v120, v120
	v_fmac_f32_e32 v219, v220, v220
	v_pk_add_f32 v[222:223], v[114:115], v[234:235]
	v_fmac_f32_e32 v125, v121, v121
	v_fmac_f32_e32 v219, v221, v221
	v_fmac_f32_e32 v125, v122, v122
	v_fmac_f32_e32 v219, v222, v222
	v_fmac_f32_e32 v125, v123, v123
	v_fmac_f32_e32 v219, v223, v223
	v_cvt_pk_bf16_f32 v114, v120, v121
	v_add_f32_e32 v121, v125, v219
	v_cvt_pk_bf16_f32 v115, v122, v123
	ds_bpermute_b32 v122, v218, v121
	v_cvt_pk_bf16_f32 v113, v126, v127
	global_store_dwordx4 v[238:239], v[112:115], off
	global_store_dwordx4 v[236:237], v[116:119], off offset:512
	global_store_dwordx4 v[236:237], v[220:223], off offset:528
	v_lshlrev_b32_e32 v126, 2, v240
	v_cvt_pk_bf16_f32 v120, v116, v117
	s_waitcnt lgkmcnt(0)
	v_add_f32_e32 v112, v121, v122
	ds_bpermute_b32 v113, v126, v112
	v_cvt_pk_bf16_f32 v121, v118, v119
	v_cvt_pk_bf16_f32 v122, v220, v221
	v_cvt_pk_bf16_f32 v123, v222, v223
	global_store_dwordx4 v[238:239], v[120:123], off offset:256
	s_and_saveexec_b64 s[20:21], s[0:1]
	s_cbranch_execz .LBB0_964
	s_waitcnt lgkmcnt(0)
	v_add_f32_e32 v114, v112, v113
	v_lshlrev_b64 v[112:113], 7, v[194:195]
	v_lshl_add_u64 v[112:113], s[14:15], 0, v[112:113]
	v_lshl_add_u64 v[112:113], s[18:19], 2, v[112:113]
	s_lshl_b32 s2, s36, 2
	v_lshl_add_u64 v[112:113], v[112:113], 0, s[2:3]
	global_store_dword v[112:113], v114, off

; #define PG8_STAGE(bufoff, gbase, voff) do { _Pragma("unroll") for (int _i = 0; _i < 2; ++_i) \
;     __builtin_amdgcn_global_load_lds((const unsigned*)((const char*)(gbase) + (voff)[_i]), (LAS unsigned*)(lds + (bufoff) + ldsw + _i * 8192), 16, 0, 0); } while (0)
; #define PG8_LDA(dst, b, h) do { _Pragma("unroll") for (int m = 0; m < 4; ++m) _Pragma("unroll") for (int k = 0; k < 2; ++k) dst[m][k] = *(const LAS bf16x8*)(lds + PG8_SA(b, h) + aoff + m * 2048 + k * 1024); } while (0)
; #define PG8_LDB(dst, b, h) do { _Pragma("unroll") for (int n = 0; n < 2; ++n) _Pragma("unroll") for (int k = 0; k < 2; ++k) dst[n][k] = *(const LAS bf16x8*)(lds + PG8_SB(b, h) + boff + n * 2048 + k * 1024); } while (0)
; #define PG8_MMA(ai, bj, At, Bt) do { __builtin_amdgcn_s_setprio(1); _Pragma("unroll") for (int m = 0; m < 4; ++m) _Pragma("unroll") for (int n = 0; n < 2; ++n) _Pragma("unroll") for (int k = 0; k < 2; ++k) \
;     acc[ai][bj][m][n] = __builtin_amdgcn_mfma_f32_16x16x32_bf16(Bt[n][k], At[m][k], acc[ai][bj][m][n], 0, 0, 0); __builtin_amdgcn_s_setprio(0); } while (0)
; #define PG8_WAIT_V(n) asm volatile("s_waitcnt vmcnt(" #n ")" ::: "memory")
; #define PG8_WAIT_L(n) asm volatile("s_waitcnt lgkmcnt(" #n ")" ::: "memory")
; #define PG8_BAR __builtin_amdgcn_s_barrier()
; #define PG8_SCHED __builtin_amdgcn_sched_barrier(0)
; template <class Epi, class Sched = StaticOrder>
; DI void gemm_phase(LAS unsigned char* lds, const Gemm g, const Sched& S, const Epi& E) {
;     ...
;       const char* a1 = cA + (size_t)(t + 1) * kstep;
;       const char* a2 = last ? nA : cA + (size_t)(t + 2) * kstep; const char* b2 = last ? nB : cB + (size_t)(t + 2) * kstep;
;       const char* a3 = a2 + kstep; const char* b3 = b2 + kstep;
;       PG8_LDB(B0, 0, 0); PG8_SCHED; PG8_LDA(At, 0, 0); PG8_STAGE(PG8_SA(1, 1), a1 + hstep, voffA);
;       PG8_WAIT_L(8); PG8_BAR; PG8_WAIT_L(0); PG8_MMA(0, 0, At, B0); PG8_BAR; PG8_SCHED;
;       PG8_LDB(B1, 0, 1); PG8_STAGE(PG8_SB(0, 0), b2, voffB);
;       PG8_BAR; PG8_WAIT_L(0); PG8_MMA(0, 1, At, B1); PG8_BAR;
;       PG8_LDA(At, 0, 1); PG8_STAGE(PG8_SA(0, 0), a2, voffA);
;       PG8_BAR; PG8_WAIT_L(0); PG8_MMA(1, 0, At, B0); PG8_BAR; PG8_SCHED;
;       PG8_STAGE(PG8_SB(0, 1), b2 + hstep, voffB);
;       PG8_WAIT_V(6); PG8_BAR; PG8_MMA(1, 1, At, B1); PG8_BAR;
.LBB0_1052:
	ds_read_b128 v[128:131], v203
	ds_read_b128 v[132:135], v203 offset:1024
	ds_read_b128 v[136:139], v203 offset:2048
	ds_read_b128 v[140:143], v203 offset:3072
	s_add_u32 s12, s10, 0xfff80080
	s_addc_u32 s13, s11, -1
	s_cmp_eq_u32 s52, 28
	s_cselect_b32 s65, s41, s13
	s_cselect_b32 s64, s42, s12
	s_cselect_b32 s13, s43, s49
	s_cselect_b32 s12, s44, s45
	s_add_i32 m0, s61, 0xc000
	ds_read_b128 v[144:147], v204
	ds_read_b128 v[148:151], v204 offset:1024
	ds_read_b128 v[152:155], v204 offset:2048
	ds_read_b128 v[156:159], v204 offset:3072
	ds_read_b128 v[178:181], v204 offset:4096
	ds_read_b128 v[182:185], v204 offset:5120
	ds_read_b128 v[186:189], v204 offset:6144
	ds_read_b128 v[190:193], v204 offset:7168
	global_load_lds_dwordx4 v172, s[10:11]
	s_add_i32 m0, s61, 0xe000
	s_nop 0
	global_load_lds_dwordx4 v174, s[10:11]
	ds_read_b128 v[194:197], v205
	ds_read_b128 v[212:215], v205 offset:1024
	ds_read_b128 v[216:219], v205 offset:2048
	ds_read_b128 v[220:223], v205 offset:3072
	s_waitcnt vmcnt(8)
	s_waitcnt lgkmcnt(4)
	s_setprio 1
	s_barrier
	v_mfma_f32_16x16x32_bf16 v[124:127], v[128:131], v[144:147], v[124:127]
	v_mfma_f32_16x16x32_bf16 v[120:123], v[136:139], v[144:147], v[120:123]
	v_mfma_f32_16x16x32_bf16 v[116:119], v[128:131], v[152:155], v[116:119]
	v_mfma_f32_16x16x32_bf16 v[104:107], v[136:139], v[152:155], v[104:107]
	v_mfma_f32_16x16x32_bf16 v[92:95], v[128:131], v[178:181], v[92:95]
	v_mfma_f32_16x16x32_bf16 v[88:91], v[136:139], v[178:181], v[88:91]
	v_mfma_f32_16x16x32_bf16 v[84:87], v[128:131], v[186:189], v[84:87]
	v_mfma_f32_16x16x32_bf16 v[72:75], v[136:139], v[186:189], v[72:75]
	v_mfma_f32_16x16x32_bf16 v[124:127], v[132:135], v[148:151], v[124:127]
	v_mfma_f32_16x16x32_bf16 v[120:123], v[140:143], v[148:151], v[120:123]
	v_mfma_f32_16x16x32_bf16 v[116:119], v[132:135], v[156:159], v[116:119]
	v_mfma_f32_16x16x32_bf16 v[104:107], v[140:143], v[156:159], v[104:107]
	v_mfma_f32_16x16x32_bf16 v[92:95], v[132:135], v[182:185], v[92:95]
	v_mfma_f32_16x16x32_bf16 v[88:91], v[140:143], v[182:185], v[88:91]
	v_mfma_f32_16x16x32_bf16 v[84:87], v[132:135], v[190:193], v[84:87]
	v_mfma_f32_16x16x32_bf16 v[72:75], v[140:143], v[190:193], v[72:75]
	s_waitcnt lgkmcnt(0)
	v_mfma_f32_16x16x32_bf16 v[112:115], v[194:197], v[144:147], v[112:115]
	v_mfma_f32_16x16x32_bf16 v[108:111], v[216:219], v[144:147], v[108:111]
	v_mfma_f32_16x16x32_bf16 v[100:103], v[194:197], v[152:155], v[100:103]
	v_mfma_f32_16x16x32_bf16 v[96:99], v[216:219], v[152:155], v[96:99]
	v_mfma_f32_16x16x32_bf16 v[80:83], v[194:197], v[178:181], v[80:83]
	v_mfma_f32_16x16x32_bf16 v[76:79], v[216:219], v[178:181], v[76:79]
	v_mfma_f32_16x16x32_bf16 v[68:71], v[194:197], v[186:189], v[68:71]
	v_mfma_f32_16x16x32_bf16 v[64:67], v[216:219], v[186:189], v[64:67]
	v_mfma_f32_16x16x32_bf16 v[112:115], v[212:215], v[148:151], v[112:115]
	v_mfma_f32_16x16x32_bf16 v[108:111], v[220:223], v[148:151], v[108:111]
	v_mfma_f32_16x16x32_bf16 v[100:103], v[212:215], v[156:159], v[100:103]
	v_mfma_f32_16x16x32_bf16 v[96:99], v[220:223], v[156:159], v[96:99]
	v_mfma_f32_16x16x32_bf16 v[80:83], v[212:215], v[182:185], v[80:83]
	v_mfma_f32_16x16x32_bf16 v[76:79], v[220:223], v[182:185], v[76:79]
	v_mfma_f32_16x16x32_bf16 v[68:71], v[212:215], v[190:193], v[68:71]
	v_mfma_f32_16x16x32_bf16 v[64:67], v[220:223], v[190:193], v[64:67]
	s_barrier
	s_setprio 0
	s_add_i32 s53, s80, s70
	s_add_u32 s98, s12, 0x80
	s_addc_u32 s99, s13, 0
	s_add_u32 s100, s64, 0x80
	s_addc_u32 s101, s65, 0
	s_mov_b32 m0, s53
	s_nop 0
	global_load_lds_dwordx4 v162, s[12:13]
	s_add_i32 m0, s53, 0x2000
	s_nop 0
	global_load_lds_dwordx4 v166, s[12:13]
	s_mov_b32 m0, s61
	ds_read_b128 v[144:147], v204 offset:16384
	ds_read_b128 v[148:151], v204 offset:17408
	ds_read_b128 v[152:155], v204 offset:18432
	ds_read_b128 v[156:159], v204 offset:19456
	ds_read_b128 v[178:181], v204 offset:20480
	ds_read_b128 v[182:185], v204 offset:21504
	ds_read_b128 v[186:189], v204 offset:22528
	ds_read_b128 v[190:193], v204 offset:23552
	global_load_lds_dwordx4 v160, s[64:65]
	s_mov_b32 m0, s63
	s_nop 0
	global_load_lds_dwordx4 v164, s[64:65]
	s_add_u32 s54, s12, 0x80000
	s_addc_u32 s55, s13, 0
	s_add_i32 s53, s81, s70
	s_waitcnt vmcnt(6)
	s_waitcnt lgkmcnt(0)
	s_setprio 1
	s_barrier
	v_mfma_f32_16x16x32_bf16 v[60:63], v[128:131], v[144:147], v[60:63]
	s_mov_b32 m0, s53
	v_mfma_f32_16x16x32_bf16 v[56:59], v[136:139], v[144:147], v[56:59]
	global_load_lds_dwordx4 v162, s[54:55]
	v_mfma_f32_16x16x32_bf16 v[48:51], v[128:131], v[152:155], v[48:51]
	s_bitset1_b32 m0, 13
	v_mfma_f32_16x16x32_bf16 v[40:43], v[136:139], v[152:155], v[40:43]
	global_load_lds_dwordx4 v166, s[54:55]
	v_mfma_f32_16x16x32_bf16 v[28:31], v[128:131], v[178:181], v[28:31]
	v_mfma_f32_16x16x32_bf16 v[24:27], v[136:139], v[178:181], v[24:27]
	v_mfma_f32_16x16x32_bf16 v[12:15], v[128:131], v[186:189], v[12:15]
	v_mfma_f32_16x16x32_bf16 v[8:11], v[136:139], v[186:189], v[8:11]
	v_mfma_f32_16x16x32_bf16 v[60:63], v[132:135], v[148:151], v[60:63]
	v_mfma_f32_16x16x32_bf16 v[56:59], v[140:143], v[148:151], v[56:59]
	v_mfma_f32_16x16x32_bf16 v[48:51], v[132:135], v[156:159], v[48:51]
	v_mfma_f32_16x16x32_bf16 v[40:43], v[140:143], v[156:159], v[40:43]
	v_mfma_f32_16x16x32_bf16 v[28:31], v[132:135], v[182:185], v[28:31]
	v_mfma_f32_16x16x32_bf16 v[24:27], v[140:143], v[182:185], v[24:27]
	v_mfma_f32_16x16x32_bf16 v[12:15], v[132:135], v[190:193], v[12:15]
	v_mfma_f32_16x16x32_bf16 v[8:11], v[140:143], v[190:193], v[8:11]
	v_mfma_f32_16x16x32_bf16 v[52:55], v[194:197], v[144:147], v[52:55]
	v_mfma_f32_16x16x32_bf16 v[44:47], v[216:219], v[144:147], v[44:47]
	v_mfma_f32_16x16x32_bf16 v[36:39], v[194:197], v[152:155], v[36:39]
	v_mfma_f32_16x16x32_bf16 v[32:35], v[216:219], v[152:155], v[32:35]
	v_mfma_f32_16x16x32_bf16 v[20:23], v[194:197], v[178:181], v[20:23]
	v_mfma_f32_16x16x32_bf16 v[16:19], v[216:219], v[178:181], v[16:19]
	v_mfma_f32_16x16x32_bf16 v[4:7], v[194:197], v[186:189], v[4:7]
	v_mfma_f32_16x16x32_bf16 v[0:3], v[216:219], v[186:189], v[0:3]
	v_mfma_f32_16x16x32_bf16 v[52:55], v[212:215], v[148:151], v[52:55]
	v_mfma_f32_16x16x32_bf16 v[44:47], v[220:223], v[148:151], v[44:47]
	v_mfma_f32_16x16x32_bf16 v[36:39], v[212:215], v[156:159], v[36:39]
	v_mfma_f32_16x16x32_bf16 v[32:35], v[220:223], v[156:159], v[32:35]
	v_mfma_f32_16x16x32_bf16 v[20:23], v[212:215], v[182:185], v[20:23]
	v_mfma_f32_16x16x32_bf16 v[16:19], v[220:223], v[182:185], v[16:19]
	v_mfma_f32_16x16x32_bf16 v[4:7], v[212:215], v[190:193], v[4:7]
	v_mfma_f32_16x16x32_bf16 v[0:3], v[220:223], v[190:193], v[0:3]
	s_barrier
; #define PG8_STAGE(bufoff, gbase, voff) do { _Pragma("unroll") for (int _i = 0; _i < 2; ++_i) \
;     __builtin_amdgcn_global_load_lds((const unsigned*)((const char*)(gbase) + (voff)[_i]), (LAS unsigned*)(lds + (bufoff) + ldsw + _i * 8192), 16, 0, 0); } while (0)
; #define PG8_LDA(dst, b, h) do { _Pragma("unroll") for (int m = 0; m < 4; ++m) _Pragma("unroll") for (int k = 0; k < 2; ++k) dst[m][k] = *(const LAS bf16x8*)(lds + PG8_SA(b, h) + aoff + m * 2048 + k * 1024); } while (0)
; #define PG8_LDB(dst, b, h) do { _Pragma("unroll") for (int n = 0; n < 2; ++n) _Pragma("unroll") for (int k = 0; k < 2; ++k) dst[n][k] = *(const LAS bf16x8*)(lds + PG8_SB(b, h) + boff + n * 2048 + k * 1024); } while (0)
; #define PG8_MMA(ai, bj, At, Bt) do { __builtin_amdgcn_s_setprio(1); _Pragma("unroll") for (int m = 0; m < 4; ++m) _Pragma("unroll") for (int n = 0; n < 2; ++n) _Pragma("unroll") for (int k = 0; k < 2; ++k) \
;     acc[ai][bj][m][n] = __builtin_amdgcn_mfma_f32_16x16x32_bf16(Bt[n][k], At[m][k], acc[ai][bj][m][n], 0, 0, 0); __builtin_amdgcn_s_setprio(0); } while (0)
; #define PG8_WAIT_V(n) asm volatile("s_waitcnt vmcnt(" #n ")" ::: "memory")
; #define PG8_WAIT_L(n) asm volatile("s_waitcnt lgkmcnt(" #n ")" ::: "memory")
; #define PG8_BAR __builtin_amdgcn_s_barrier()
; #define PG8_SCHED __builtin_amdgcn_sched_barrier(0)
; template <class Epi, class Sched = StaticOrder>
; DI void gemm_phase(LAS unsigned char* lds, const Gemm g, const Sched& S, const Epi& E) {
;     ...
;       PG8_LDB(B0, 1, 0); PG8_SCHED; PG8_LDA(At, 1, 0); PG8_STAGE(PG8_SA(0, 1), a2 + hstep, voffA);
;       PG8_WAIT_L(8); PG8_BAR; PG8_WAIT_L(0); PG8_MMA(0, 0, At, B0); PG8_BAR; PG8_SCHED;
;       PG8_LDB(B1, 1, 1); PG8_STAGE(PG8_SB(1, 0), b3, voffB);
;       PG8_BAR; PG8_WAIT_L(0); PG8_MMA(0, 1, At, B1); PG8_BAR;
;       PG8_LDA(At, 1, 1); PG8_STAGE(PG8_SA(1, 0), a3, voffA);
;       PG8_BAR; PG8_WAIT_L(0); PG8_MMA(1, 0, At, B0); PG8_BAR; PG8_SCHED;
;       PG8_STAGE(PG8_SB(1, 1), b3 + hstep, voffB);
;       PG8_WAIT_V(6); PG8_BAR; PG8_MMA(1, 1, At, B1); PG8_BAR;
	s_setprio 0
	s_add_i32 s53, 0, 0x18000
	v_add_u32_e32 v140, s53, v199
	ds_read_b128 v[128:131], v140
	ds_read_b128 v[132:135], v140 offset:1024
	ds_read_b128 v[136:139], v140 offset:2048
	ds_read_b128 v[140:143], v140 offset:3072
	s_add_u32 s54, s64, 0x80000
	s_addc_u32 s55, s65, 0
	s_mov_b32 m0, s71
	ds_read_b128 v[144:147], v204 offset:32768
	ds_read_b128 v[148:151], v204 offset:33792
	ds_read_b128 v[152:155], v204 offset:34816
	ds_read_b128 v[156:159], v204 offset:35840
	ds_read_b128 v[178:181], v204 offset:36864
	ds_read_b128 v[182:185], v204 offset:37888
	ds_read_b128 v[186:189], v204 offset:38912
	ds_read_b128 v[190:193], v204 offset:39936
	global_load_lds_dwordx4 v160, s[54:55]
	s_mov_b32 m0, s72
	s_nop 0
	global_load_lds_dwordx4 v164, s[54:55]
	s_add_i32 s54, 0, 0x1c000
	v_add_u32_e32 v168, s54, v199
	ds_read_b128 v[194:197], v168
	ds_read_b128 v[212:215], v168 offset:1024
	ds_read_b128 v[216:219], v168 offset:2048
	ds_read_b128 v[220:223], v168 offset:3072
	s_waitcnt vmcnt(8)
	s_waitcnt lgkmcnt(4)
	s_setprio 1
	s_barrier
	v_mfma_f32_16x16x32_bf16 v[124:127], v[128:131], v[144:147], v[124:127]
	v_mfma_f32_16x16x32_bf16 v[120:123], v[136:139], v[144:147], v[120:123]
	v_mfma_f32_16x16x32_bf16 v[116:119], v[128:131], v[152:155], v[116:119]
	v_mfma_f32_16x16x32_bf16 v[104:107], v[136:139], v[152:155], v[104:107]
	v_mfma_f32_16x16x32_bf16 v[92:95], v[128:131], v[178:181], v[92:95]
	v_mfma_f32_16x16x32_bf16 v[88:91], v[136:139], v[178:181], v[88:91]
	v_mfma_f32_16x16x32_bf16 v[84:87], v[128:131], v[186:189], v[84:87]
	v_mfma_f32_16x16x32_bf16 v[72:75], v[136:139], v[186:189], v[72:75]
	v_mfma_f32_16x16x32_bf16 v[124:127], v[132:135], v[148:151], v[124:127]
	v_mfma_f32_16x16x32_bf16 v[120:123], v[140:143], v[148:151], v[120:123]
	v_mfma_f32_16x16x32_bf16 v[116:119], v[132:135], v[156:159], v[116:119]
	v_mfma_f32_16x16x32_bf16 v[104:107], v[140:143], v[156:159], v[104:107]
	v_mfma_f32_16x16x32_bf16 v[92:95], v[132:135], v[182:185], v[92:95]
	v_mfma_f32_16x16x32_bf16 v[88:91], v[140:143], v[182:185], v[88:91]
	v_mfma_f32_16x16x32_bf16 v[84:87], v[132:135], v[190:193], v[84:87]
	v_mfma_f32_16x16x32_bf16 v[72:75], v[140:143], v[190:193], v[72:75]
	s_waitcnt lgkmcnt(0)
	v_mfma_f32_16x16x32_bf16 v[112:115], v[194:197], v[144:147], v[112:115]
	v_mfma_f32_16x16x32_bf16 v[108:111], v[216:219], v[144:147], v[108:111]
	v_mfma_f32_16x16x32_bf16 v[100:103], v[194:197], v[152:155], v[100:103]
	v_mfma_f32_16x16x32_bf16 v[96:99], v[216:219], v[152:155], v[96:99]
	v_mfma_f32_16x16x32_bf16 v[80:83], v[194:197], v[178:181], v[80:83]
	v_mfma_f32_16x16x32_bf16 v[76:79], v[216:219], v[178:181], v[76:79]
	v_mfma_f32_16x16x32_bf16 v[68:71], v[194:197], v[186:189], v[68:71]
	v_mfma_f32_16x16x32_bf16 v[64:67], v[216:219], v[186:189], v[64:67]
	v_mfma_f32_16x16x32_bf16 v[112:115], v[212:215], v[148:151], v[112:115]
	v_mfma_f32_16x16x32_bf16 v[108:111], v[220:223], v[148:151], v[108:111]
	v_mfma_f32_16x16x32_bf16 v[100:103], v[212:215], v[156:159], v[100:103]
	v_mfma_f32_16x16x32_bf16 v[96:99], v[220:223], v[156:159], v[96:99]
	v_mfma_f32_16x16x32_bf16 v[80:83], v[212:215], v[182:185], v[80:83]
	v_mfma_f32_16x16x32_bf16 v[76:79], v[220:223], v[182:185], v[76:79]
	v_mfma_f32_16x16x32_bf16 v[68:71], v[212:215], v[190:193], v[68:71]
	v_mfma_f32_16x16x32_bf16 v[64:67], v[220:223], v[190:193], v[64:67]
	s_barrier
	s_setprio 0
	s_add_i32 s53, s53, s70
	s_mov_b32 m0, s53
	s_nop 0
	global_load_lds_dwordx4 v162, s[98:99]
	s_add_i32 m0, s53, 0x2000
	s_nop 0
	global_load_lds_dwordx4 v166, s[98:99]
	s_mov_b32 m0, s76
	ds_read_b128 v[144:147], v204 offset:49152
	ds_read_b128 v[148:151], v204 offset:50176
	ds_read_b128 v[152:155], v204 offset:51200
	ds_read_b128 v[156:159], v204 offset:52224
	ds_read_b128 v[178:181], v204 offset:53248
	ds_read_b128 v[182:185], v204 offset:54272
	ds_read_b128 v[186:189], v204 offset:55296
	ds_read_b128 v[190:193], v204 offset:56320
	global_load_lds_dwordx4 v160, s[100:101]
	s_mov_b32 m0, s77
	s_nop 0
	global_load_lds_dwordx4 v164, s[100:101]
	s_add_u32 s12, s12, 0x80080
	s_addc_u32 s13, s13, 0
	s_add_i32 s53, s54, s70
	s_add_i32 s52, s52, 2
	s_add_u32 s10, s10, 0x100
	s_addc_u32 s11, s11, 0
	s_add_u32 s45, s45, 0x100
	s_addc_u32 s49, s49, 0
	s_cmp_gt_u32 s52, 29
	s_waitcnt vmcnt(6)
	s_waitcnt lgkmcnt(0)
	s_setprio 1
	s_barrier
	v_mfma_f32_16x16x32_bf16 v[60:63], v[128:131], v[144:147], v[60:63]
	s_mov_b32 m0, s53
	v_mfma_f32_16x16x32_bf16 v[56:59], v[136:139], v[144:147], v[56:59]
	global_load_lds_dwordx4 v162, s[12:13]
	v_mfma_f32_16x16x32_bf16 v[48:51], v[128:131], v[152:155], v[48:51]
	s_bitset1_b32 m0, 13
	v_mfma_f32_16x16x32_bf16 v[40:43], v[136:139], v[152:155], v[40:43]
	global_load_lds_dwordx4 v166, s[12:13]
	v_mfma_f32_16x16x32_bf16 v[28:31], v[128:131], v[178:181], v[28:31]
	v_mfma_f32_16x16x32_bf16 v[24:27], v[136:139], v[178:181], v[24:27]
	v_mfma_f32_16x16x32_bf16 v[12:15], v[128:131], v[186:189], v[12:15]
	v_mfma_f32_16x16x32_bf16 v[8:11], v[136:139], v[186:189], v[8:11]
	v_mfma_f32_16x16x32_bf16 v[60:63], v[132:135], v[148:151], v[60:63]
	v_mfma_f32_16x16x32_bf16 v[56:59], v[140:143], v[148:151], v[56:59]
	v_mfma_f32_16x16x32_bf16 v[48:51], v[132:135], v[156:159], v[48:51]
	v_mfma_f32_16x16x32_bf16 v[40:43], v[140:143], v[156:159], v[40:43]
	v_mfma_f32_16x16x32_bf16 v[28:31], v[132:135], v[182:185], v[28:31]
	v_mfma_f32_16x16x32_bf16 v[24:27], v[140:143], v[182:185], v[24:27]
	v_mfma_f32_16x16x32_bf16 v[12:15], v[132:135], v[190:193], v[12:15]
	v_mfma_f32_16x16x32_bf16 v[8:11], v[140:143], v[190:193], v[8:11]
	v_mfma_f32_16x16x32_bf16 v[52:55], v[194:197], v[144:147], v[52:55]
	v_mfma_f32_16x16x32_bf16 v[44:47], v[216:219], v[144:147], v[44:47]
	v_mfma_f32_16x16x32_bf16 v[36:39], v[194:197], v[152:155], v[36:39]
	v_mfma_f32_16x16x32_bf16 v[32:35], v[216:219], v[152:155], v[32:35]
	v_mfma_f32_16x16x32_bf16 v[20:23], v[194:197], v[178:181], v[20:23]
	v_mfma_f32_16x16x32_bf16 v[16:19], v[216:219], v[178:181], v[16:19]
	v_mfma_f32_16x16x32_bf16 v[4:7], v[194:197], v[186:189], v[4:7]
	v_mfma_f32_16x16x32_bf16 v[0:3], v[216:219], v[186:189], v[0:3]
	v_mfma_f32_16x16x32_bf16 v[52:55], v[212:215], v[148:151], v[52:55]
	v_mfma_f32_16x16x32_bf16 v[44:47], v[220:223], v[148:151], v[44:47]
	v_mfma_f32_16x16x32_bf16 v[36:39], v[212:215], v[156:159], v[36:39]
	v_mfma_f32_16x16x32_bf16 v[32:35], v[220:223], v[156:159], v[32:35]
	v_mfma_f32_16x16x32_bf16 v[20:23], v[212:215], v[182:185], v[20:23]
	v_mfma_f32_16x16x32_bf16 v[16:19], v[220:223], v[182:185], v[16:19]
	v_mfma_f32_16x16x32_bf16 v[4:7], v[212:215], v[190:193], v[4:7]
	v_mfma_f32_16x16x32_bf16 v[0:3], v[220:223], v[190:193], v[0:3]
	s_barrier
; DI float row_rstd(const float* ssq, int row, int fq) {
;   const f32x4 a = *(const f32x4*)(ssq + (size_t)row * 32 + fq * 8), b = *(const f32x4*)(ssq + (size_t)row * 32 + fq * 8 + 4);
;   float sm = ((a[0] + a[1]) + (a[2] + a[3])) + ((b[0] + b[1]) + (b[2] + b[3]));
;   sm += __shfl_xor(sm, 16); sm += __shfl_xor(sm, 32);
;   return rsqrtf(sm * (1.0f / 2048.f) + 1e-6f);
; }
;   DI void operator()(const f32x4 (&acc)[2][2][4][2], const Unit& u, int wr, int wc, int fr, int fq) const {
;     ...
;     const int col = u.pn * 128 + wc * 32 + 8 * fq;
;     float w0[8], w1[8], w2[8];
; #pragma unroll
;     for (int e = 0; e < 8; ++e) { w0[e] = cw[col + e]; w1[e] = cw[2048 + col + e]; w2[e] = cw[4096 + col + e]; }
; #pragma unroll
;     for (int ai = 0; ai < 2; ++ai) {
;       const int row0 = u.pm * BM + ai * HALF + wr * 64, span = row0 >> 6;
;       float rsv[4];
; #pragma unroll
;       for (int m = 0; m < 4; ++m) rsv[m] = row_rstd(ssq, row0 + 16 * m + fr, fq);
	s_setprio 0
	s_cbranch_scc0 .LBB0_1052
	s_cmp_lt_i32 s62, 16
	s_mov_b64 s[10:11], -1
	s_cbranch_scc0 .LBB0_1067
	s_lshl_b32 s41, s60, 8
	s_add_i32 s41, s41, s75
	v_or_b32_e32 v186, s41, v177
	v_ashrrev_i32_e32 v187, 31, v186
	v_lshlrev_b64 v[128:129], 7, v[186:187]
	v_or_b32_e32 v180, 16, v186
	v_lshl_add_u64 v[128:129], v[170:171], 0, v[128:129]
	v_ashrrev_i32_e32 v181, 31, v180
	global_load_dwordx4 v[152:155], v[128:129], off
	global_load_dwordx4 v[156:159], v[128:129], off offset:16
	v_lshlrev_b64 v[128:129], 7, v[180:181]
	v_lshl_add_u64 v[128:129], v[170:171], 0, v[128:129]
	global_load_dwordx4 v[188:191], v[128:129], off
	global_load_dwordx4 v[192:195], v[128:129], off offset:16
	v_or_b32_e32 v184, 32, v186
	v_ashrrev_i32_e32 v185, 31, v184
	v_lshlrev_b64 v[128:129], 7, v[184:185]
	v_or_b32_e32 v182, 48, v186
	v_lshl_add_u64 v[128:129], v[170:171], 0, v[128:129]
	v_ashrrev_i32_e32 v183, 31, v182
	global_load_dwordx4 v[212:215], v[128:129], off
	global_load_dwordx4 v[216:219], v[128:129], off offset:16
	v_lshlrev_b64 v[128:129], 7, v[182:183]
	v_lshl_add_u64 v[128:129], v[170:171], 0, v[128:129]
	global_load_dwordx4 v[220:223], v[128:129], off
	global_load_dwordx4 v[224:227], v[128:129], off offset:16
	v_and_b32_e32 v129, 64, v206
	v_lshl_or_b32 v178, s62, 7, v200
	v_xor_b32_e32 v128, 16, v206
	v_add_u32_e32 v129, 64, v129
	v_readlane_b32 s44, v243, 3
	v_xor_b32_e32 v130, 32, v206
	v_ashrrev_i32_e32 v179, 31, v178
	v_readlane_b32 s45, v243, 4
	v_cmp_lt_i32_e32 vcc, v128, v129
	s_movk_i32 s10, 0x2000
	v_lshl_add_u64 v[144:145], v[178:179], 2, s[44:45]
	v_cndmask_b32_e32 v134, v206, v128, vcc
	v_cmp_lt_i32_e32 vcc, v130, v129
	v_lshl_add_u64 v[132:133], v[144:145], 0, s[26:27]
	v_lshl_add_u64 v[136:137], v[144:145], 0, s[28:29]
	v_cndmask_b32_e32 v135, v206, v130, vcc
	v_add_co_u32_e32 v146, vcc, s10, v144
	global_load_dwordx4 v[128:131], v[144:145], off offset:16
	global_load_dwordx4 v[140:143], v[144:145], off
	v_addc_co_u32_e32 v147, vcc, 0, v145, vcc
	v_add_co_u32_e32 v148, vcc, s74, v144
	v_lshlrev_b32_e32 v196, 2, v134
	s_nop 0
	v_addc_co_u32_e32 v149, vcc, 0, v145, vcc
	v_lshlrev_b32_e32 v207, 2, v135
	global_load_dwordx4 v[132:135], v[132:133], off offset:16
	s_nop 0
	global_load_dwordx4 v[136:139], v[136:137], off offset:16
	s_nop 0
	global_load_dwordx4 v[144:147], v[146:147], off
	s_nop 0
	global_load_dwordx4 v[148:151], v[148:149], off
	v_mov_b32_e32 v197, 0
	v_mov_b32_e32 v211, 0
	v_readlane_b32 s46, v243, 5
	v_readlane_b32 s47, v243, 6
	v_readlane_b32 s48, v243, 7
	v_readlane_b32 s49, v243, 8
	v_readlane_b32 s50, v243, 9
	v_readlane_b32 s51, v243, 10
	v_readlane_b32 s52, v243, 11
	v_readlane_b32 s53, v243, 12
	v_readlane_b32 s54, v243, 13
	v_readlane_b32 s55, v243, 14
	v_readlane_b32 s56, v243, 15
	v_readlane_b32 s57, v243, 16
	v_readlane_b32 s58, v243, 17
	v_readlane_b32 s59, v243, 18
	s_waitcnt vmcnt(0)
	v_mov_b32_e32 v208, v152
	v_mov_b32_e32 v209, v156
	v_mov_b32_e32 v156, v153
	v_mov_b32_e32 v152, v154
	v_mov_b32_e32 v153, v158
	v_mov_b32_e32 v158, v155
	v_pk_add_f32 v[154:155], v[208:209], v[156:157]
	v_pk_add_f32 v[152:153], v[152:153], v[158:159]
	v_mov_b32_e32 v156, v188
	v_mov_b32_e32 v157, v192
	v_mov_b32_e32 v192, v189
	v_mov_b32_e32 v158, v190
	v_mov_b32_e32 v159, v194
	v_mov_b32_e32 v194, v191
	v_pk_add_f32 v[152:153], v[154:155], v[152:153]
	v_pk_add_f32 v[154:155], v[156:157], v[192:193]
	v_pk_add_f32 v[156:157], v[158:159], v[194:195]
	v_mov_b32_e32 v188, v212
	v_pk_add_f32 v[154:155], v[154:155], v[156:157]
	v_mov_b32_e32 v157, v152
	v_mov_b32_e32 v156, v154
	v_mov_b32_e32 v152, v155
	v_pk_add_f32 v[152:153], v[156:157], v[152:153]
	ds_bpermute_b32 v155, v196, v153
	ds_bpermute_b32 v154, v196, v152
	v_mov_b32_e32 v189, v216
	v_mov_b32_e32 v216, v213
	v_mov_b32_e32 v190, v214
	v_mov_b32_e32 v191, v218
	s_waitcnt lgkmcnt(0)
	v_pk_add_f32 v[152:153], v[152:153], v[154:155]
	ds_bpermute_b32 v155, v207, v153
	ds_bpermute_b32 v154, v207, v152
	v_mov_b32_e32 v218, v215
	v_mov_b32_e32 v208, v220
	v_mov_b32_e32 v209, v224
	v_mov_b32_e32 v224, v221
	v_mov_b32_e32 v212, v222
	v_mov_b32_e32 v213, v226
	v_mov_b32_e32 v226, v223
	v_pk_add_f32 v[156:157], v[188:189], v[216:217]
	v_pk_add_f32 v[158:159], v[190:191], v[218:219]
	v_pk_add_f32 v[188:189], v[208:209], v[224:225]
	v_pk_add_f32 v[190:191], v[212:213], v[226:227]
	s_waitcnt lgkmcnt(0)
; DI unsigned pack2(float lo, float hi) { f32x2 v = {lo, hi}; bf16v2 r = __builtin_convertvector(v, bf16v2); return __builtin_bit_cast(unsigned, r); }
; DI float dpp_ror1(float v) { return __int_as_float(__builtin_amdgcn_update_dpp(0, __float_as_int(v), 0x121, 0xf, 0xf, false)); }
; DI float dpp_ror2(float v) { return __int_as_float(__builtin_amdgcn_update_dpp(0, __float_as_int(v), 0x122, 0xf, 0xf, false)); }
;   DI void operator()(const f32x4 (&acc)[2][2][4][2], const Unit& u, int wr, int wc, int fr, int fq) const {
;     ...
;       float p1[8], p2[8];
; #pragma unroll
;       for (int e = 0; e < 8; ++e) { p1[e] = 0.f; p2[e] = 0.f; }
; #pragma unroll
;       for (int m = 0; m < 4; ++m) {
;         float g[8], a[8];
;         const float rs1 = rsv[m], rs2 = rs1 * rs1;
; #pragma unroll
;         for (int e = 0; e < 4; ++e) { g[e] = acc[ai][0][m][0][e] * acc[ai][1][m][0][e] * rs2; g[4 + e] = acc[ai][0][m][1][e] * acc[ai][1][m][1][e] * rs2; }
; #pragma unroll
;         for (int e = 0; e < 8; ++e) {
;           const float x1 = dpp_ror1(g[e]), x2 = dpp_ror2(g[e]);
;           const float pr1 = (fr == 0) ? p1[e] : x1, pr2 = (fr < 2) ? p2[e] : x2;
;           a[e] = w2[e] * g[e] + w1[e] * pr1 + w0[e] * pr2;
;           p1[e] = x1; p2[e] = x2;
;         }
;         if (m == 0 && fr < 2) {
;           float* hc = headC + (size_t)(span * 2 + fr) * 2048 + col;
;           *(f32x4*)hc = (f32x4){a[0], a[1], a[2], a[3]}; *(f32x4*)(hc + 4) = (f32x4){a[4], a[5], a[6], a[7]};
;         } else {
;           u32x4 w; w.x = pack2(a[0] * rs1, a[1] * rs1); w.y = pack2(a[2] * rs1, a[3] * rs1); w.z = pack2(a[4] * rs1, a[5] * rs1); w.w = pack2(a[6] * rs1, a[7] * rs1);
;           *(u32x4*)(C + (size_t)(row0 + 16 * m + fr) * 2048 + col) = w;
;         }
	v_pk_add_f32 v[152:153], v[152:153], v[154:155]
	v_pk_add_f32 v[156:157], v[156:157], v[158:159]
	v_pk_add_f32 v[158:159], v[188:189], v[190:191]
	v_pk_fma_f32 v[188:189], v[152:153], s[30:31], v[176:177] op_sel_hi:[1,0,0]
	v_mov_b32_e32 v153, v156
	v_mul_f32_e32 v152, 0x4b800000, v189
	v_cmp_gt_f32_e64 s[10:11], s84, v189
	v_mov_b32_e32 v156, v159
	v_mov_b32_e32 v194, v123
	v_cndmask_b32_e64 v152, v189, v152, s[10:11]
	v_rsq_f32_e32 v168, v152
	v_mov_b32_e32 v152, v158
	v_pk_add_f32 v[152:153], v[152:153], v[156:157]
	ds_bpermute_b32 v155, v196, v153
	ds_bpermute_b32 v154, v196, v152
	v_mul_f32_e32 v156, 0x45800000, v168
	v_cndmask_b32_e64 v195, v168, v156, s[10:11]
	v_mov_b32_e32 v217, 0
	v_mul_f32_e32 v156, v125, v113
	s_waitcnt lgkmcnt(0)
	v_pk_add_f32 v[190:191], v[152:153], v[154:155]
	v_mov_b32_e32 v152, v111
	v_mov_b32_e32 v153, v195
	v_mul_f32_e32 v154, v124, v112
	v_pk_mul_f32 v[152:153], v[194:195], v[152:153]
	v_mul_f32_e32 v155, v120, v108
	v_mul_f32_e32 v154, v154, v153
	v_pk_mul_f32 v[222:223], v[152:153], v[152:153] op_sel:[0,1] op_sel_hi:[1,0]
	v_mov_b32_e32 v213, 0
	v_mov_b32_dpp v217, v154 row_ror:1 row_mask:0xf bank_mask:0xf
	v_cndmask_b32_e64 v152, v217, 0, s[0:1]
	v_mul_f32_e32 v157, v121, v109
	v_mul_f32_e32 v158, v126, v114
	v_mul_f32_e32 v159, v122, v110
	v_mul_f32_e32 v168, v127, v115
	v_mul_f32_e32 v194, v155, v153
	v_mul_f32_e32 v155, v156, v153
	v_mov_b32_dpp v213, v154 row_ror:2 row_mask:0xf bank_mask:0xf
	v_mov_b32_e32 v221, 0
	v_mul_f32_e32 v152, v144, v152
	v_mul_f32_e32 v208, v157, v153
	v_mul_f32_e32 v156, v158, v153
	v_mul_f32_e32 v159, v159, v153
	v_mul_f32_e32 v157, v168, v153
	v_mov_b32_dpp v221, v155 row_ror:1 row_mask:0xf bank_mask:0xf
	v_cndmask_b32_e64 v153, v213, 0, s[8:9]
	v_fmac_f32_e32 v152, v148, v154
	v_mov_b32_e32 v219, 0
	v_fmac_f32_e32 v152, v140, v153
	v_cndmask_b32_e64 v153, v221, 0, s[0:1]
	v_mov_b32_dpp v219, v155 row_ror:2 row_mask:0xf bank_mask:0xf
	v_mul_f32_e32 v153, v145, v153
	v_mov_b32_e32 v216, 0
	v_cndmask_b32_e64 v154, v219, 0, s[8:9]
	v_fmac_f32_e32 v153, v149, v155
	v_mov_b32_dpp v216, v156 row_ror:1 row_mask:0xf bank_mask:0xf
	v_fmac_f32_e32 v153, v141, v154
	v_mov_b32_e32 v212, 0
	v_cndmask_b32_e64 v154, v216, 0, s[0:1]
	v_mov_b32_e32 v220, 0
	v_mov_b32_dpp v212, v156 row_ror:2 row_mask:0xf bank_mask:0xf
	v_mul_f32_e32 v154, v146, v154
	v_mov_b32_dpp v220, v157 row_ror:1 row_mask:0xf bank_mask:0xf
	v_cndmask_b32_e64 v155, v212, 0, s[8:9]
	v_fmac_f32_e32 v154, v150, v156
	v_mov_b32_e32 v218, 0
	v_fmac_f32_e32 v154, v142, v155
	v_cndmask_b32_e64 v155, v220, 0, s[0:1]
	v_mov_b32_dpp v218, v157 row_ror:2 row_mask:0xf bank_mask:0xf
	v_mul_f32_e32 v155, v147, v155
	v_cndmask_b32_e64 v156, v218, 0, s[8:9]
	v_fmac_f32_e32 v155, v151, v157
	v_mov_b32_dpp v197, v194 row_ror:1 row_mask:0xf bank_mask:0xf
	v_fmac_f32_e32 v155, v143, v156
	v_mov_b32_e32 v189, 0
	v_cndmask_b32_e64 v156, v197, 0, s[0:1]
	v_mov_b32_e32 v214, 0
	v_mov_b32_dpp v189, v194 row_ror:2 row_mask:0xf bank_mask:0xf
	v_mul_f32_e32 v156, v132, v156
	v_mov_b32_dpp v214, v208 row_ror:1 row_mask:0xf bank_mask:0xf
	v_cndmask_b32_e64 v157, v189, 0, s[8:9]
	v_fmac_f32_e32 v156, v136, v194
	v_fmac_f32_e32 v156, v128, v157
	v_cndmask_b32_e64 v157, v214, 0, s[0:1]
	v_mov_b32_e32 v209, 0
	v_mul_f32_e32 v157, v133, v157
	v_fmac_f32_e32 v157, v137, v208
	v_mov_b32_dpp v209, v208 row_ror:2 row_mask:0xf bank_mask:0xf
	v_mov_b32_e32 v208, 0
	v_cndmask_b32_e64 v158, v209, 0, s[8:9]
	v_fmac_f32_e32 v157, v129, v158
	v_mov_b32_dpp v208, v159 row_ror:1 row_mask:0xf bank_mask:0xf
	v_mov_b32_e32 v194, 0
	v_cndmask_b32_e64 v158, v208, 0, s[0:1]
	ds_bpermute_b32 v193, v207, v191
	ds_bpermute_b32 v192, v207, v190
	v_mov_b32_dpp v194, v159 row_ror:2 row_mask:0xf bank_mask:0xf
	v_mov_b32_e32 v215, 0
	v_mul_f32_e32 v158, v134, v158
	v_cndmask_b32_e64 v168, v194, 0, s[8:9]
	v_mov_b32_dpp v215, v222 row_ror:1 row_mask:0xf bank_mask:0xf
	v_fmac_f32_e32 v158, v138, v159
	v_mov_b32_dpp v211, v222 row_ror:2 row_mask:0xf bank_mask:0xf
	v_fmac_f32_e32 v158, v130, v168
	v_cndmask_b32_e64 v168, v215, 0, s[0:1]
	v_mul_f32_e32 v159, v139, v222
	v_cndmask_b32_e64 v223, v211, 0, s[8:9]
	v_fmac_f32_e32 v159, v135, v168
	v_cmp_gt_f32_e32 vcc, s84, v188
	v_fmac_f32_e32 v159, v131, v223
	s_and_saveexec_b64 s[10:11], s[4:5]
	s_xor_b64 s[10:11], exec, s[10:11]
	s_cbranch_execz .LBB0_1056
	v_mul_f32_e32 v152, v195, v152
	v_mul_f32_e32 v153, v195, v153
	v_cvt_pk_bf16_f32 v152, v152, v153
	v_mul_f32_e32 v153, v195, v154
	v_mul_f32_e32 v154, v195, v155
	v_cvt_pk_bf16_f32 v153, v153, v154
	v_mul_f32_e32 v154, v195, v156
	v_mul_f32_e32 v155, v195, v157
	v_cvt_pk_bf16_f32 v154, v154, v155
	v_mul_f32_e32 v155, v195, v158
	v_mul_f32_e32 v156, v195, v159
	v_cvt_pk_bf16_f32 v155, v155, v156
	v_lshlrev_b64 v[156:157], 12, v[186:187]
	v_lshl_add_u64 v[156:157], s[18:19], 0, v[156:157]
	v_lshl_add_u64 v[156:157], v[178:179], 1, v[156:157]
	global_store_dwordx4 v[156:157], v[152:155], off

; #define PG8_STAGE(bufoff, gbase, voff) do { _Pragma("unroll") for (int _i = 0; _i < 2; ++_i) \
;     __builtin_amdgcn_global_load_lds((const unsigned*)((const char*)(gbase) + (voff)[_i]), (LAS unsigned*)(lds + (bufoff) + ldsw + _i * 8192), 16, 0, 0); } while (0)
; #define PG8_LDA(dst, b, h) do { _Pragma("unroll") for (int m = 0; m < 4; ++m) _Pragma("unroll") for (int k = 0; k < 2; ++k) dst[m][k] = *(const LAS bf16x8*)(lds + PG8_SA(b, h) + aoff + m * 2048 + k * 1024); } while (0)
; #define PG8_LDB(dst, b, h) do { _Pragma("unroll") for (int n = 0; n < 2; ++n) _Pragma("unroll") for (int k = 0; k < 2; ++k) dst[n][k] = *(const LAS bf16x8*)(lds + PG8_SB(b, h) + boff + n * 2048 + k * 1024); } while (0)
; #define PG8_MMA(ai, bj, At, Bt) do { __builtin_amdgcn_s_setprio(1); _Pragma("unroll") for (int m = 0; m < 4; ++m) _Pragma("unroll") for (int n = 0; n < 2; ++n) _Pragma("unroll") for (int k = 0; k < 2; ++k) \
;     acc[ai][bj][m][n] = __builtin_amdgcn_mfma_f32_16x16x32_bf16(Bt[n][k], At[m][k], acc[ai][bj][m][n], 0, 0, 0); __builtin_amdgcn_s_setprio(0); } while (0)
; #define PG8_WAIT_V(n) asm volatile("s_waitcnt vmcnt(" #n ")" ::: "memory")
; #define PG8_WAIT_L(n) asm volatile("s_waitcnt lgkmcnt(" #n ")" ::: "memory")
; #define PG8_BAR __builtin_amdgcn_s_barrier()
; #define PG8_SCHED __builtin_amdgcn_sched_barrier(0)
; template <class Epi, class Sched = StaticOrder>
; DI void gemm_phase(LAS unsigned char* lds, const Gemm g, const Sched& S, const Epi& E) {
;     ...
;       const char* a1 = cA + (size_t)(t + 1) * kstep;
;       const char* a2 = last ? nA : cA + (size_t)(t + 2) * kstep; const char* b2 = last ? nB : cB + (size_t)(t + 2) * kstep;
;       const char* a3 = a2 + kstep; const char* b3 = b2 + kstep;
;       PG8_LDB(B0, 0, 0); PG8_SCHED; PG8_LDA(At, 0, 0); PG8_STAGE(PG8_SA(1, 1), a1 + hstep, voffA);
;       PG8_WAIT_L(8); PG8_BAR; PG8_WAIT_L(0); PG8_MMA(0, 0, At, B0); PG8_BAR; PG8_SCHED;
;       PG8_LDB(B1, 0, 1); PG8_STAGE(PG8_SB(0, 0), b2, voffB);
;       PG8_BAR; PG8_WAIT_L(0); PG8_MMA(0, 1, At, B1); PG8_BAR;
;       PG8_LDA(At, 0, 1); PG8_STAGE(PG8_SA(0, 0), a2, voffA);
;       PG8_BAR; PG8_WAIT_L(0); PG8_MMA(1, 0, At, B0); PG8_BAR; PG8_SCHED;
;       PG8_STAGE(PG8_SB(0, 1), b2 + hstep, voffB);
;       PG8_WAIT_V(6); PG8_BAR; PG8_MMA(1, 1, At, B1); PG8_BAR;
.LBB0_1194:
	ds_read_b128 v[128:131], v214
	ds_read_b128 v[132:135], v214 offset:1024
	ds_read_b128 v[136:139], v214 offset:2048
	ds_read_b128 v[140:143], v214 offset:3072
	s_add_u32 s24, s22, 0xfff80080
	s_addc_u32 s25, s23, -1
	s_cmp_eq_u32 s54, 28
	s_cselect_b32 s27, s17, s25
	s_cselect_b32 s26, s43, s24
	s_cselect_b32 s25, s15, s53
	s_cselect_b32 s24, s51, s52
	s_add_i32 m0, s37, 0xc000
	ds_read_b128 v[144:147], v215
	ds_read_b128 v[148:151], v215 offset:1024
	ds_read_b128 v[152:155], v215 offset:2048
	ds_read_b128 v[156:159], v215 offset:3072
	ds_read_b128 v[160:163], v215 offset:4096
	ds_read_b128 v[164:167], v215 offset:5120
	ds_read_b128 v[168:171], v215 offset:6144
	ds_read_b128 v[172:175], v215 offset:7168
	global_load_lds_dwordx4 v184, s[22:23]
	s_add_i32 m0, s37, 0xe000
	s_nop 0
	global_load_lds_dwordx4 v186, s[22:23]
	ds_read_b128 v[192:195], v216
	ds_read_b128 v[196:199], v216 offset:1024
	ds_read_b128 v[200:203], v216 offset:2048
	ds_read_b128 v[204:207], v216 offset:3072
	s_waitcnt vmcnt(8)
	s_waitcnt lgkmcnt(4)
	s_setprio 1
	s_barrier
	v_mfma_f32_16x16x32_bf16 v[124:127], v[128:131], v[144:147], v[124:127]
	v_mfma_f32_16x16x32_bf16 v[120:123], v[136:139], v[144:147], v[120:123]
	v_mfma_f32_16x16x32_bf16 v[108:111], v[128:131], v[152:155], v[108:111]
	v_mfma_f32_16x16x32_bf16 v[104:107], v[136:139], v[152:155], v[104:107]
	v_mfma_f32_16x16x32_bf16 v[92:95], v[128:131], v[160:163], v[92:95]
	v_mfma_f32_16x16x32_bf16 v[88:91], v[136:139], v[160:163], v[88:91]
	v_mfma_f32_16x16x32_bf16 v[76:79], v[128:131], v[168:171], v[76:79]
	v_mfma_f32_16x16x32_bf16 v[72:75], v[136:139], v[168:171], v[72:75]
	v_mfma_f32_16x16x32_bf16 v[124:127], v[132:135], v[148:151], v[124:127]
	v_mfma_f32_16x16x32_bf16 v[120:123], v[140:143], v[148:151], v[120:123]
	v_mfma_f32_16x16x32_bf16 v[108:111], v[132:135], v[156:159], v[108:111]
	v_mfma_f32_16x16x32_bf16 v[104:107], v[140:143], v[156:159], v[104:107]
	v_mfma_f32_16x16x32_bf16 v[92:95], v[132:135], v[164:167], v[92:95]
	v_mfma_f32_16x16x32_bf16 v[88:91], v[140:143], v[164:167], v[88:91]
	v_mfma_f32_16x16x32_bf16 v[76:79], v[132:135], v[172:175], v[76:79]
	v_mfma_f32_16x16x32_bf16 v[72:75], v[140:143], v[172:175], v[72:75]
	s_waitcnt lgkmcnt(0)
	v_mfma_f32_16x16x32_bf16 v[116:119], v[192:195], v[144:147], v[116:119]
	v_mfma_f32_16x16x32_bf16 v[112:115], v[200:203], v[144:147], v[112:115]
	v_mfma_f32_16x16x32_bf16 v[100:103], v[192:195], v[152:155], v[100:103]
	v_mfma_f32_16x16x32_bf16 v[96:99], v[200:203], v[152:155], v[96:99]
	v_mfma_f32_16x16x32_bf16 v[84:87], v[192:195], v[160:163], v[84:87]
	v_mfma_f32_16x16x32_bf16 v[80:83], v[200:203], v[160:163], v[80:83]
	v_mfma_f32_16x16x32_bf16 v[68:71], v[192:195], v[168:171], v[68:71]
	v_mfma_f32_16x16x32_bf16 v[64:67], v[200:203], v[168:171], v[64:67]
	v_mfma_f32_16x16x32_bf16 v[116:119], v[196:199], v[148:151], v[116:119]
	v_mfma_f32_16x16x32_bf16 v[112:115], v[204:207], v[148:151], v[112:115]
	v_mfma_f32_16x16x32_bf16 v[100:103], v[196:199], v[156:159], v[100:103]
	v_mfma_f32_16x16x32_bf16 v[96:99], v[204:207], v[156:159], v[96:99]
	v_mfma_f32_16x16x32_bf16 v[84:87], v[196:199], v[164:167], v[84:87]
	v_mfma_f32_16x16x32_bf16 v[80:83], v[204:207], v[164:167], v[80:83]
	v_mfma_f32_16x16x32_bf16 v[68:71], v[196:199], v[172:175], v[68:71]
	v_mfma_f32_16x16x32_bf16 v[64:67], v[204:207], v[172:175], v[64:67]
	s_barrier
	s_setprio 0
	s_add_i32 s55, s48, s35
	s_add_u32 s98, s24, 0x80
	s_addc_u32 s99, s25, 0
	s_add_u32 s100, s26, 0x80
	s_addc_u32 s101, s27, 0
	s_mov_b32 m0, s55
	s_nop 0
	global_load_lds_dwordx4 v180, s[24:25]
	s_add_i32 m0, s55, 0x2000
	s_nop 0
	global_load_lds_dwordx4 v176, s[24:25]
	s_mov_b32 m0, s37
	ds_read_b128 v[144:147], v215 offset:16384
	ds_read_b128 v[148:151], v215 offset:17408
	ds_read_b128 v[152:155], v215 offset:18432
	ds_read_b128 v[156:159], v215 offset:19456
	ds_read_b128 v[160:163], v215 offset:20480
	ds_read_b128 v[164:167], v215 offset:21504
	ds_read_b128 v[168:171], v215 offset:22528
	ds_read_b128 v[172:175], v215 offset:23552
	global_load_lds_dwordx4 v182, s[26:27]
	s_mov_b32 m0, s38
	s_nop 0
	global_load_lds_dwordx4 v178, s[26:27]
	s_add_u32 s56, s24, 0x80000
	s_addc_u32 s57, s25, 0
	s_add_i32 s55, s49, s35
	s_waitcnt vmcnt(6)
	s_waitcnt lgkmcnt(0)
	s_setprio 1
	s_barrier
	v_mfma_f32_16x16x32_bf16 v[60:63], v[128:131], v[144:147], v[60:63]
	s_mov_b32 m0, s55
	v_mfma_f32_16x16x32_bf16 v[56:59], v[136:139], v[144:147], v[56:59]
	global_load_lds_dwordx4 v180, s[56:57]
	v_mfma_f32_16x16x32_bf16 v[44:47], v[128:131], v[152:155], v[44:47]
	s_bitset1_b32 m0, 13
	v_mfma_f32_16x16x32_bf16 v[40:43], v[136:139], v[152:155], v[40:43]
	global_load_lds_dwordx4 v176, s[56:57]
	v_mfma_f32_16x16x32_bf16 v[28:31], v[128:131], v[160:163], v[28:31]
	v_mfma_f32_16x16x32_bf16 v[24:27], v[136:139], v[160:163], v[24:27]
	v_mfma_f32_16x16x32_bf16 v[12:15], v[128:131], v[168:171], v[12:15]
	v_mfma_f32_16x16x32_bf16 v[8:11], v[136:139], v[168:171], v[8:11]
	v_mfma_f32_16x16x32_bf16 v[60:63], v[132:135], v[148:151], v[60:63]
	v_mfma_f32_16x16x32_bf16 v[56:59], v[140:143], v[148:151], v[56:59]
	v_mfma_f32_16x16x32_bf16 v[44:47], v[132:135], v[156:159], v[44:47]
	v_mfma_f32_16x16x32_bf16 v[40:43], v[140:143], v[156:159], v[40:43]
	v_mfma_f32_16x16x32_bf16 v[28:31], v[132:135], v[164:167], v[28:31]
	v_mfma_f32_16x16x32_bf16 v[24:27], v[140:143], v[164:167], v[24:27]
	v_mfma_f32_16x16x32_bf16 v[12:15], v[132:135], v[172:175], v[12:15]
	v_mfma_f32_16x16x32_bf16 v[8:11], v[140:143], v[172:175], v[8:11]
	v_mfma_f32_16x16x32_bf16 v[52:55], v[192:195], v[144:147], v[52:55]
	v_mfma_f32_16x16x32_bf16 v[48:51], v[200:203], v[144:147], v[48:51]
	v_mfma_f32_16x16x32_bf16 v[36:39], v[192:195], v[152:155], v[36:39]
	v_mfma_f32_16x16x32_bf16 v[32:35], v[200:203], v[152:155], v[32:35]
	v_mfma_f32_16x16x32_bf16 v[20:23], v[192:195], v[160:163], v[20:23]
	v_mfma_f32_16x16x32_bf16 v[16:19], v[200:203], v[160:163], v[16:19]
	v_mfma_f32_16x16x32_bf16 v[4:7], v[192:195], v[168:171], v[4:7]
	v_mfma_f32_16x16x32_bf16 v[0:3], v[200:203], v[168:171], v[0:3]
	v_mfma_f32_16x16x32_bf16 v[52:55], v[196:199], v[148:151], v[52:55]
	v_mfma_f32_16x16x32_bf16 v[48:51], v[204:207], v[148:151], v[48:51]
	v_mfma_f32_16x16x32_bf16 v[36:39], v[196:199], v[156:159], v[36:39]
	v_mfma_f32_16x16x32_bf16 v[32:35], v[204:207], v[156:159], v[32:35]
	v_mfma_f32_16x16x32_bf16 v[20:23], v[196:199], v[164:167], v[20:23]
	v_mfma_f32_16x16x32_bf16 v[16:19], v[204:207], v[164:167], v[16:19]
	v_mfma_f32_16x16x32_bf16 v[4:7], v[196:199], v[172:175], v[4:7]
	v_mfma_f32_16x16x32_bf16 v[0:3], v[204:207], v[172:175], v[0:3]
	s_barrier
; #define PG8_STAGE(bufoff, gbase, voff) do { _Pragma("unroll") for (int _i = 0; _i < 2; ++_i) \
;     __builtin_amdgcn_global_load_lds((const unsigned*)((const char*)(gbase) + (voff)[_i]), (LAS unsigned*)(lds + (bufoff) + ldsw + _i * 8192), 16, 0, 0); } while (0)
; #define PG8_LDA(dst, b, h) do { _Pragma("unroll") for (int m = 0; m < 4; ++m) _Pragma("unroll") for (int k = 0; k < 2; ++k) dst[m][k] = *(const LAS bf16x8*)(lds + PG8_SA(b, h) + aoff + m * 2048 + k * 1024); } while (0)
; #define PG8_LDB(dst, b, h) do { _Pragma("unroll") for (int n = 0; n < 2; ++n) _Pragma("unroll") for (int k = 0; k < 2; ++k) dst[n][k] = *(const LAS bf16x8*)(lds + PG8_SB(b, h) + boff + n * 2048 + k * 1024); } while (0)
; #define PG8_MMA(ai, bj, At, Bt) do { __builtin_amdgcn_s_setprio(1); _Pragma("unroll") for (int m = 0; m < 4; ++m) _Pragma("unroll") for (int n = 0; n < 2; ++n) _Pragma("unroll") for (int k = 0; k < 2; ++k) \
;     acc[ai][bj][m][n] = __builtin_amdgcn_mfma_f32_16x16x32_bf16(Bt[n][k], At[m][k], acc[ai][bj][m][n], 0, 0, 0); __builtin_amdgcn_s_setprio(0); } while (0)
; #define PG8_WAIT_V(n) asm volatile("s_waitcnt vmcnt(" #n ")" ::: "memory")
; #define PG8_WAIT_L(n) asm volatile("s_waitcnt lgkmcnt(" #n ")" ::: "memory")
; #define PG8_BAR __builtin_amdgcn_s_barrier()
; #define PG8_SCHED __builtin_amdgcn_sched_barrier(0)
; template <class Epi, class Sched = StaticOrder>
; DI void gemm_phase(LAS unsigned char* lds, const Gemm g, const Sched& S, const Epi& E) {
;     ...
;       PG8_LDB(B0, 1, 0); PG8_SCHED; PG8_LDA(At, 1, 0); PG8_STAGE(PG8_SA(0, 1), a2 + hstep, voffA);
;       PG8_WAIT_L(8); PG8_BAR; PG8_WAIT_L(0); PG8_MMA(0, 0, At, B0); PG8_BAR; PG8_SCHED;
;       PG8_LDB(B1, 1, 1); PG8_STAGE(PG8_SB(1, 0), b3, voffB);
;       PG8_BAR; PG8_WAIT_L(0); PG8_MMA(0, 1, At, B1); PG8_BAR;
;       PG8_LDA(At, 1, 1); PG8_STAGE(PG8_SA(1, 0), a3, voffA);
;       PG8_BAR; PG8_WAIT_L(0); PG8_MMA(1, 0, At, B0); PG8_BAR; PG8_SCHED;
;       PG8_STAGE(PG8_SB(1, 1), b3 + hstep, voffB);
;       PG8_WAIT_V(6); PG8_BAR; PG8_MMA(1, 1, At, B1); PG8_BAR;
	s_setprio 0
	s_add_i32 s55, 0, 0x18000
	v_add_u32_e32 v140, s55, v212
	ds_read_b128 v[128:131], v140
	ds_read_b128 v[132:135], v140 offset:1024
	ds_read_b128 v[136:139], v140 offset:2048
	ds_read_b128 v[140:143], v140 offset:3072
	s_add_u32 s26, s26, 0x80000
	s_addc_u32 s27, s27, 0
	s_mov_b32 m0, s39
	ds_read_b128 v[144:147], v215 offset:32768
	ds_read_b128 v[148:151], v215 offset:33792
	ds_read_b128 v[152:155], v215 offset:34816
	ds_read_b128 v[156:159], v215 offset:35840
	ds_read_b128 v[160:163], v215 offset:36864
	ds_read_b128 v[164:167], v215 offset:37888
	ds_read_b128 v[168:171], v215 offset:38912
	ds_read_b128 v[172:175], v215 offset:39936
	global_load_lds_dwordx4 v182, s[26:27]
	s_mov_b32 m0, s40
	s_nop 0
	global_load_lds_dwordx4 v178, s[26:27]
	s_add_i32 s26, 0, 0x1c000
	v_add_u32_e32 v204, s26, v212
	ds_read_b128 v[192:195], v204
	ds_read_b128 v[196:199], v204 offset:1024
	ds_read_b128 v[200:203], v204 offset:2048
	ds_read_b128 v[204:207], v204 offset:3072
	s_waitcnt vmcnt(8)
	s_waitcnt lgkmcnt(4)
	s_setprio 1
	s_barrier
	v_mfma_f32_16x16x32_bf16 v[124:127], v[128:131], v[144:147], v[124:127]
	v_mfma_f32_16x16x32_bf16 v[120:123], v[136:139], v[144:147], v[120:123]
	v_mfma_f32_16x16x32_bf16 v[108:111], v[128:131], v[152:155], v[108:111]
	v_mfma_f32_16x16x32_bf16 v[104:107], v[136:139], v[152:155], v[104:107]
	v_mfma_f32_16x16x32_bf16 v[92:95], v[128:131], v[160:163], v[92:95]
	v_mfma_f32_16x16x32_bf16 v[88:91], v[136:139], v[160:163], v[88:91]
	v_mfma_f32_16x16x32_bf16 v[76:79], v[128:131], v[168:171], v[76:79]
	v_mfma_f32_16x16x32_bf16 v[72:75], v[136:139], v[168:171], v[72:75]
	v_mfma_f32_16x16x32_bf16 v[124:127], v[132:135], v[148:151], v[124:127]
	v_mfma_f32_16x16x32_bf16 v[120:123], v[140:143], v[148:151], v[120:123]
	v_mfma_f32_16x16x32_bf16 v[108:111], v[132:135], v[156:159], v[108:111]
	v_mfma_f32_16x16x32_bf16 v[104:107], v[140:143], v[156:159], v[104:107]
	v_mfma_f32_16x16x32_bf16 v[92:95], v[132:135], v[164:167], v[92:95]
	v_mfma_f32_16x16x32_bf16 v[88:91], v[140:143], v[164:167], v[88:91]
	v_mfma_f32_16x16x32_bf16 v[76:79], v[132:135], v[172:175], v[76:79]
	v_mfma_f32_16x16x32_bf16 v[72:75], v[140:143], v[172:175], v[72:75]
	s_waitcnt lgkmcnt(0)
	v_mfma_f32_16x16x32_bf16 v[116:119], v[192:195], v[144:147], v[116:119]
	v_mfma_f32_16x16x32_bf16 v[112:115], v[200:203], v[144:147], v[112:115]
	v_mfma_f32_16x16x32_bf16 v[100:103], v[192:195], v[152:155], v[100:103]
	v_mfma_f32_16x16x32_bf16 v[96:99], v[200:203], v[152:155], v[96:99]
	v_mfma_f32_16x16x32_bf16 v[84:87], v[192:195], v[160:163], v[84:87]
	v_mfma_f32_16x16x32_bf16 v[80:83], v[200:203], v[160:163], v[80:83]
	v_mfma_f32_16x16x32_bf16 v[68:71], v[192:195], v[168:171], v[68:71]
	v_mfma_f32_16x16x32_bf16 v[64:67], v[200:203], v[168:171], v[64:67]
	v_mfma_f32_16x16x32_bf16 v[116:119], v[196:199], v[148:151], v[116:119]
	v_mfma_f32_16x16x32_bf16 v[112:115], v[204:207], v[148:151], v[112:115]
	v_mfma_f32_16x16x32_bf16 v[100:103], v[196:199], v[156:159], v[100:103]
	v_mfma_f32_16x16x32_bf16 v[96:99], v[204:207], v[156:159], v[96:99]
	v_mfma_f32_16x16x32_bf16 v[84:87], v[196:199], v[164:167], v[84:87]
	v_mfma_f32_16x16x32_bf16 v[80:83], v[204:207], v[164:167], v[80:83]
	v_mfma_f32_16x16x32_bf16 v[68:71], v[196:199], v[172:175], v[68:71]
	v_mfma_f32_16x16x32_bf16 v[64:67], v[204:207], v[172:175], v[64:67]
	s_barrier
	s_setprio 0
	s_add_i32 s27, s55, s35
	s_mov_b32 m0, s27
	s_nop 0
	global_load_lds_dwordx4 v180, s[98:99]
	s_add_i32 m0, s27, 0x2000
	s_nop 0
	global_load_lds_dwordx4 v176, s[98:99]
	s_mov_b32 m0, s44
	ds_read_b128 v[144:147], v215 offset:49152
	ds_read_b128 v[148:151], v215 offset:50176
	ds_read_b128 v[152:155], v215 offset:51200
	ds_read_b128 v[156:159], v215 offset:52224
	ds_read_b128 v[160:163], v215 offset:53248
	ds_read_b128 v[164:167], v215 offset:54272
	ds_read_b128 v[168:171], v215 offset:55296
	ds_read_b128 v[172:175], v215 offset:56320
	global_load_lds_dwordx4 v182, s[100:101]
	s_mov_b32 m0, s45
	s_nop 0
	global_load_lds_dwordx4 v178, s[100:101]
	s_add_u32 s24, s24, 0x80080
	s_addc_u32 s25, s25, 0
	s_add_i32 s26, s26, s35
	s_add_i32 s54, s54, 2
	s_add_u32 s22, s22, 0x100
	s_addc_u32 s23, s23, 0
	s_add_u32 s52, s52, 0x100
	s_addc_u32 s53, s53, 0
	s_cmp_gt_u32 s54, 29
	s_waitcnt vmcnt(6)
	s_waitcnt lgkmcnt(0)
	s_setprio 1
	s_barrier
	v_mfma_f32_16x16x32_bf16 v[60:63], v[128:131], v[144:147], v[60:63]
	s_mov_b32 m0, s26
	v_mfma_f32_16x16x32_bf16 v[56:59], v[136:139], v[144:147], v[56:59]
	global_load_lds_dwordx4 v180, s[24:25]
	v_mfma_f32_16x16x32_bf16 v[44:47], v[128:131], v[152:155], v[44:47]
	s_bitset1_b32 m0, 13
	v_mfma_f32_16x16x32_bf16 v[40:43], v[136:139], v[152:155], v[40:43]
	global_load_lds_dwordx4 v176, s[24:25]
	v_mfma_f32_16x16x32_bf16 v[28:31], v[128:131], v[160:163], v[28:31]
	v_mfma_f32_16x16x32_bf16 v[24:27], v[136:139], v[160:163], v[24:27]
	v_mfma_f32_16x16x32_bf16 v[12:15], v[128:131], v[168:171], v[12:15]
	v_mfma_f32_16x16x32_bf16 v[8:11], v[136:139], v[168:171], v[8:11]
	v_mfma_f32_16x16x32_bf16 v[60:63], v[132:135], v[148:151], v[60:63]
	v_mfma_f32_16x16x32_bf16 v[56:59], v[140:143], v[148:151], v[56:59]
	v_mfma_f32_16x16x32_bf16 v[44:47], v[132:135], v[156:159], v[44:47]
	v_mfma_f32_16x16x32_bf16 v[40:43], v[140:143], v[156:159], v[40:43]
	v_mfma_f32_16x16x32_bf16 v[28:31], v[132:135], v[164:167], v[28:31]
	v_mfma_f32_16x16x32_bf16 v[24:27], v[140:143], v[164:167], v[24:27]
	v_mfma_f32_16x16x32_bf16 v[12:15], v[132:135], v[172:175], v[12:15]
	v_mfma_f32_16x16x32_bf16 v[8:11], v[140:143], v[172:175], v[8:11]
	v_mfma_f32_16x16x32_bf16 v[52:55], v[192:195], v[144:147], v[52:55]
	v_mfma_f32_16x16x32_bf16 v[48:51], v[200:203], v[144:147], v[48:51]
	v_mfma_f32_16x16x32_bf16 v[36:39], v[192:195], v[152:155], v[36:39]
	v_mfma_f32_16x16x32_bf16 v[32:35], v[200:203], v[152:155], v[32:35]
	v_mfma_f32_16x16x32_bf16 v[20:23], v[192:195], v[160:163], v[20:23]
	v_mfma_f32_16x16x32_bf16 v[16:19], v[200:203], v[160:163], v[16:19]
	v_mfma_f32_16x16x32_bf16 v[4:7], v[192:195], v[168:171], v[4:7]
	v_mfma_f32_16x16x32_bf16 v[0:3], v[200:203], v[168:171], v[0:3]
	v_mfma_f32_16x16x32_bf16 v[52:55], v[196:199], v[148:151], v[52:55]
	v_mfma_f32_16x16x32_bf16 v[48:51], v[204:207], v[148:151], v[48:51]
	v_mfma_f32_16x16x32_bf16 v[36:39], v[196:199], v[156:159], v[36:39]
	v_mfma_f32_16x16x32_bf16 v[32:35], v[204:207], v[156:159], v[32:35]
	v_mfma_f32_16x16x32_bf16 v[20:23], v[196:199], v[164:167], v[20:23]
	v_mfma_f32_16x16x32_bf16 v[16:19], v[204:207], v[164:167], v[16:19]
	v_mfma_f32_16x16x32_bf16 v[4:7], v[196:199], v[172:175], v[4:7]
	v_mfma_f32_16x16x32_bf16 v[0:3], v[204:207], v[172:175], v[0:3]
	s_barrier
; DI unsigned pack2(float lo, float hi) { f32x2 v = {lo, hi}; bf16v2 r = __builtin_convertvector(v, bf16v2); return __builtin_bit_cast(unsigned, r); }
;   DI void operator()(const f32x4 (&acc)[2][2][4][2], const Unit& u, int wr, int wc, int fr, int fq) const {
;     const int row0 = u.pm * BM + wr * 64 + fr, col0 = u.pn * BM + wc * 32 + 8 * fq;
; #pragma unroll
;     for (int ai = 0; ai < 2; ++ai) {
;       f32x4 bv[4][2][2];
; #pragma unroll
;       for (int m = 0; m < 4; ++m)
; #pragma unroll
;         for (int bj = 0; bj < 2; ++bj) {
;           const float* bp = base + (size_t)(row0 + ai * HALF + m * 16) * 2048 + col0 + bj * HALF;
;           bv[m][bj][0] = *(const f32x4*)bp; bv[m][bj][1] = *(const f32x4*)(bp + 4);
;         }
; #pragma unroll
;       for (int m = 0; m < 4; ++m) {
;         const int row = row0 + ai * HALF + m * 16;
;         const size_t off = (size_t)row * 2048 + col0;
;         float ss = 0.f;
; #pragma unroll
;         for (int bj = 0; bj < 2; ++bj) {
;           const f32x4 v0 = acc[ai][bj][m][0] + bv[m][bj][0], v1 = acc[ai][bj][m][1] + bv[m][bj][1];
;           *(f32x4*)(C + off + bj * HALF) = v0; *(f32x4*)(C + off + bj * HALF + 4) = v1;
;           if (xb) {
;             u32x4 w; w.x = pack2(v0[0], v0[1]); w.y = pack2(v0[2], v0[3]); w.z = pack2(v1[0], v1[1]); w.w = pack2(v1[2], v1[3]);
;             *(u32x4*)(xb + off + bj * HALF) = w;
;             ss += v0[0] * v0[0] + v0[1] * v0[1] + v0[2] * v0[2] + v0[3] * v0[3] + v1[0] * v1[0] + v1[1] * v1[1] + v1[2] * v1[2] + v1[3] * v1[3];
;           }
;         }
;         if (xb) {
;           ss += __shfl_xor(ss, 16); ss += __shfl_xor(ss, 32);
;           if (fq == 0) ssq[(size_t)row * 32 + u.pn * 4 + wc] = ss;
;         }
	s_setprio 0
	s_cbranch_scc0 .LBB0_1194
	v_lshl_add_u32 v194, s12, 8, v211
	v_lshl_or_b32 v192, s42, 8, v213
	v_readlane_b32 s52, v243, 3
	v_ashrrev_i32_e32 v193, 31, v192
	v_readlane_b32 s66, v243, 17
	v_readlane_b32 s67, v243, 18
	v_ashrrev_i32_e32 v195, 31, v194
	v_lshlrev_b64 v[128:129], 13, v[194:195]
	v_lshl_add_u64 v[196:197], v[192:193], 2, s[66:67]
	v_lshl_add_u64 v[236:237], v[196:197], 0, v[128:129]
	global_load_dwordx4 v[220:223], v[236:237], off
	global_load_dwordx4 v[224:227], v[236:237], off offset:16
	global_load_dwordx4 v[228:231], v[236:237], off offset:512
	global_load_dwordx4 v[232:235], v[236:237], off offset:528
	v_or_b32_e32 v206, 16, v194
	v_or_b32_e32 v202, 32, v194
	v_or_b32_e32 v198, 48, v194
	v_ashrrev_i32_e32 v207, 31, v206
	v_ashrrev_i32_e32 v203, 31, v202
	v_ashrrev_i32_e32 v199, 31, v198
	v_lshlrev_b64 v[128:129], 13, v[206:207]
	v_lshlrev_b64 v[130:131], 13, v[202:203]
	v_lshlrev_b64 v[132:133], 13, v[198:199]
	v_lshl_add_u64 v[208:209], v[196:197], 0, v[128:129]
	v_lshl_add_u64 v[204:205], v[196:197], 0, v[130:131]
	v_lshl_add_u64 v[200:201], v[196:197], 0, v[132:133]
	global_load_dwordx4 v[168:171], v[208:209], off offset:16
	global_load_dwordx4 v[172:175], v[208:209], off
	global_load_dwordx4 v[160:163], v[208:209], off offset:528
	global_load_dwordx4 v[164:167], v[208:209], off offset:512
	global_load_dwordx4 v[152:155], v[204:205], off offset:16
	global_load_dwordx4 v[156:159], v[204:205], off
	global_load_dwordx4 v[144:147], v[204:205], off offset:528
	global_load_dwordx4 v[148:151], v[204:205], off offset:512
	global_load_dwordx4 v[136:139], v[200:201], off offset:16
	global_load_dwordx4 v[140:143], v[200:201], off
	global_load_dwordx4 v[128:131], v[200:201], off offset:528
	global_load_dwordx4 v[132:135], v[200:201], off offset:512
	v_and_b32_e32 v218, 64, v217
	v_xor_b32_e32 v238, 16, v217
	v_add_u32_e32 v240, 64, v218
	v_xor_b32_e32 v239, 32, v217
	v_cmp_lt_i32_e32 vcc, v238, v240
	v_lshlrev_b64 v[218:219], 11, v[194:195]
	s_lshl_b32 s22, s42, 2
	v_cndmask_b32_e32 v241, v217, v238, vcc
	v_cmp_lt_i32_e32 vcc, v239, v240
	s_ashr_i32 s23, s22, 31
	v_readlane_b32 s53, v243, 4
	v_cndmask_b32_e32 v240, v217, v239, vcc
	v_lshl_add_u64 v[238:239], v[218:219], 0, v[192:193]
	v_lshlrev_b32_e32 v218, 2, v241
	v_lshl_add_u64 v[238:239], v[238:239], 1, s[2:3]
	v_readlane_b32 s54, v243, 5
	v_readlane_b32 s55, v243, 6
	v_readlane_b32 s56, v243, 7
	v_readlane_b32 s57, v243, 8
	v_readlane_b32 s58, v243, 9
	v_readlane_b32 s59, v243, 10
	v_readlane_b32 s60, v243, 11
	v_readlane_b32 s61, v243, 12
	v_readlane_b32 s62, v243, 13
	v_readlane_b32 s63, v243, 14
	v_readlane_b32 s64, v243, 15
	v_readlane_b32 s65, v243, 16
	s_waitcnt vmcnt(0)
	v_pk_add_f32 v[126:127], v[126:127], v[222:223]
	v_pk_add_f32 v[124:125], v[124:125], v[220:221]
	v_pk_add_f32 v[116:117], v[116:117], v[228:229]
	v_pk_add_f32 v[122:123], v[122:123], v[226:227]
	v_pk_add_f32 v[120:121], v[120:121], v[224:225]
	v_pk_add_f32 v[220:221], v[112:113], v[232:233]
	global_store_dwordx4 v[236:237], v[124:127], off
	global_store_dwordx4 v[236:237], v[120:123], off offset:16
	v_cvt_pk_bf16_f32 v112, v124, v125
	v_mul_f32_e32 v125, v125, v125
	v_mul_f32_e32 v219, v117, v117
	v_pk_add_f32 v[118:119], v[118:119], v[230:231]
	v_fmac_f32_e32 v125, v124, v124
	v_fmac_f32_e32 v219, v116, v116
	v_fmac_f32_e32 v125, v126, v126
	v_fmac_f32_e32 v219, v118, v118
	v_fmac_f32_e32 v125, v127, v127
	v_fmac_f32_e32 v219, v119, v119
	v_fmac_f32_e32 v125, v120, v120
	v_fmac_f32_e32 v219, v220, v220
	v_pk_add_f32 v[222:223], v[114:115], v[234:235]
	v_fmac_f32_e32 v125, v121, v121
	v_fmac_f32_e32 v219, v221, v221
	v_fmac_f32_e32 v125, v122, v122
	v_fmac_f32_e32 v219, v222, v222
	v_fmac_f32_e32 v125, v123, v123
	v_fmac_f32_e32 v219, v223, v223
	v_cvt_pk_bf16_f32 v114, v120, v121
	v_add_f32_e32 v121, v125, v219
	v_cvt_pk_bf16_f32 v115, v122, v123
	ds_bpermute_b32 v122, v218, v121
	v_cvt_pk_bf16_f32 v113, v126, v127
	global_store_dwordx4 v[238:239], v[112:115], off
	global_store_dwordx4 v[236:237], v[116:119], off offset:512
	global_store_dwordx4 v[236:237], v[220:223], off offset:528
	v_lshlrev_b32_e32 v126, 2, v240
	v_cvt_pk_bf16_f32 v120, v116, v117
	s_waitcnt lgkmcnt(0)
	v_add_f32_e32 v112, v121, v122
	ds_bpermute_b32 v113, v126, v112
	v_cvt_pk_bf16_f32 v121, v118, v119
	v_cvt_pk_bf16_f32 v122, v220, v221
	v_cvt_pk_bf16_f32 v123, v222, v223
	global_store_dwordx4 v[238:239], v[120:123], off offset:256
	s_and_saveexec_b64 s[24:25], s[0:1]
	s_cbranch_execz .LBB0_1197
	s_waitcnt lgkmcnt(0)
	v_add_f32_e32 v114, v112, v113
	v_lshlrev_b64 v[112:113], 7, v[194:195]
	v_lshl_add_u64 v[112:113], s[8:9], 0, v[112:113]
	v_lshl_add_u64 v[112:113], s[22:23], 2, v[112:113]
	s_lshl_b32 s12, s41, 2
	v_lshl_add_u64 v[112:113], v[112:113], 0, s[12:13]
	global_store_dword v[112:113], v114, off

; #define PG8_STAGE(bufoff, gbase, voff) do { _Pragma("unroll") for (int _i = 0; _i < 2; ++_i) \
;     __builtin_amdgcn_global_load_lds((const unsigned*)((const char*)(gbase) + (voff)[_i]), (LAS unsigned*)(lds + (bufoff) + ldsw + _i * 8192), 16, 0, 0); } while (0)
; #define PG8_LDA(dst, b, h) do { _Pragma("unroll") for (int m = 0; m < 4; ++m) _Pragma("unroll") for (int k = 0; k < 2; ++k) dst[m][k] = *(const LAS bf16x8*)(lds + PG8_SA(b, h) + aoff + m * 2048 + k * 1024); } while (0)
; #define PG8_LDB(dst, b, h) do { _Pragma("unroll") for (int n = 0; n < 2; ++n) _Pragma("unroll") for (int k = 0; k < 2; ++k) dst[n][k] = *(const LAS bf16x8*)(lds + PG8_SB(b, h) + boff + n * 2048 + k * 1024); } while (0)
; #define PG8_MMA(ai, bj, At, Bt) do { __builtin_amdgcn_s_setprio(1); _Pragma("unroll") for (int m = 0; m < 4; ++m) _Pragma("unroll") for (int n = 0; n < 2; ++n) _Pragma("unroll") for (int k = 0; k < 2; ++k) \
;     acc[ai][bj][m][n] = __builtin_amdgcn_mfma_f32_16x16x32_bf16(Bt[n][k], At[m][k], acc[ai][bj][m][n], 0, 0, 0); __builtin_amdgcn_s_setprio(0); } while (0)
; #define PG8_BAR __builtin_amdgcn_s_barrier()
; template <class Epi, class Sched = StaticOrder>
; DI void gemm_phase(LAS unsigned char* lds, const Gemm g, const Sched& S, const Epi& E) {
;     ...
;     const bool has_next = S.next(ui + 1, nxt);
;     const char* nA = has_next ? (const char*)g.A + (size_t)nxt.pm * tstep : cA; const char* nB = has_next ? (const char*)g.Bt + (size_t)nxt.pn * tstep : cB;
;     for (int t = 0; t < nt; t += 2) {
;       const bool last = (t == nt - 2);
;       const char* a1 = cA + (size_t)(t + 1) * kstep;
;       const char* a2 = last ? nA : cA + (size_t)(t + 2) * kstep; const char* b2 = last ? nB : cB + (size_t)(t + 2) * kstep;
;       const char* a3 = a2 + kstep; const char* b3 = b2 + kstep;
;       PG8_LDB(B0, 0, 0); PG8_SCHED; PG8_LDA(At, 0, 0); PG8_STAGE(PG8_SA(1, 1), a1 + hstep, voffA);
;       PG8_WAIT_L(8); PG8_BAR; PG8_WAIT_L(0); PG8_MMA(0, 0, At, B0); PG8_BAR; PG8_SCHED;
;       PG8_LDB(B1, 0, 1); PG8_STAGE(PG8_SB(0, 0), b2, voffB);
;       PG8_BAR; PG8_WAIT_L(0); PG8_MMA(0, 1, At, B1); PG8_BAR;
;       PG8_LDA(At, 0, 1); PG8_STAGE(PG8_SA(0, 0), a2, voffA);
;       PG8_BAR; PG8_WAIT_L(0); PG8_MMA(1, 0, At, B0); PG8_BAR; PG8_SCHED;
;       PG8_STAGE(PG8_SB(0, 1), b2 + hstep, voffB);
;       PG8_WAIT_V(6); PG8_BAR; PG8_MMA(1, 1, At, B1); PG8_BAR;
.LBB0_1277:
	ds_read_b128 v[64:67], v201
	ds_read_b128 v[68:71], v201 offset:1024
	ds_read_b128 v[72:75], v201 offset:2048
	ds_read_b128 v[76:79], v201 offset:3072
	s_add_u32 s48, s14, 0xfff80080
	s_addc_u32 s49, s15, -1
	s_cmp_eq_u32 s58, 28
	s_cselect_b32 s51, s41, s49
	s_cselect_b32 s50, s42, s48
	s_cselect_b32 s49, s39, s53
	s_cselect_b32 s48, s43, s52
	s_add_i32 m0, s64, 0xc000
	ds_read_b128 v[80:83], v202
	ds_read_b128 v[84:87], v202 offset:1024
	ds_read_b128 v[88:91], v202 offset:2048
	ds_read_b128 v[92:95], v202 offset:3072
	ds_read_b128 v[180:183], v202 offset:4096
	ds_read_b128 v[184:187], v202 offset:5120
	ds_read_b128 v[188:191], v202 offset:6144
	ds_read_b128 v[192:195], v202 offset:7168
	global_load_lds_dwordx4 v170, s[14:15]
	s_add_i32 m0, s64, 0xe000
	s_nop 0
	global_load_lds_dwordx4 v172, s[14:15]
	ds_read_b128 v[206:209], v203
	ds_read_b128 v[212:215], v203 offset:1024
	ds_read_b128 v[216:219], v203 offset:2048
	ds_read_b128 v[220:223], v203 offset:3072
	s_waitcnt vmcnt(8)
	s_waitcnt lgkmcnt(4)
	s_setprio 1
	s_barrier
	v_mfma_f32_16x16x32_bf16 v[156:159], v[64:67], v[80:83], v[156:159]
	v_mfma_f32_16x16x32_bf16 v[144:147], v[72:75], v[80:83], v[144:147]
	v_mfma_f32_16x16x32_bf16 v[140:143], v[64:67], v[88:91], v[140:143]
	v_mfma_f32_16x16x32_bf16 v[132:135], v[72:75], v[88:91], v[132:135]
	v_mfma_f32_16x16x32_bf16 v[124:127], v[64:67], v[180:183], v[124:127]
	v_mfma_f32_16x16x32_bf16 v[116:119], v[72:75], v[180:183], v[116:119]
	v_mfma_f32_16x16x32_bf16 v[112:115], v[64:67], v[188:191], v[112:115]
	v_mfma_f32_16x16x32_bf16 v[108:111], v[72:75], v[188:191], v[108:111]
	v_mfma_f32_16x16x32_bf16 v[156:159], v[68:71], v[84:87], v[156:159]
	v_mfma_f32_16x16x32_bf16 v[144:147], v[76:79], v[84:87], v[144:147]
	v_mfma_f32_16x16x32_bf16 v[140:143], v[68:71], v[92:95], v[140:143]
	v_mfma_f32_16x16x32_bf16 v[132:135], v[76:79], v[92:95], v[132:135]
	v_mfma_f32_16x16x32_bf16 v[124:127], v[68:71], v[184:187], v[124:127]
	v_mfma_f32_16x16x32_bf16 v[116:119], v[76:79], v[184:187], v[116:119]
	v_mfma_f32_16x16x32_bf16 v[112:115], v[68:71], v[192:195], v[112:115]
	v_mfma_f32_16x16x32_bf16 v[108:111], v[76:79], v[192:195], v[108:111]
	s_waitcnt lgkmcnt(0)
	v_mfma_f32_16x16x32_bf16 v[152:155], v[206:209], v[80:83], v[152:155]
	v_mfma_f32_16x16x32_bf16 v[80:83], v[216:219], v[80:83], v[148:151]
	v_mfma_f32_16x16x32_bf16 v[152:155], v[212:215], v[84:87], v[152:155]
	v_mfma_f32_16x16x32_bf16 v[80:83], v[220:223], v[84:87], v[80:83]
	v_mfma_f32_16x16x32_bf16 v[84:87], v[206:209], v[88:91], v[136:139]
	v_mfma_f32_16x16x32_bf16 v[88:91], v[216:219], v[88:91], v[128:131]
	v_mfma_f32_16x16x32_bf16 v[104:107], v[216:219], v[180:183], v[104:107]
	v_mfma_f32_16x16x32_bf16 v[100:103], v[206:209], v[188:191], v[100:103]
	v_mfma_f32_16x16x32_bf16 v[96:99], v[216:219], v[188:191], v[96:99]
	v_mfma_f32_16x16x32_bf16 v[84:87], v[212:215], v[92:95], v[84:87]
	v_mfma_f32_16x16x32_bf16 v[88:91], v[220:223], v[92:95], v[88:91]
	v_mfma_f32_16x16x32_bf16 v[92:95], v[206:209], v[180:183], v[120:123]
	v_mfma_f32_16x16x32_bf16 v[104:107], v[220:223], v[184:187], v[104:107]
	v_mfma_f32_16x16x32_bf16 v[100:103], v[212:215], v[192:195], v[100:103]
	v_mfma_f32_16x16x32_bf16 v[96:99], v[220:223], v[192:195], v[96:99]
	v_mfma_f32_16x16x32_bf16 v[92:95], v[212:215], v[184:187], v[92:95]
	s_barrier
	s_setprio 0
	s_add_i32 s59, s72, s62
	s_add_u32 s98, s48, 0x80
	s_addc_u32 s99, s49, 0
	s_add_u32 s100, s50, 0x80
	s_addc_u32 s101, s51, 0
	s_mov_b32 m0, s59
	s_nop 0
	global_load_lds_dwordx4 v164, s[48:49]
	s_add_i32 m0, s59, 0x2000
	s_nop 0
	global_load_lds_dwordx4 v160, s[48:49]
	s_mov_b32 m0, s64
	ds_read_b128 v[120:123], v202 offset:16384
	ds_read_b128 v[128:131], v202 offset:17408
	ds_read_b128 v[136:139], v202 offset:18432
	ds_read_b128 v[148:151], v202 offset:19456
	ds_read_b128 v[180:183], v202 offset:20480
	ds_read_b128 v[184:187], v202 offset:21504
	ds_read_b128 v[188:191], v202 offset:22528
	ds_read_b128 v[192:195], v202 offset:23552
	global_load_lds_dwordx4 v166, s[50:51]
	s_mov_b32 m0, s65
	s_nop 0
	global_load_lds_dwordx4 v162, s[50:51]
	s_add_u32 s78, s48, 0x80000
	s_addc_u32 s79, s49, 0
	s_add_i32 s59, s73, s62
	s_waitcnt vmcnt(6)
	s_waitcnt lgkmcnt(0)
	s_setprio 1
	s_barrier
	v_mfma_f32_16x16x32_bf16 v[60:63], v[64:67], v[120:123], v[60:63]
	s_mov_b32 m0, s59
	v_mfma_f32_16x16x32_bf16 v[48:51], v[72:75], v[120:123], v[48:51]
	global_load_lds_dwordx4 v164, s[78:79]
	v_mfma_f32_16x16x32_bf16 v[44:47], v[64:67], v[136:139], v[44:47]
	s_bitset1_b32 m0, 13
	v_mfma_f32_16x16x32_bf16 v[36:39], v[72:75], v[136:139], v[36:39]
	global_load_lds_dwordx4 v160, s[78:79]
	v_mfma_f32_16x16x32_bf16 v[28:31], v[64:67], v[180:183], v[28:31]
	v_mfma_f32_16x16x32_bf16 v[20:23], v[72:75], v[180:183], v[20:23]
	v_mfma_f32_16x16x32_bf16 v[16:19], v[64:67], v[188:191], v[16:19]
	v_mfma_f32_16x16x32_bf16 v[12:15], v[72:75], v[188:191], v[12:15]
	v_mfma_f32_16x16x32_bf16 v[60:63], v[68:71], v[128:131], v[60:63]
	v_mfma_f32_16x16x32_bf16 v[48:51], v[76:79], v[128:131], v[48:51]
	v_mfma_f32_16x16x32_bf16 v[44:47], v[68:71], v[148:151], v[44:47]
	v_mfma_f32_16x16x32_bf16 v[36:39], v[76:79], v[148:151], v[36:39]
	v_mfma_f32_16x16x32_bf16 v[28:31], v[68:71], v[184:187], v[28:31]
	v_mfma_f32_16x16x32_bf16 v[20:23], v[76:79], v[184:187], v[20:23]
	v_mfma_f32_16x16x32_bf16 v[16:19], v[68:71], v[192:195], v[16:19]
	v_mfma_f32_16x16x32_bf16 v[12:15], v[76:79], v[192:195], v[12:15]
	v_mfma_f32_16x16x32_bf16 v[56:59], v[206:209], v[120:123], v[56:59]
	v_mfma_f32_16x16x32_bf16 v[52:55], v[216:219], v[120:123], v[52:55]
	v_mfma_f32_16x16x32_bf16 v[40:43], v[206:209], v[136:139], v[40:43]
	v_mfma_f32_16x16x32_bf16 v[32:35], v[216:219], v[136:139], v[32:35]
	v_mfma_f32_16x16x32_bf16 v[24:27], v[206:209], v[180:183], v[24:27]
	v_mfma_f32_16x16x32_bf16 v[8:11], v[216:219], v[180:183], v[8:11]
	v_mfma_f32_16x16x32_bf16 v[4:7], v[206:209], v[188:191], v[4:7]
	v_mfma_f32_16x16x32_bf16 v[0:3], v[216:219], v[188:191], v[0:3]
	v_mfma_f32_16x16x32_bf16 v[56:59], v[212:215], v[128:131], v[56:59]
	v_mfma_f32_16x16x32_bf16 v[52:55], v[220:223], v[128:131], v[52:55]
	v_mfma_f32_16x16x32_bf16 v[40:43], v[212:215], v[148:151], v[40:43]
	v_mfma_f32_16x16x32_bf16 v[32:35], v[220:223], v[148:151], v[32:35]
	v_mfma_f32_16x16x32_bf16 v[24:27], v[212:215], v[184:187], v[24:27]
	v_mfma_f32_16x16x32_bf16 v[8:11], v[220:223], v[184:187], v[8:11]
	v_mfma_f32_16x16x32_bf16 v[4:7], v[212:215], v[192:195], v[4:7]
	v_mfma_f32_16x16x32_bf16 v[0:3], v[220:223], v[192:195], v[0:3]
	s_barrier
; #define PG8_STAGE(bufoff, gbase, voff) do { _Pragma("unroll") for (int _i = 0; _i < 2; ++_i) \
;     __builtin_amdgcn_global_load_lds((const unsigned*)((const char*)(gbase) + (voff)[_i]), (LAS unsigned*)(lds + (bufoff) + ldsw + _i * 8192), 16, 0, 0); } while (0)
; #define PG8_LDA(dst, b, h) do { _Pragma("unroll") for (int m = 0; m < 4; ++m) _Pragma("unroll") for (int k = 0; k < 2; ++k) dst[m][k] = *(const LAS bf16x8*)(lds + PG8_SA(b, h) + aoff + m * 2048 + k * 1024); } while (0)
; #define PG8_LDB(dst, b, h) do { _Pragma("unroll") for (int n = 0; n < 2; ++n) _Pragma("unroll") for (int k = 0; k < 2; ++k) dst[n][k] = *(const LAS bf16x8*)(lds + PG8_SB(b, h) + boff + n * 2048 + k * 1024); } while (0)
; #define PG8_MMA(ai, bj, At, Bt) do { __builtin_amdgcn_s_setprio(1); _Pragma("unroll") for (int m = 0; m < 4; ++m) _Pragma("unroll") for (int n = 0; n < 2; ++n) _Pragma("unroll") for (int k = 0; k < 2; ++k) \
;     acc[ai][bj][m][n] = __builtin_amdgcn_mfma_f32_16x16x32_bf16(Bt[n][k], At[m][k], acc[ai][bj][m][n], 0, 0, 0); __builtin_amdgcn_s_setprio(0); } while (0)
; #define PG8_WAIT_V(n) asm volatile("s_waitcnt vmcnt(" #n ")" ::: "memory")
; #define PG8_WAIT_L(n) asm volatile("s_waitcnt lgkmcnt(" #n ")" ::: "memory")
; #define PG8_BAR __builtin_amdgcn_s_barrier()
; #define PG8_SCHED __builtin_amdgcn_sched_barrier(0)
; template <class Epi, class Sched = StaticOrder>
; DI void gemm_phase(LAS unsigned char* lds, const Gemm g, const Sched& S, const Epi& E) {
;     ...
;       PG8_LDB(B0, 1, 0); PG8_SCHED; PG8_LDA(At, 1, 0); PG8_STAGE(PG8_SA(0, 1), a2 + hstep, voffA);
;       PG8_WAIT_L(8); PG8_BAR; PG8_WAIT_L(0); PG8_MMA(0, 0, At, B0); PG8_BAR; PG8_SCHED;
;       PG8_LDB(B1, 1, 1); PG8_STAGE(PG8_SB(1, 0), b3, voffB);
;       PG8_BAR; PG8_WAIT_L(0); PG8_MMA(0, 1, At, B1); PG8_BAR;
;       PG8_LDA(At, 1, 1); PG8_STAGE(PG8_SA(1, 0), a3, voffA);
;       PG8_BAR; PG8_WAIT_L(0); PG8_MMA(1, 0, At, B0); PG8_BAR; PG8_SCHED;
;       PG8_STAGE(PG8_SB(1, 1), b3 + hstep, voffB);
;       PG8_WAIT_V(6); PG8_BAR; PG8_MMA(1, 1, At, B1); PG8_BAR;
	s_setprio 0
	s_add_i32 s59, 0, 0x18000
	v_add_u32_e32 v76, s59, v198
	ds_read_b128 v[64:67], v76
	ds_read_b128 v[68:71], v76 offset:1024
	ds_read_b128 v[72:75], v76 offset:2048
	ds_read_b128 v[76:79], v76 offset:3072
	s_add_u32 s50, s50, 0x80000
	s_addc_u32 s51, s51, 0
	s_mov_b32 m0, s66
	ds_read_b128 v[120:123], v202 offset:32768
	ds_read_b128 v[128:131], v202 offset:33792
	ds_read_b128 v[180:183], v202 offset:34816
	ds_read_b128 v[184:187], v202 offset:35840
	ds_read_b128 v[188:191], v202 offset:36864
	ds_read_b128 v[192:195], v202 offset:37888
	ds_read_b128 v[206:209], v202 offset:38912
	ds_read_b128 v[212:215], v202 offset:39936
	global_load_lds_dwordx4 v166, s[50:51]
	s_mov_b32 m0, s67
	s_nop 0
	global_load_lds_dwordx4 v162, s[50:51]
	s_add_i32 s50, 0, 0x1c000
	v_add_u32_e32 v244, s50, v198
	ds_read_b128 v[216:219], v244
	ds_read_b128 v[220:223], v244 offset:1024
	ds_read_b128 v[224:227], v244 offset:2048
	ds_read_b128 v[228:231], v244 offset:3072
	s_waitcnt vmcnt(8)
	s_waitcnt lgkmcnt(4)
	s_setprio 1
	s_barrier
	v_mfma_f32_16x16x32_bf16 v[136:139], v[64:67], v[120:123], v[156:159]
	v_mfma_f32_16x16x32_bf16 v[156:159], v[68:71], v[128:131], v[136:139]
	v_mfma_f32_16x16x32_bf16 v[136:139], v[72:75], v[120:123], v[144:147]
	v_mfma_f32_16x16x32_bf16 v[144:147], v[76:79], v[128:131], v[136:139]
	v_mfma_f32_16x16x32_bf16 v[136:139], v[64:67], v[180:183], v[140:143]
	v_mfma_f32_16x16x32_bf16 v[132:135], v[72:75], v[180:183], v[132:135]
	v_mfma_f32_16x16x32_bf16 v[124:127], v[64:67], v[188:191], v[124:127]
	v_mfma_f32_16x16x32_bf16 v[116:119], v[72:75], v[188:191], v[116:119]
	v_mfma_f32_16x16x32_bf16 v[112:115], v[64:67], v[206:209], v[112:115]
	v_mfma_f32_16x16x32_bf16 v[108:111], v[72:75], v[206:209], v[108:111]
	v_mfma_f32_16x16x32_bf16 v[140:143], v[68:71], v[184:187], v[136:139]
	v_mfma_f32_16x16x32_bf16 v[132:135], v[76:79], v[184:187], v[132:135]
	v_mfma_f32_16x16x32_bf16 v[124:127], v[68:71], v[192:195], v[124:127]
	v_mfma_f32_16x16x32_bf16 v[116:119], v[76:79], v[192:195], v[116:119]
	v_mfma_f32_16x16x32_bf16 v[112:115], v[68:71], v[212:215], v[112:115]
	v_mfma_f32_16x16x32_bf16 v[108:111], v[76:79], v[212:215], v[108:111]
	s_waitcnt lgkmcnt(0)
	v_mfma_f32_16x16x32_bf16 v[80:83], v[224:227], v[120:123], v[80:83]
	v_mfma_f32_16x16x32_bf16 v[136:139], v[216:219], v[120:123], v[152:155]
	v_mfma_f32_16x16x32_bf16 v[148:151], v[228:231], v[128:131], v[80:83]
	v_mfma_f32_16x16x32_bf16 v[80:83], v[216:219], v[180:183], v[84:87]
	v_mfma_f32_16x16x32_bf16 v[152:155], v[220:223], v[128:131], v[136:139]
	v_mfma_f32_16x16x32_bf16 v[136:139], v[220:223], v[184:187], v[80:83]
	v_mfma_f32_16x16x32_bf16 v[80:83], v[224:227], v[180:183], v[88:91]
	v_mfma_f32_16x16x32_bf16 v[128:131], v[228:231], v[184:187], v[80:83]
	v_mfma_f32_16x16x32_bf16 v[80:83], v[216:219], v[188:191], v[92:95]
	v_mfma_f32_16x16x32_bf16 v[120:123], v[220:223], v[192:195], v[80:83]
	v_mfma_f32_16x16x32_bf16 v[80:83], v[224:227], v[188:191], v[104:107]
	v_mfma_f32_16x16x32_bf16 v[104:107], v[228:231], v[192:195], v[80:83]
	v_mfma_f32_16x16x32_bf16 v[80:83], v[216:219], v[206:209], v[100:103]
	v_mfma_f32_16x16x32_bf16 v[100:103], v[220:223], v[212:215], v[80:83]
	v_mfma_f32_16x16x32_bf16 v[80:83], v[224:227], v[206:209], v[96:99]
	v_mfma_f32_16x16x32_bf16 v[96:99], v[228:231], v[212:215], v[80:83]
	s_barrier
	s_setprio 0
	s_add_i32 s51, s59, s62
	s_mov_b32 m0, s51
	s_nop 0
	global_load_lds_dwordx4 v164, s[98:99]
	s_add_i32 m0, s51, 0x2000
	s_nop 0
	global_load_lds_dwordx4 v160, s[98:99]
	s_mov_b32 m0, s55
	s_nop 2
	ds_read_b128 v[80:83], v202 offset:49152
	ds_read_b128 v[84:87], v202 offset:50176
	ds_read_b128 v[88:91], v202 offset:51200
	ds_read_b128 v[92:95], v202 offset:52224
	ds_read_b128 v[180:183], v202 offset:53248
	ds_read_b128 v[184:187], v202 offset:54272
	ds_read_b128 v[188:191], v202 offset:55296
	ds_read_b128 v[192:195], v202 offset:56320
	global_load_lds_dwordx4 v166, s[100:101]
	s_mov_b32 m0, s68
	s_nop 0
	global_load_lds_dwordx4 v162, s[100:101]
	s_add_u32 s48, s48, 0x80080
	s_addc_u32 s49, s49, 0
	s_add_i32 s50, s50, s62
	s_add_i32 s58, s58, 2
	s_add_u32 s14, s14, 0x100
	s_addc_u32 s15, s15, 0
	s_add_u32 s52, s52, 0x100
	s_addc_u32 s53, s53, 0
	s_cmp_gt_u32 s58, 29
	s_waitcnt vmcnt(6)
	s_waitcnt lgkmcnt(0)
	s_setprio 1
	s_barrier
	v_mfma_f32_16x16x32_bf16 v[60:63], v[64:67], v[80:83], v[60:63]
	s_mov_b32 m0, s50
	v_mfma_f32_16x16x32_bf16 v[48:51], v[72:75], v[80:83], v[48:51]
	global_load_lds_dwordx4 v164, s[48:49]
	v_mfma_f32_16x16x32_bf16 v[44:47], v[64:67], v[88:91], v[44:47]
	s_bitset1_b32 m0, 13
	v_mfma_f32_16x16x32_bf16 v[36:39], v[72:75], v[88:91], v[36:39]
	global_load_lds_dwordx4 v160, s[48:49]
	v_mfma_f32_16x16x32_bf16 v[28:31], v[64:67], v[180:183], v[28:31]
	v_mfma_f32_16x16x32_bf16 v[20:23], v[72:75], v[180:183], v[20:23]
	v_mfma_f32_16x16x32_bf16 v[16:19], v[64:67], v[188:191], v[16:19]
	v_mfma_f32_16x16x32_bf16 v[12:15], v[72:75], v[188:191], v[12:15]
	v_mfma_f32_16x16x32_bf16 v[60:63], v[68:71], v[84:87], v[60:63]
	v_mfma_f32_16x16x32_bf16 v[48:51], v[76:79], v[84:87], v[48:51]
	v_mfma_f32_16x16x32_bf16 v[44:47], v[68:71], v[92:95], v[44:47]
	v_mfma_f32_16x16x32_bf16 v[36:39], v[76:79], v[92:95], v[36:39]
	v_mfma_f32_16x16x32_bf16 v[28:31], v[68:71], v[184:187], v[28:31]
	v_mfma_f32_16x16x32_bf16 v[20:23], v[76:79], v[184:187], v[20:23]
	v_mfma_f32_16x16x32_bf16 v[16:19], v[68:71], v[192:195], v[16:19]
	v_mfma_f32_16x16x32_bf16 v[12:15], v[76:79], v[192:195], v[12:15]
	v_mfma_f32_16x16x32_bf16 v[56:59], v[216:219], v[80:83], v[56:59]
	v_mfma_f32_16x16x32_bf16 v[52:55], v[224:227], v[80:83], v[52:55]
	v_mfma_f32_16x16x32_bf16 v[40:43], v[216:219], v[88:91], v[40:43]
	v_mfma_f32_16x16x32_bf16 v[32:35], v[224:227], v[88:91], v[32:35]
	v_mfma_f32_16x16x32_bf16 v[24:27], v[216:219], v[180:183], v[24:27]
	v_mfma_f32_16x16x32_bf16 v[8:11], v[224:227], v[180:183], v[8:11]
	v_mfma_f32_16x16x32_bf16 v[4:7], v[216:219], v[188:191], v[4:7]
	v_mfma_f32_16x16x32_bf16 v[0:3], v[224:227], v[188:191], v[0:3]
	v_mfma_f32_16x16x32_bf16 v[56:59], v[220:223], v[84:87], v[56:59]
	v_mfma_f32_16x16x32_bf16 v[52:55], v[228:231], v[84:87], v[52:55]
	v_mfma_f32_16x16x32_bf16 v[40:43], v[220:223], v[92:95], v[40:43]
	v_mfma_f32_16x16x32_bf16 v[32:35], v[228:231], v[92:95], v[32:35]
	v_mfma_f32_16x16x32_bf16 v[24:27], v[220:223], v[184:187], v[24:27]
	v_mfma_f32_16x16x32_bf16 v[8:11], v[228:231], v[184:187], v[8:11]
	v_mfma_f32_16x16x32_bf16 v[4:7], v[220:223], v[192:195], v[4:7]
	v_mfma_f32_16x16x32_bf16 v[0:3], v[228:231], v[192:195], v[0:3]
	s_barrier
; DI float dpp_ror1(float v) { return __int_as_float(__builtin_amdgcn_update_dpp(0, __float_as_int(v), 0x121, 0xf, 0xf, false)); }
; DI float dpp_ror2(float v) { return __int_as_float(__builtin_amdgcn_update_dpp(0, __float_as_int(v), 0x122, 0xf, 0xf, false)); }
; DI float row_rstd(const float* ssq, int row, int fq) {
;   const f32x4 a = *(const f32x4*)(ssq + (size_t)row * 32 + fq * 8), b = *(const f32x4*)(ssq + (size_t)row * 32 + fq * 8 + 4);
;   float sm = ((a[0] + a[1]) + (a[2] + a[3])) + ((b[0] + b[1]) + (b[2] + b[3]));
;   sm += __shfl_xor(sm, 16); sm += __shfl_xor(sm, 32);
;   return rsqrtf(sm * (1.0f / 2048.f) + 1e-6f);
;   DI void operator()(const f32x4 (&acc)[2][2][4][2], const Unit& u, int wr, int wc, int fr, int fq) const {
;     const int col = u.pn * 128 + wc * 32 + 8 * fq;
;     float w0[8], w1[8], w2[8], bb[8];
; #pragma unroll
;     for (int e = 0; e < 8; ++e) { w0[e] = cw[col + e]; w1[e] = cw[5632 + col + e]; w2[e] = cw[2 * 5632 + col + e]; bb[e] = cb[col + e]; }
; #pragma unroll
;     for (int ai = 0; ai < 2; ++ai) {
;       const int row0 = u.pm * BM + ai * HALF + wr * 64, span = row0 >> 6;
;       float rsv[4];
; #pragma unroll
;       for (int m = 0; m < 4; ++m) rsv[m] = row_rstd(ssq, row0 + 16 * m + fr, fq);
;       float p1[8], p2[8];
; #pragma unroll
;       for (int e = 0; e < 8; ++e) { p1[e] = 0.f; p2[e] = 0.f; }
; #pragma unroll
;       for (int m = 0; m < 4; ++m) {
;         float g[8], uu[8], a[8];
;         const float rs = rsv[m];
; #pragma unroll
;         for (int e = 0; e < 4; ++e) { g[e] = acc[ai][0][m][0][e] * rs; g[4 + e] = acc[ai][0][m][1][e] * rs; uu[e] = acc[ai][1][m][0][e] * rs; uu[4 + e] = acc[ai][1][m][1][e] * rs; }
; #pragma unroll
;         for (int e = 0; e < 8; ++e) {
;           const float x1 = dpp_ror1(g[e]), x2 = dpp_ror2(g[e]);
;           const float pr1 = (fr == 0) ? p1[e] : x1, pr2 = (fr < 2) ? p2[e] : x2;
;           a[e] = w2[e] * g[e] + w1[e] * pr1 + w0[e] * pr2 + bb[e];
;           p1[e] = x1; p2[e] = x2;
;         }
	s_setprio 0
	s_cbranch_scc0 .LBB0_1277
	s_lshl_b32 s39, s12, 8
	s_add_i32 s39, s39, s54
	v_or_b32_e32 v190, s39, v179
	v_ashrrev_i32_e32 v191, 31, v190
	v_lshlrev_b64 v[64:65], 7, v[190:191]
	v_or_b32_e32 v188, 16, v190
	v_lshl_add_u64 v[64:65], v[168:169], 0, v[64:65]
	v_ashrrev_i32_e32 v189, 31, v188
	global_load_dwordx4 v[192:195], v[64:65], off
	global_load_dwordx4 v[206:209], v[64:65], off offset:16
	v_lshlrev_b64 v[64:65], 7, v[188:189]
	v_lshl_add_u64 v[64:65], v[168:169], 0, v[64:65]
	global_load_dwordx4 v[212:215], v[64:65], off
	global_load_dwordx4 v[216:219], v[64:65], off offset:16
	v_or_b32_e32 v186, 32, v190
	v_ashrrev_i32_e32 v187, 31, v186
	v_lshlrev_b64 v[64:65], 7, v[186:187]
	v_or_b32_e32 v184, 48, v190
	v_lshl_add_u64 v[64:65], v[168:169], 0, v[64:65]
	v_ashrrev_i32_e32 v185, 31, v184
	global_load_dwordx4 v[220:223], v[64:65], off
	global_load_dwordx4 v[224:227], v[64:65], off offset:16
	v_lshlrev_b64 v[64:65], 7, v[184:185]
	v_lshl_add_u64 v[64:65], v[168:169], 0, v[64:65]
	global_load_dwordx4 v[228:231], v[64:65], off
	global_load_dwordx4 v[232:235], v[64:65], off offset:16
	v_lshl_or_b32 v180, s13, 7, v200
	v_and_b32_e32 v65, 64, v204
	v_xor_b32_e32 v64, 16, v204
	v_ashrrev_i32_e32 v181, 31, v180
	v_add_u32_e32 v65, 64, v65
	v_xor_b32_e32 v66, 32, v204
	v_lshlrev_b64 v[182:183], 2, v[180:181]
	v_cmp_lt_i32_e32 vcc, v64, v65
	v_lshl_add_u64 v[88:89], s[16:17], 0, v[182:183]
	v_lshl_add_u64 v[72:73], s[18:19], 0, v[182:183]
	v_cndmask_b32_e32 v64, v204, v64, vcc
	v_cmp_lt_i32_e32 vcc, v66, v65
	v_lshl_add_u64 v[74:75], v[88:89], 0, s[30:31]
	v_lshl_add_u64 v[76:77], v[88:89], 0, s[34:35]
	v_cndmask_b32_e32 v65, v204, v66, vcc
	v_add_co_u32_e32 v90, vcc, 0x5000, v88
	v_lshlrev_b32_e32 v187, 2, v64
	s_nop 0
	v_addc_co_u32_e32 v91, vcc, 0, v89, vcc
	v_add_co_u32_e32 v92, vcc, 0xb000, v88
	v_lshlrev_b32_e32 v185, 2, v65
	s_nop 0
	v_addc_co_u32_e32 v93, vcc, 0, v89, vcc
	global_load_dwordx4 v[64:67], v[88:89], off offset:16
	global_load_dwordx4 v[80:83], v[88:89], off
	global_load_dwordx4 v[68:71], v[72:73], off offset:16
	global_load_dwordx4 v[84:87], v[72:73], off
	s_nop 0
	global_load_dwordx4 v[72:75], v[74:75], off offset:16
	s_nop 0
	global_load_dwordx4 v[76:79], v[76:77], off offset:16
	s_nop 0
	global_load_dwordx4 v[88:91], v[90:91], off offset:2048
	s_nop 0
	global_load_dwordx4 v[92:95], v[92:93], off
	v_mov_b32_e32 v211, 0
	v_mov_b32_e32 v205, 0
	s_waitcnt vmcnt(0)
	v_mov_b32_e32 v196, v192
	v_mov_b32_e32 v197, v206
	v_mov_b32_e32 v206, v193
	v_mov_b32_e32 v192, v194
	v_mov_b32_e32 v193, v208
	v_mov_b32_e32 v208, v195
	v_pk_add_f32 v[194:195], v[196:197], v[206:207]
	v_pk_add_f32 v[192:193], v[192:193], v[208:209]
	v_mov_b32_e32 v196, v212
	v_mov_b32_e32 v197, v216
	v_mov_b32_e32 v216, v213
	v_mov_b32_e32 v206, v214
	v_mov_b32_e32 v207, v218
	v_mov_b32_e32 v218, v215
	v_pk_add_f32 v[192:193], v[194:195], v[192:193]
	v_pk_add_f32 v[194:195], v[196:197], v[216:217]
	v_pk_add_f32 v[196:197], v[206:207], v[218:219]
	v_mov_b32_e32 v208, v220
	v_pk_add_f32 v[194:195], v[194:195], v[196:197]
	v_mov_b32_e32 v197, v192
	v_mov_b32_e32 v196, v194
	v_mov_b32_e32 v192, v195
	v_pk_add_f32 v[192:193], v[196:197], v[192:193]
	ds_bpermute_b32 v195, v187, v193
	ds_bpermute_b32 v194, v187, v192
	v_mov_b32_e32 v209, v224
	v_mov_b32_e32 v224, v221
	v_mov_b32_e32 v212, v222
	v_mov_b32_e32 v213, v226
	s_waitcnt lgkmcnt(0)
	v_pk_add_f32 v[192:193], v[192:193], v[194:195]
	ds_bpermute_b32 v195, v185, v193
	ds_bpermute_b32 v194, v185, v192
	v_mov_b32_e32 v226, v223
	v_mov_b32_e32 v196, v228
	v_mov_b32_e32 v197, v232
	v_mov_b32_e32 v232, v229
	s_waitcnt lgkmcnt(0)
	v_pk_add_f32 v[192:193], v[192:193], v[194:195]
	v_mov_b32_e32 v206, v230
	v_pk_fma_f32 v[192:193], v[192:193], s[36:37], v[178:179] op_sel_hi:[1,0,0]
	v_mov_b32_e32 v207, v234
	v_mul_f32_e32 v189, 0x4b800000, v193
	v_cmp_gt_f32_e64 s[12:13], s74, v193
	v_mov_b32_e32 v234, v231
	v_pk_add_f32 v[208:209], v[208:209], v[224:225]
	v_cndmask_b32_e64 v189, v193, v189, s[12:13]
	v_rsq_f32_e32 v189, v189
	v_pk_add_f32 v[212:213], v[212:213], v[226:227]
	v_pk_add_f32 v[196:197], v[196:197], v[232:233]
	v_pk_add_f32 v[194:195], v[206:207], v[234:235]
	v_mul_f32_e32 v191, 0x45800000, v189
	v_cndmask_b32_e64 v220, v189, v191, s[12:13]
	v_pk_add_f32 v[208:209], v[208:209], v[212:213]
	v_pk_add_f32 v[194:195], v[196:197], v[194:195]
	v_pk_mul_f32 v[156:157], v[156:157], v[220:221] op_sel_hi:[1,0]
	v_mov_b32_e32 v216, 0
	v_mov_b32_e32 v218, 0
	v_mov_b32_e32 v196, v194
	v_mov_b32_e32 v197, v208
	v_mov_b32_e32 v208, v195
	v_mov_b32_dpp v216, v156 row_ror:1 row_mask:0xf bank_mask:0xf
	v_mov_b32_dpp v218, v157 row_ror:1 row_mask:0xf bank_mask:0xf
	v_pk_add_f32 v[194:195], v[196:197], v[208:209]
	v_cndmask_b32_e64 v207, v218, 0, s[0:1]
	v_cndmask_b32_e64 v206, v216, 0, s[0:1]
	v_pk_mul_f32 v[158:159], v[158:159], v[220:221] op_sel_hi:[1,0]
	v_mov_b32_e32 v212, 0
	v_mov_b32_e32 v214, 0
	ds_bpermute_b32 v197, v187, v195
	ds_bpermute_b32 v196, v187, v194
	v_mov_b32_e32 v215, 0
	v_mov_b32_e32 v217, 0
	v_pk_mul_f32 v[206:207], v[88:89], v[206:207]
	v_mov_b32_dpp v212, v158 row_ror:1 row_mask:0xf bank_mask:0xf
	v_mov_b32_dpp v214, v159 row_ror:1 row_mask:0xf bank_mask:0xf
	v_mov_b32_dpp v215, v156 row_ror:2 row_mask:0xf bank_mask:0xf
	v_mov_b32_dpp v217, v157 row_ror:2 row_mask:0xf bank_mask:0xf
	v_pk_fma_f32 v[156:157], v[92:93], v[156:157], v[206:207]
	v_mov_b32_e32 v213, 0
	v_cndmask_b32_e64 v207, v214, 0, s[0:1]
	v_cndmask_b32_e64 v206, v212, 0, s[0:1]
	v_cndmask_b32_e64 v209, v217, 0, s[4:5]
	v_cndmask_b32_e64 v208, v215, 0, s[4:5]
	v_mov_b32_dpp v211, v158 row_ror:2 row_mask:0xf bank_mask:0xf
	v_mov_b32_dpp v213, v159 row_ror:2 row_mask:0xf bank_mask:0xf
	v_pk_mul_f32 v[206:207], v[90:91], v[206:207]
	v_pk_fma_f32 v[156:157], v[80:81], v[208:209], v[156:157]
	v_cndmask_b32_e64 v209, v213, 0, s[4:5]
	v_cndmask_b32_e64 v208, v211, 0, s[4:5]
	v_pk_fma_f32 v[158:159], v[94:95], v[158:159], v[206:207]
	v_pk_mul_f32 v[144:145], v[144:145], v[220:221] op_sel_hi:[1,0]
	v_pk_fma_f32 v[158:159], v[82:83], v[208:209], v[158:159]
	v_mov_b32_e32 v207, 0
	v_mov_b32_e32 v209, 0
	v_pk_mul_f32 v[146:147], v[146:147], v[220:221] op_sel_hi:[1,0]
	v_mov_b32_e32 v191, 0
	s_waitcnt lgkmcnt(0)
; DI unsigned pack2(float lo, float hi) { f32x2 v = {lo, hi}; bf16v2 r = __builtin_convertvector(v, bf16v2); return __builtin_bit_cast(unsigned, r); }
; DI float silu_f(float x) { return x * sigmoid_f(x); }
; DI float dpp_ror1(float v) { return __int_as_float(__builtin_amdgcn_update_dpp(0, __float_as_int(v), 0x121, 0xf, 0xf, false)); }
; DI float dpp_ror2(float v) { return __int_as_float(__builtin_amdgcn_update_dpp(0, __float_as_int(v), 0x122, 0xf, 0xf, false)); }
;   DI void operator()(const f32x4 (&acc)[2][2][4][2], const Unit& u, int wr, int wc, int fr, int fq) const {
;     ...
;       for (int m = 0; m < 4; ++m) {
;         float g[8], uu[8], a[8];
;         const float rs = rsv[m];
; #pragma unroll
;         for (int e = 0; e < 4; ++e) { g[e] = acc[ai][0][m][0][e] * rs; g[4 + e] = acc[ai][0][m][1][e] * rs; uu[e] = acc[ai][1][m][0][e] * rs; uu[4 + e] = acc[ai][1][m][1][e] * rs; }
; #pragma unroll
;         for (int e = 0; e < 8; ++e) {
;           const float x1 = dpp_ror1(g[e]), x2 = dpp_ror2(g[e]);
;           const float pr1 = (fr == 0) ? p1[e] : x1, pr2 = (fr < 2) ? p2[e] : x2;
;           a[e] = w2[e] * g[e] + w1[e] * pr1 + w0[e] * pr2 + bb[e];
;           p1[e] = x1; p2[e] = x2;
;         }
;         if (m == 0 && fr < 2) {
;           float* ha = headA + (size_t)(span * 2 + fr) * 5632 + col; float* hu = headU + (size_t)(span * 2 + fr) * 5632 + col;
;           *(f32x4*)ha = (f32x4){a[0], a[1], a[2], a[3]}; *(f32x4*)(ha + 4) = (f32x4){a[4], a[5], a[6], a[7]};
;           *(f32x4*)hu = (f32x4){uu[0], uu[1], uu[2], uu[3]}; *(f32x4*)(hu + 4) = (f32x4){uu[4], uu[5], uu[6], uu[7]};
;         } else {
;           u32x4 w;
;           w.x = pack2(silu_f(a[0]) * uu[0], silu_f(a[1]) * uu[1]);
;           w.y = pack2(silu_f(a[2]) * uu[2], silu_f(a[3]) * uu[3]);
;           w.z = pack2(silu_f(a[4]) * uu[4], silu_f(a[5]) * uu[5]);
;           w.w = pack2(silu_f(a[6]) * uu[6], silu_f(a[7]) * uu[7]);
;           *(u32x4*)(H + (size_t)(row0 + 16 * m + fr) * 5632 + col) = w;
;         }
	v_pk_add_f32 v[194:195], v[194:195], v[196:197]
	v_mov_b32_dpp v207, v144 row_ror:1 row_mask:0xf bank_mask:0xf
	v_mov_b32_dpp v209, v145 row_ror:1 row_mask:0xf bank_mask:0xf
	v_mov_b32_dpp v191, v146 row_ror:1 row_mask:0xf bank_mask:0xf
	v_mov_b32_dpp v205, v147 row_ror:1 row_mask:0xf bank_mask:0xf
	ds_bpermute_b32 v197, v185, v195
	ds_bpermute_b32 v196, v185, v194
	v_pk_mul_f32 v[152:153], v[152:153], v[220:221] op_sel_hi:[1,0]
	v_pk_mul_f32 v[148:149], v[148:149], v[220:221] op_sel_hi:[1,0]
	v_pk_mul_f32 v[154:155], v[154:155], v[220:221] op_sel_hi:[1,0]
	v_pk_mul_f32 v[150:151], v[150:151], v[220:221] op_sel_hi:[1,0]
	v_mov_b32_e32 v206, 0
	v_mov_b32_e32 v208, 0
	v_cndmask_b32_e64 v223, v209, 0, s[0:1]
	v_cndmask_b32_e64 v222, v207, 0, s[0:1]
	v_mov_b32_e32 v189, 0
	v_mov_b32_e32 v193, 0
	v_cndmask_b32_e64 v221, v205, 0, s[0:1]
	v_cndmask_b32_e64 v220, v191, 0, s[0:1]
	v_mov_b32_dpp v206, v144 row_ror:2 row_mask:0xf bank_mask:0xf
	v_mov_b32_dpp v208, v145 row_ror:2 row_mask:0xf bank_mask:0xf
	v_pk_mul_f32 v[222:223], v[72:73], v[222:223]
	v_mov_b32_dpp v189, v146 row_ror:2 row_mask:0xf bank_mask:0xf
	v_mov_b32_dpp v193, v147 row_ror:2 row_mask:0xf bank_mask:0xf
	v_pk_mul_f32 v[220:221], v[74:75], v[220:221]
	v_cndmask_b32_e64 v225, v208, 0, s[4:5]
	v_cndmask_b32_e64 v224, v206, 0, s[4:5]
	v_pk_fma_f32 v[144:145], v[76:77], v[144:145], v[222:223]
	v_cndmask_b32_e64 v223, v193, 0, s[4:5]
	v_cndmask_b32_e64 v222, v189, 0, s[4:5]
	v_pk_fma_f32 v[146:147], v[78:79], v[146:147], v[220:221]
	v_pk_fma_f32 v[144:145], v[64:65], v[224:225], v[144:145]
	v_pk_fma_f32 v[146:147], v[66:67], v[222:223], v[146:147]
	v_cmp_gt_f32_e32 vcc, s74, v192
	v_pk_add_f32 v[156:157], v[84:85], v[156:157]
	v_pk_add_f32 v[158:159], v[86:87], v[158:159]
	v_pk_add_f32 v[144:145], v[68:69], v[144:145]
	v_pk_add_f32 v[146:147], v[70:71], v[146:147]
	s_and_saveexec_b64 s[12:13], s[10:11]
	s_xor_b64 s[12:13], exec, s[12:13]
	s_cbranch_execz .LBB0_1280
	v_mul_f32_e32 v219, 0xbfb8aa3b, v156
	v_exp_f32_e32 v219, v219
	v_mul_f32_e32 v220, 0xbfb8aa3b, v157
	v_exp_f32_e32 v220, v220
	v_mul_f32_e32 v222, 0xbfb8aa3b, v159
	v_add_f32_e32 v219, 1.0, v219
	v_exp_f32_e32 v223, v222
	v_add_f32_e32 v221, 1.0, v220
	v_rcp_f32_e32 v220, v219
	v_mul_f32_e32 v219, 0xbfb8aa3b, v158
	v_exp_f32_e32 v219, v219
	v_rcp_f32_e32 v221, v221
	v_add_f32_e32 v219, 1.0, v219
	v_rcp_f32_e32 v222, v219
	v_add_f32_e32 v219, 1.0, v223
	v_rcp_f32_e32 v223, v219
	v_pk_mul_f32 v[156:157], v[156:157], v[220:221]
	s_nop 0
	v_pk_mul_f32 v[152:153], v[152:153], v[156:157]
	v_pk_mul_f32 v[156:157], v[158:159], v[222:223]
	v_cvt_pk_bf16_f32 v152, v152, v153
	v_mul_f32_e32 v153, 0xbfb8aa3b, v144
	v_pk_mul_f32 v[154:155], v[154:155], v[156:157]
	v_exp_f32_e32 v156, v153
	v_mul_f32_e32 v153, 0xbfb8aa3b, v145
	v_exp_f32_e32 v157, v153
	v_cvt_pk_bf16_f32 v153, v154, v155
	v_add_f32_e32 v154, 1.0, v156
	v_mul_f32_e32 v156, 0xbfb8aa3b, v146
	v_add_f32_e32 v155, 1.0, v157
	v_mul_f32_e32 v157, 0xbfb8aa3b, v147
	v_exp_f32_e32 v156, v156
	v_exp_f32_e32 v157, v157
	v_rcp_f32_e32 v154, v154
	v_rcp_f32_e32 v155, v155
	v_add_f32_e32 v156, 1.0, v156
	v_add_f32_e32 v157, 1.0, v157
	v_rcp_f32_e32 v156, v156
	v_rcp_f32_e32 v157, v157
	v_pk_mul_f32 v[144:145], v[144:145], v[154:155]
	s_nop 0
	v_pk_mul_f32 v[144:145], v[148:149], v[144:145]
	s_nop 0
	v_cvt_pk_bf16_f32 v154, v144, v145
	v_pk_mul_f32 v[144:145], v[146:147], v[156:157]
	s_nop 0
	v_pk_mul_f32 v[144:145], v[150:151], v[144:145]
	s_nop 0
	v_cvt_pk_bf16_f32 v155, v144, v145
	v_mov_b64_e32 v[144:145], s[20:21]
	v_mad_i64_i32 v[144:145], s[14:15], v190, s75, v[144:145]
	v_lshl_add_u64 v[144:145], v[180:181], 1, v[144:145]
	global_store_dwordx4 v[144:145], v[152:155], off

; #define PG8_STAGE(bufoff, gbase, voff) do { _Pragma("unroll") for (int _i = 0; _i < 2; ++_i) \
;     __builtin_amdgcn_global_load_lds((const unsigned*)((const char*)(gbase) + (voff)[_i]), (LAS unsigned*)(lds + (bufoff) + ldsw + _i * 8192), 16, 0, 0); } while (0)
; #define PG8_LDA(dst, b, h) do { _Pragma("unroll") for (int m = 0; m < 4; ++m) _Pragma("unroll") for (int k = 0; k < 2; ++k) dst[m][k] = *(const LAS bf16x8*)(lds + PG8_SA(b, h) + aoff + m * 2048 + k * 1024); } while (0)
; #define PG8_LDB(dst, b, h) do { _Pragma("unroll") for (int n = 0; n < 2; ++n) _Pragma("unroll") for (int k = 0; k < 2; ++k) dst[n][k] = *(const LAS bf16x8*)(lds + PG8_SB(b, h) + boff + n * 2048 + k * 1024); } while (0)
; #define PG8_MMA(ai, bj, At, Bt) do { __builtin_amdgcn_s_setprio(1); _Pragma("unroll") for (int m = 0; m < 4; ++m) _Pragma("unroll") for (int n = 0; n < 2; ++n) _Pragma("unroll") for (int k = 0; k < 2; ++k) \
;     acc[ai][bj][m][n] = __builtin_amdgcn_mfma_f32_16x16x32_bf16(Bt[n][k], At[m][k], acc[ai][bj][m][n], 0, 0, 0); __builtin_amdgcn_s_setprio(0); } while (0)
; #define PG8_BAR __builtin_amdgcn_s_barrier()
; template <class Epi, class Sched = StaticOrder>
; DI void gemm_phase(LAS unsigned char* lds, const Gemm g, const Sched& S, const Epi& E) {
;     ...
;     const bool has_next = S.next(ui + 1, nxt);
;     const char* nA = has_next ? (const char*)g.A + (size_t)nxt.pm * tstep : cA; const char* nB = has_next ? (const char*)g.Bt + (size_t)nxt.pn * tstep : cB;
;     for (int t = 0; t < nt; t += 2) {
;       const bool last = (t == nt - 2);
;       const char* a1 = cA + (size_t)(t + 1) * kstep;
;       const char* a2 = last ? nA : cA + (size_t)(t + 2) * kstep; const char* b2 = last ? nB : cB + (size_t)(t + 2) * kstep;
;       const char* a3 = a2 + kstep; const char* b3 = b2 + kstep;
;       PG8_LDB(B0, 0, 0); PG8_SCHED; PG8_LDA(At, 0, 0); PG8_STAGE(PG8_SA(1, 1), a1 + hstep, voffA);
;       PG8_WAIT_L(8); PG8_BAR; PG8_WAIT_L(0); PG8_MMA(0, 0, At, B0); PG8_BAR; PG8_SCHED;
;       PG8_LDB(B1, 0, 1); PG8_STAGE(PG8_SB(0, 0), b2, voffB);
;       PG8_BAR; PG8_WAIT_L(0); PG8_MMA(0, 1, At, B1); PG8_BAR;
;       PG8_LDA(At, 0, 1); PG8_STAGE(PG8_SA(0, 0), a2, voffA);
;       PG8_BAR; PG8_WAIT_L(0); PG8_MMA(1, 0, At, B0); PG8_BAR; PG8_SCHED;
;       PG8_STAGE(PG8_SB(0, 1), b2 + hstep, voffB);
;       PG8_WAIT_V(6); PG8_BAR; PG8_MMA(1, 1, At, B1); PG8_BAR;
.LBB0_1424:
	ds_read_b128 v[144:147], v159
	ds_read_b128 v[148:151], v159 offset:1024
	ds_read_b128 v[152:155], v159 offset:2048
	ds_read_b128 v[162:165], v159 offset:3072
	s_add_u32 s18, s16, 0xffea0080
	s_addc_u32 s19, s17, -1
	s_cmpk_eq_i32 s47, 0x54
	s_cselect_b32 s21, s3, s19
	s_cselect_b32 s20, s2, s18
	s_cselect_b32 s19, s5, s46
	s_cselect_b32 s18, s4, s45
	s_add_i32 m0, s30, 0xc000
	ds_read_b128 v[166:169], v160
	ds_read_b128 v[170:173], v160 offset:1024
	ds_read_b128 v[174:177], v160 offset:2048
	ds_read_b128 v[178:181], v160 offset:3072
	ds_read_b128 v[182:185], v160 offset:4096
	ds_read_b128 v[186:189], v160 offset:5120
	ds_read_b128 v[190:193], v160 offset:6144
	ds_read_b128 v[194:197], v160 offset:7168
	global_load_lds_dwordx4 v136, s[16:17]
	s_add_i32 m0, s30, 0xe000
	s_nop 0
	global_load_lds_dwordx4 v138, s[16:17]
	ds_read_b128 v[198:201], v161
	ds_read_b128 v[202:205], v161 offset:1024
	ds_read_b128 v[206:209], v161 offset:2048
	ds_read_b128 v[210:213], v161 offset:3072
	s_waitcnt vmcnt(8)
	s_waitcnt lgkmcnt(4)
	s_setprio 1
	s_barrier
	v_mfma_f32_16x16x32_bf16 v[124:127], v[144:147], v[166:169], v[124:127]
	v_mfma_f32_16x16x32_bf16 v[120:123], v[152:155], v[166:169], v[120:123]
	v_mfma_f32_16x16x32_bf16 v[116:119], v[144:147], v[174:177], v[116:119]
	v_mfma_f32_16x16x32_bf16 v[112:115], v[152:155], v[174:177], v[112:115]
	v_mfma_f32_16x16x32_bf16 v[104:107], v[144:147], v[182:185], v[104:107]
	v_mfma_f32_16x16x32_bf16 v[96:99], v[152:155], v[182:185], v[96:99]
	v_mfma_f32_16x16x32_bf16 v[88:91], v[144:147], v[190:193], v[88:91]
	v_mfma_f32_16x16x32_bf16 v[80:83], v[152:155], v[190:193], v[80:83]
	v_mfma_f32_16x16x32_bf16 v[124:127], v[148:151], v[170:173], v[124:127]
	v_mfma_f32_16x16x32_bf16 v[120:123], v[162:165], v[170:173], v[120:123]
	v_mfma_f32_16x16x32_bf16 v[116:119], v[148:151], v[178:181], v[116:119]
	v_mfma_f32_16x16x32_bf16 v[112:115], v[162:165], v[178:181], v[112:115]
	v_mfma_f32_16x16x32_bf16 v[104:107], v[148:151], v[186:189], v[104:107]
	v_mfma_f32_16x16x32_bf16 v[96:99], v[162:165], v[186:189], v[96:99]
	v_mfma_f32_16x16x32_bf16 v[88:91], v[148:151], v[194:197], v[88:91]
	v_mfma_f32_16x16x32_bf16 v[80:83], v[162:165], v[194:197], v[80:83]
	s_waitcnt lgkmcnt(0)
	v_mfma_f32_16x16x32_bf16 v[108:111], v[198:201], v[166:169], v[108:111]
	v_mfma_f32_16x16x32_bf16 v[100:103], v[206:209], v[166:169], v[100:103]
	v_mfma_f32_16x16x32_bf16 v[92:95], v[198:201], v[174:177], v[92:95]
	v_mfma_f32_16x16x32_bf16 v[84:87], v[206:209], v[174:177], v[84:87]
	v_mfma_f32_16x16x32_bf16 v[76:79], v[198:201], v[182:185], v[76:79]
	v_mfma_f32_16x16x32_bf16 v[72:75], v[206:209], v[182:185], v[72:75]
	v_mfma_f32_16x16x32_bf16 v[68:71], v[198:201], v[190:193], v[68:71]
	v_mfma_f32_16x16x32_bf16 v[64:67], v[206:209], v[190:193], v[64:67]
	v_mfma_f32_16x16x32_bf16 v[108:111], v[202:205], v[170:173], v[108:111]
	v_mfma_f32_16x16x32_bf16 v[100:103], v[210:213], v[170:173], v[100:103]
	v_mfma_f32_16x16x32_bf16 v[92:95], v[202:205], v[178:181], v[92:95]
	v_mfma_f32_16x16x32_bf16 v[84:87], v[210:213], v[178:181], v[84:87]
	v_mfma_f32_16x16x32_bf16 v[76:79], v[202:205], v[186:189], v[76:79]
	v_mfma_f32_16x16x32_bf16 v[72:75], v[210:213], v[186:189], v[72:75]
	v_mfma_f32_16x16x32_bf16 v[68:71], v[202:205], v[194:197], v[68:71]
	v_mfma_f32_16x16x32_bf16 v[64:67], v[210:213], v[194:197], v[64:67]
	s_barrier
	s_setprio 0
	s_add_i32 s48, s39, s28
	s_add_u32 s98, s18, 0x80
	s_addc_u32 s99, s19, 0
	s_add_u32 s100, s20, 0x80
	s_addc_u32 s101, s21, 0
	s_mov_b32 m0, s48
	s_nop 0
	global_load_lds_dwordx4 v132, s[18:19]
	s_add_i32 m0, s48, 0x2000
	s_nop 0
	global_load_lds_dwordx4 v128, s[18:19]
	s_mov_b32 m0, s30
	ds_read_b128 v[166:169], v160 offset:16384
	ds_read_b128 v[170:173], v160 offset:17408
	ds_read_b128 v[174:177], v160 offset:18432
	ds_read_b128 v[178:181], v160 offset:19456
	ds_read_b128 v[182:185], v160 offset:20480
	ds_read_b128 v[186:189], v160 offset:21504
	ds_read_b128 v[190:193], v160 offset:22528
	ds_read_b128 v[194:197], v160 offset:23552
	global_load_lds_dwordx4 v134, s[20:21]
	s_mov_b32 m0, s31
	s_nop 0
	global_load_lds_dwordx4 v130, s[20:21]
	s_add_u32 s48, s18, 0x160000
	s_addc_u32 s49, s19, 0
	s_add_i32 s50, s40, s28
	s_waitcnt vmcnt(6)
	s_waitcnt lgkmcnt(0)
	s_setprio 1
	s_barrier
	v_mfma_f32_16x16x32_bf16 v[60:63], v[144:147], v[166:169], v[60:63]
	s_mov_b32 m0, s50
	v_mfma_f32_16x16x32_bf16 v[56:59], v[152:155], v[166:169], v[56:59]
	global_load_lds_dwordx4 v132, s[48:49]
	v_mfma_f32_16x16x32_bf16 v[52:55], v[144:147], v[174:177], v[52:55]
	s_bitset1_b32 m0, 13
	v_mfma_f32_16x16x32_bf16 v[44:47], v[152:155], v[174:177], v[44:47]
	global_load_lds_dwordx4 v128, s[48:49]
	v_mfma_f32_16x16x32_bf16 v[36:39], v[144:147], v[182:185], v[36:39]
	v_mfma_f32_16x16x32_bf16 v[28:31], v[152:155], v[182:185], v[28:31]
	v_mfma_f32_16x16x32_bf16 v[20:23], v[144:147], v[190:193], v[20:23]
	v_mfma_f32_16x16x32_bf16 v[12:15], v[152:155], v[190:193], v[12:15]
	v_mfma_f32_16x16x32_bf16 v[60:63], v[148:151], v[170:173], v[60:63]
	v_mfma_f32_16x16x32_bf16 v[56:59], v[162:165], v[170:173], v[56:59]
	v_mfma_f32_16x16x32_bf16 v[52:55], v[148:151], v[178:181], v[52:55]
	v_mfma_f32_16x16x32_bf16 v[44:47], v[162:165], v[178:181], v[44:47]
	v_mfma_f32_16x16x32_bf16 v[36:39], v[148:151], v[186:189], v[36:39]
	v_mfma_f32_16x16x32_bf16 v[28:31], v[162:165], v[186:189], v[28:31]
	v_mfma_f32_16x16x32_bf16 v[20:23], v[148:151], v[194:197], v[20:23]
	v_mfma_f32_16x16x32_bf16 v[12:15], v[162:165], v[194:197], v[12:15]
	v_mfma_f32_16x16x32_bf16 v[48:51], v[198:201], v[166:169], v[48:51]
	v_mfma_f32_16x16x32_bf16 v[40:43], v[206:209], v[166:169], v[40:43]
	v_mfma_f32_16x16x32_bf16 v[32:35], v[198:201], v[174:177], v[32:35]
	v_mfma_f32_16x16x32_bf16 v[24:27], v[206:209], v[174:177], v[24:27]
	v_mfma_f32_16x16x32_bf16 v[16:19], v[198:201], v[182:185], v[16:19]
	v_mfma_f32_16x16x32_bf16 v[8:11], v[206:209], v[182:185], v[8:11]
	v_mfma_f32_16x16x32_bf16 v[4:7], v[198:201], v[190:193], v[4:7]
	v_mfma_f32_16x16x32_bf16 v[0:3], v[206:209], v[190:193], v[0:3]
	v_mfma_f32_16x16x32_bf16 v[48:51], v[202:205], v[170:173], v[48:51]
	v_mfma_f32_16x16x32_bf16 v[40:43], v[210:213], v[170:173], v[40:43]
	v_mfma_f32_16x16x32_bf16 v[32:35], v[202:205], v[178:181], v[32:35]
	v_mfma_f32_16x16x32_bf16 v[24:27], v[210:213], v[178:181], v[24:27]
	v_mfma_f32_16x16x32_bf16 v[16:19], v[202:205], v[186:189], v[16:19]
	v_mfma_f32_16x16x32_bf16 v[8:11], v[210:213], v[186:189], v[8:11]
	v_mfma_f32_16x16x32_bf16 v[4:7], v[202:205], v[194:197], v[4:7]
	v_mfma_f32_16x16x32_bf16 v[0:3], v[210:213], v[194:197], v[0:3]
	s_barrier
; #define PG8_STAGE(bufoff, gbase, voff) do { _Pragma("unroll") for (int _i = 0; _i < 2; ++_i) \
;     __builtin_amdgcn_global_load_lds((const unsigned*)((const char*)(gbase) + (voff)[_i]), (LAS unsigned*)(lds + (bufoff) + ldsw + _i * 8192), 16, 0, 0); } while (0)
; #define PG8_LDA(dst, b, h) do { _Pragma("unroll") for (int m = 0; m < 4; ++m) _Pragma("unroll") for (int k = 0; k < 2; ++k) dst[m][k] = *(const LAS bf16x8*)(lds + PG8_SA(b, h) + aoff + m * 2048 + k * 1024); } while (0)
; #define PG8_LDB(dst, b, h) do { _Pragma("unroll") for (int n = 0; n < 2; ++n) _Pragma("unroll") for (int k = 0; k < 2; ++k) dst[n][k] = *(const LAS bf16x8*)(lds + PG8_SB(b, h) + boff + n * 2048 + k * 1024); } while (0)
; #define PG8_MMA(ai, bj, At, Bt) do { __builtin_amdgcn_s_setprio(1); _Pragma("unroll") for (int m = 0; m < 4; ++m) _Pragma("unroll") for (int n = 0; n < 2; ++n) _Pragma("unroll") for (int k = 0; k < 2; ++k) \
;     acc[ai][bj][m][n] = __builtin_amdgcn_mfma_f32_16x16x32_bf16(Bt[n][k], At[m][k], acc[ai][bj][m][n], 0, 0, 0); __builtin_amdgcn_s_setprio(0); } while (0)
; #define PG8_WAIT_V(n) asm volatile("s_waitcnt vmcnt(" #n ")" ::: "memory")
; #define PG8_WAIT_L(n) asm volatile("s_waitcnt lgkmcnt(" #n ")" ::: "memory")
; #define PG8_BAR __builtin_amdgcn_s_barrier()
; #define PG8_SCHED __builtin_amdgcn_sched_barrier(0)
; template <class Epi, class Sched = StaticOrder>
; DI void gemm_phase(LAS unsigned char* lds, const Gemm g, const Sched& S, const Epi& E) {
;     ...
;       PG8_LDB(B0, 1, 0); PG8_SCHED; PG8_LDA(At, 1, 0); PG8_STAGE(PG8_SA(0, 1), a2 + hstep, voffA);
;       PG8_WAIT_L(8); PG8_BAR; PG8_WAIT_L(0); PG8_MMA(0, 0, At, B0); PG8_BAR; PG8_SCHED;
;       PG8_LDB(B1, 1, 1); PG8_STAGE(PG8_SB(1, 0), b3, voffB);
;       PG8_BAR; PG8_WAIT_L(0); PG8_MMA(0, 1, At, B1); PG8_BAR;
;       PG8_LDA(At, 1, 1); PG8_STAGE(PG8_SA(1, 0), a3, voffA);
;       PG8_BAR; PG8_WAIT_L(0); PG8_MMA(1, 0, At, B0); PG8_BAR; PG8_SCHED;
;       PG8_STAGE(PG8_SB(1, 1), b3 + hstep, voffB);
;       PG8_WAIT_V(6); PG8_BAR; PG8_MMA(1, 1, At, B1); PG8_BAR;
	s_setprio 0
	s_add_i32 s48, 0, 0x18000
	v_add_u32_e32 v162, s48, v157
	ds_read_b128 v[144:147], v162
	ds_read_b128 v[148:151], v162 offset:1024
	ds_read_b128 v[152:155], v162 offset:2048
	ds_read_b128 v[162:165], v162 offset:3072
	s_add_u32 s20, s20, 0x160000
	s_addc_u32 s21, s21, 0
	s_mov_b32 m0, s33
	ds_read_b128 v[166:169], v160 offset:32768
	ds_read_b128 v[170:173], v160 offset:33792
	ds_read_b128 v[174:177], v160 offset:34816
	ds_read_b128 v[178:181], v160 offset:35840
	ds_read_b128 v[182:185], v160 offset:36864
	ds_read_b128 v[186:189], v160 offset:37888
	ds_read_b128 v[190:193], v160 offset:38912
	ds_read_b128 v[194:197], v160 offset:39936
	global_load_lds_dwordx4 v134, s[20:21]
	s_mov_b32 m0, s34
	s_nop 0
	global_load_lds_dwordx4 v130, s[20:21]
	s_add_i32 s20, 0, 0x1c000
	v_add_u32_e32 v210, s20, v157
	ds_read_b128 v[198:201], v210
	ds_read_b128 v[202:205], v210 offset:1024
	ds_read_b128 v[206:209], v210 offset:2048
	ds_read_b128 v[210:213], v210 offset:3072
	s_waitcnt vmcnt(8)
	s_waitcnt lgkmcnt(4)
	s_setprio 1
	s_barrier
	v_mfma_f32_16x16x32_bf16 v[124:127], v[144:147], v[166:169], v[124:127]
	v_mfma_f32_16x16x32_bf16 v[120:123], v[152:155], v[166:169], v[120:123]
	v_mfma_f32_16x16x32_bf16 v[116:119], v[144:147], v[174:177], v[116:119]
	v_mfma_f32_16x16x32_bf16 v[112:115], v[152:155], v[174:177], v[112:115]
	v_mfma_f32_16x16x32_bf16 v[104:107], v[144:147], v[182:185], v[104:107]
	v_mfma_f32_16x16x32_bf16 v[96:99], v[152:155], v[182:185], v[96:99]
	v_mfma_f32_16x16x32_bf16 v[88:91], v[144:147], v[190:193], v[88:91]
	v_mfma_f32_16x16x32_bf16 v[80:83], v[152:155], v[190:193], v[80:83]
	v_mfma_f32_16x16x32_bf16 v[124:127], v[148:151], v[170:173], v[124:127]
	v_mfma_f32_16x16x32_bf16 v[120:123], v[162:165], v[170:173], v[120:123]
	v_mfma_f32_16x16x32_bf16 v[116:119], v[148:151], v[178:181], v[116:119]
	v_mfma_f32_16x16x32_bf16 v[112:115], v[162:165], v[178:181], v[112:115]
	v_mfma_f32_16x16x32_bf16 v[104:107], v[148:151], v[186:189], v[104:107]
	v_mfma_f32_16x16x32_bf16 v[96:99], v[162:165], v[186:189], v[96:99]
	v_mfma_f32_16x16x32_bf16 v[88:91], v[148:151], v[194:197], v[88:91]
	v_mfma_f32_16x16x32_bf16 v[80:83], v[162:165], v[194:197], v[80:83]
	s_waitcnt lgkmcnt(0)
	v_mfma_f32_16x16x32_bf16 v[108:111], v[198:201], v[166:169], v[108:111]
	v_mfma_f32_16x16x32_bf16 v[100:103], v[206:209], v[166:169], v[100:103]
	v_mfma_f32_16x16x32_bf16 v[92:95], v[198:201], v[174:177], v[92:95]
	v_mfma_f32_16x16x32_bf16 v[84:87], v[206:209], v[174:177], v[84:87]
	v_mfma_f32_16x16x32_bf16 v[76:79], v[198:201], v[182:185], v[76:79]
	v_mfma_f32_16x16x32_bf16 v[72:75], v[206:209], v[182:185], v[72:75]
	v_mfma_f32_16x16x32_bf16 v[68:71], v[198:201], v[190:193], v[68:71]
	v_mfma_f32_16x16x32_bf16 v[64:67], v[206:209], v[190:193], v[64:67]
	v_mfma_f32_16x16x32_bf16 v[108:111], v[202:205], v[170:173], v[108:111]
	v_mfma_f32_16x16x32_bf16 v[100:103], v[210:213], v[170:173], v[100:103]
	v_mfma_f32_16x16x32_bf16 v[92:95], v[202:205], v[178:181], v[92:95]
	v_mfma_f32_16x16x32_bf16 v[84:87], v[210:213], v[178:181], v[84:87]
	v_mfma_f32_16x16x32_bf16 v[76:79], v[202:205], v[186:189], v[76:79]
	v_mfma_f32_16x16x32_bf16 v[72:75], v[210:213], v[186:189], v[72:75]
	v_mfma_f32_16x16x32_bf16 v[68:71], v[202:205], v[194:197], v[68:71]
	v_mfma_f32_16x16x32_bf16 v[64:67], v[210:213], v[194:197], v[64:67]
	s_barrier
	s_setprio 0
	s_add_i32 s21, s48, s28
	s_mov_b32 m0, s21
	s_nop 0
	global_load_lds_dwordx4 v132, s[98:99]
	s_add_i32 m0, s21, 0x2000
	s_nop 0
	global_load_lds_dwordx4 v128, s[98:99]
	s_mov_b32 m0, s35
	ds_read_b128 v[166:169], v160 offset:49152
	ds_read_b128 v[170:173], v160 offset:50176
	ds_read_b128 v[174:177], v160 offset:51200
	ds_read_b128 v[178:181], v160 offset:52224
	ds_read_b128 v[182:185], v160 offset:53248
	ds_read_b128 v[186:189], v160 offset:54272
	ds_read_b128 v[190:193], v160 offset:55296
	ds_read_b128 v[194:197], v160 offset:56320
	global_load_lds_dwordx4 v134, s[100:101]
	s_mov_b32 m0, s36
	s_nop 0
	global_load_lds_dwordx4 v130, s[100:101]
	s_add_u32 s18, s18, 0x160080
	s_addc_u32 s19, s19, 0
	s_add_i32 s20, s20, s28
	s_add_i32 s47, s47, 2
	s_add_u32 s16, s16, 0x100
	s_addc_u32 s17, s17, 0
	s_add_u32 s45, s45, 0x100
	s_addc_u32 s46, s46, 0
	s_cmpk_gt_u32 s47, 0x55
	s_waitcnt vmcnt(6)
	s_waitcnt lgkmcnt(0)
	s_setprio 1
	s_barrier
	v_mfma_f32_16x16x32_bf16 v[60:63], v[144:147], v[166:169], v[60:63]
	s_mov_b32 m0, s20
	v_mfma_f32_16x16x32_bf16 v[56:59], v[152:155], v[166:169], v[56:59]
	global_load_lds_dwordx4 v132, s[18:19]
	v_mfma_f32_16x16x32_bf16 v[52:55], v[144:147], v[174:177], v[52:55]
	s_bitset1_b32 m0, 13
	v_mfma_f32_16x16x32_bf16 v[44:47], v[152:155], v[174:177], v[44:47]
	global_load_lds_dwordx4 v128, s[18:19]
	v_mfma_f32_16x16x32_bf16 v[36:39], v[144:147], v[182:185], v[36:39]
	v_mfma_f32_16x16x32_bf16 v[28:31], v[152:155], v[182:185], v[28:31]
	v_mfma_f32_16x16x32_bf16 v[20:23], v[144:147], v[190:193], v[20:23]
	v_mfma_f32_16x16x32_bf16 v[12:15], v[152:155], v[190:193], v[12:15]
	v_mfma_f32_16x16x32_bf16 v[60:63], v[148:151], v[170:173], v[60:63]
	v_mfma_f32_16x16x32_bf16 v[56:59], v[162:165], v[170:173], v[56:59]
	v_mfma_f32_16x16x32_bf16 v[52:55], v[148:151], v[178:181], v[52:55]
	v_mfma_f32_16x16x32_bf16 v[44:47], v[162:165], v[178:181], v[44:47]
	v_mfma_f32_16x16x32_bf16 v[36:39], v[148:151], v[186:189], v[36:39]
	v_mfma_f32_16x16x32_bf16 v[28:31], v[162:165], v[186:189], v[28:31]
	v_mfma_f32_16x16x32_bf16 v[20:23], v[148:151], v[194:197], v[20:23]
	v_mfma_f32_16x16x32_bf16 v[12:15], v[162:165], v[194:197], v[12:15]
	v_mfma_f32_16x16x32_bf16 v[48:51], v[198:201], v[166:169], v[48:51]
	v_mfma_f32_16x16x32_bf16 v[40:43], v[206:209], v[166:169], v[40:43]
	v_mfma_f32_16x16x32_bf16 v[32:35], v[198:201], v[174:177], v[32:35]
	v_mfma_f32_16x16x32_bf16 v[24:27], v[206:209], v[174:177], v[24:27]
	v_mfma_f32_16x16x32_bf16 v[16:19], v[198:201], v[182:185], v[16:19]
	v_mfma_f32_16x16x32_bf16 v[8:11], v[206:209], v[182:185], v[8:11]
	v_mfma_f32_16x16x32_bf16 v[4:7], v[198:201], v[190:193], v[4:7]
	v_mfma_f32_16x16x32_bf16 v[0:3], v[206:209], v[190:193], v[0:3]
	v_mfma_f32_16x16x32_bf16 v[48:51], v[202:205], v[170:173], v[48:51]
	v_mfma_f32_16x16x32_bf16 v[40:43], v[210:213], v[170:173], v[40:43]
	v_mfma_f32_16x16x32_bf16 v[32:35], v[202:205], v[178:181], v[32:35]
	v_mfma_f32_16x16x32_bf16 v[24:27], v[210:213], v[178:181], v[24:27]
	v_mfma_f32_16x16x32_bf16 v[16:19], v[202:205], v[186:189], v[16:19]
	v_mfma_f32_16x16x32_bf16 v[8:11], v[210:213], v[186:189], v[8:11]
	v_mfma_f32_16x16x32_bf16 v[4:7], v[202:205], v[194:197], v[4:7]
	v_mfma_f32_16x16x32_bf16 v[0:3], v[210:213], v[194:197], v[0:3]
	s_barrier
;   DI void operator()(const f32x4 (&acc)[2][2][4][2], const Unit& u, int wr, int wc, int fr, int fq) const {
;     const int row0 = u.pm * BM + wr * 64 + fr, col0 = u.pn * BM + wc * 32 + 8 * fq;
; #pragma unroll
;     for (int ai = 0; ai < 2; ++ai) {
;       f32x4 bv[4][2][2];
; #pragma unroll
;       for (int m = 0; m < 4; ++m)
; #pragma unroll
;         for (int bj = 0; bj < 2; ++bj) {
;           const float* bp = base + (size_t)(row0 + ai * HALF + m * 16) * 2048 + col0 + bj * HALF;
;           bv[m][bj][0] = *(const f32x4*)bp; bv[m][bj][1] = *(const f32x4*)(bp + 4);
;         }
; #pragma unroll
;       for (int m = 0; m < 4; ++m) {
;         const int row = row0 + ai * HALF + m * 16;
;         const size_t off = (size_t)row * 2048 + col0;
;         float ss = 0.f;
; #pragma unroll
;         for (int bj = 0; bj < 2; ++bj) {
;           const f32x4 v0 = acc[ai][bj][m][0] + bv[m][bj][0], v1 = acc[ai][bj][m][1] + bv[m][bj][1];
;           *(f32x4*)(C + off + bj * HALF) = v0; *(f32x4*)(C + off + bj * HALF + 4) = v1;
	s_setprio 0
	s_cbranch_scc0 .LBB0_1424
	v_lshl_or_b32 v144, s44, 8, v158
	v_lshl_add_u32 v154, s43, 8, v156
	v_ashrrev_i32_e32 v145, 31, v144
	v_lshlrev_b64 v[144:145], 2, v[144:145]
	v_ashrrev_i32_e32 v155, 31, v154
	v_lshl_add_u64 v[146:147], s[54:55], 0, v[144:145]
	v_lshlrev_b64 v[148:149], 13, v[154:155]
	v_or_b32_e32 v174, 16, v154
	v_lshl_add_u64 v[170:171], v[146:147], 0, v[148:149]
	v_ashrrev_i32_e32 v175, 31, v174
	global_load_dwordx4 v[150:153], v[170:171], off offset:16
	global_load_dwordx4 v[162:165], v[170:171], off
	global_load_dwordx4 v[166:169], v[170:171], off offset:528
	s_nop 0
	global_load_dwordx4 v[170:173], v[170:171], off offset:512
	v_lshlrev_b64 v[222:223], 13, v[174:175]
	v_or_b32_e32 v190, 32, v154
	v_lshl_add_u64 v[186:187], v[146:147], 0, v[222:223]
	v_ashrrev_i32_e32 v191, 31, v190
	global_load_dwordx4 v[174:177], v[186:187], off offset:16
	global_load_dwordx4 v[178:181], v[186:187], off
	global_load_dwordx4 v[182:185], v[186:187], off offset:528
	s_nop 0
	global_load_dwordx4 v[186:189], v[186:187], off offset:512
	v_lshlrev_b64 v[224:225], 13, v[190:191]
	v_or_b32_e32 v154, 48, v154
	v_lshl_add_u64 v[202:203], v[146:147], 0, v[224:225]
	v_ashrrev_i32_e32 v155, 31, v154
	global_load_dwordx4 v[190:193], v[202:203], off offset:16
	global_load_dwordx4 v[194:197], v[202:203], off
	global_load_dwordx4 v[198:201], v[202:203], off offset:528
	s_nop 0
	global_load_dwordx4 v[202:205], v[202:203], off offset:512
	v_lshlrev_b64 v[154:155], 13, v[154:155]
	v_lshl_add_u64 v[218:219], v[146:147], 0, v[154:155]
	global_load_dwordx4 v[206:209], v[218:219], off offset:16
	global_load_dwordx4 v[210:213], v[218:219], off
	global_load_dwordx4 v[214:217], v[218:219], off offset:528
	s_nop 0
	global_load_dwordx4 v[218:221], v[218:219], off offset:512
	s_and_b64 vcc, exec, s[0:1]
	s_mov_b32 s44, s41
	s_mov_b32 s43, s42
	s_mov_b64 s[18:19], s[4:5]
	s_mov_b64 s[16:17], s[2:3]
	s_waitcnt vmcnt(0)
	v_pk_add_f32 v[120:121], v[120:121], v[150:151]
	v_lshl_add_u64 v[150:151], s[54:55], 0, v[148:149]
	v_pk_add_f32 v[126:127], v[126:127], v[164:165]
	v_pk_add_f32 v[124:125], v[124:125], v[162:163]
	v_lshl_add_u64 v[150:151], v[150:151], 0, v[144:145]
	v_pk_add_f32 v[110:111], v[110:111], v[172:173]
	v_pk_add_f32 v[108:109], v[108:109], v[170:171]
	v_pk_add_f32 v[122:123], v[122:123], v[152:153]
	global_store_dwordx4 v[150:151], v[124:127], off
	global_store_dwordx4 v[150:151], v[120:123], off offset:16
	v_pk_add_f32 v[102:103], v[102:103], v[168:169]
	v_pk_add_f32 v[100:101], v[100:101], v[166:167]
	global_store_dwordx4 v[150:151], v[108:111], off offset:512
	global_store_dwordx4 v[150:151], v[100:103], off offset:528
	v_pk_add_f32 v[94:95], v[94:95], v[188:189]
	v_pk_add_f32 v[108:109], v[112:113], v[174:175]
	v_lshl_add_u64 v[112:113], s[54:55], 0, v[222:223]
	v_pk_add_f32 v[102:103], v[118:119], v[180:181]
	v_pk_add_f32 v[100:101], v[116:117], v[178:179]
	v_lshl_add_u64 v[112:113], v[112:113], 0, v[144:145]
	v_pk_add_f32 v[92:93], v[92:93], v[186:187]
	v_pk_add_f32 v[110:111], v[114:115], v[176:177]
	global_store_dwordx4 v[112:113], v[100:103], off
	global_store_dwordx4 v[112:113], v[108:111], off offset:16
	v_pk_add_f32 v[86:87], v[86:87], v[184:185]
	v_pk_add_f32 v[84:85], v[84:85], v[182:183]
	global_store_dwordx4 v[112:113], v[92:95], off offset:512
	global_store_dwordx4 v[112:113], v[84:87], off offset:528
	v_pk_add_f32 v[78:79], v[78:79], v[204:205]
	v_pk_add_f32 v[92:93], v[96:97], v[190:191]
	v_lshl_add_u64 v[96:97], s[54:55], 0, v[224:225]
	v_pk_add_f32 v[86:87], v[106:107], v[196:197]
	v_pk_add_f32 v[84:85], v[104:105], v[194:195]
	v_lshl_add_u64 v[96:97], v[96:97], 0, v[144:145]
	v_pk_add_f32 v[76:77], v[76:77], v[202:203]
	v_pk_add_f32 v[94:95], v[98:99], v[192:193]
	global_store_dwordx4 v[96:97], v[84:87], off
	global_store_dwordx4 v[96:97], v[92:95], off offset:16
	v_pk_add_f32 v[74:75], v[74:75], v[200:201]
	v_pk_add_f32 v[72:73], v[72:73], v[198:199]
	global_store_dwordx4 v[96:97], v[76:79], off offset:512
	global_store_dwordx4 v[96:97], v[72:75], off offset:528
	v_pk_add_f32 v[70:71], v[70:71], v[220:221]
	v_pk_add_f32 v[76:77], v[80:81], v[206:207]
	v_lshl_add_u64 v[80:81], s[54:55], 0, v[154:155]
	v_pk_add_f32 v[74:75], v[90:91], v[212:213]
	v_pk_add_f32 v[72:73], v[88:89], v[210:211]
	v_lshl_add_u64 v[80:81], v[80:81], 0, v[144:145]
	v_pk_add_f32 v[68:69], v[68:69], v[218:219]
	v_pk_add_f32 v[64:65], v[64:65], v[214:215]
	v_lshl_add_u64 v[154:155], v[148:149], 0, s[10:11]
	v_pk_add_f32 v[78:79], v[82:83], v[208:209]
	global_store_dwordx4 v[80:81], v[72:75], off
	global_store_dwordx4 v[80:81], v[76:79], off offset:16
	v_pk_add_f32 v[66:67], v[66:67], v[216:217]
	global_store_dwordx4 v[80:81], v[68:71], off offset:512
	global_store_dwordx4 v[80:81], v[64:67], off offset:528
	v_lshl_add_u64 v[152:153], v[148:149], 0, s[12:13]
	v_lshl_add_u64 v[150:151], v[148:149], 0, s[14:15]
	v_lshl_add_u64 v[64:65], v[146:147], 0, v[154:155]
	global_load_dwordx4 v[108:111], v[64:65], off offset:16
	global_load_dwordx4 v[120:123], v[64:65], off
	global_load_dwordx4 v[92:95], v[64:65], off offset:528
	global_load_dwordx4 v[100:103], v[64:65], off offset:512
	v_lshl_add_u64 v[64:65], v[146:147], 0, v[152:153]
	global_load_dwordx4 v[88:91], v[64:65], off offset:16
	global_load_dwordx4 v[96:99], v[64:65], off
	global_load_dwordx4 v[76:79], v[64:65], off offset:528
	global_load_dwordx4 v[84:87], v[64:65], off offset:512
	v_lshl_add_u64 v[68:69], v[146:147], 0, v[150:151]
	global_load_dwordx4 v[72:75], v[68:69], off offset:16
	global_load_dwordx4 v[80:83], v[68:69], off
	global_load_dwordx4 v[64:67], v[68:69], off offset:528
	s_nop 0
	global_load_dwordx4 v[68:71], v[68:69], off offset:512
	v_lshl_add_u64 v[148:149], v[148:149], 0, s[6:7]
	v_lshl_add_u64 v[112:113], v[146:147], 0, v[148:149]
	global_load_dwordx4 v[116:119], v[112:113], off offset:16
	global_load_dwordx4 v[124:127], v[112:113], off
	global_load_dwordx4 v[104:107], v[112:113], off offset:528
	s_nop 0
	global_load_dwordx4 v[112:115], v[112:113], off offset:512
	s_waitcnt vmcnt(0)
; #define PG8_WAIT_V(n) asm volatile("s_waitcnt vmcnt(" #n ")" ::: "memory")
; #define PG8_BAR __builtin_amdgcn_s_barrier()
;   DI void operator()(const f32x4 (&acc)[2][2][4][2], const Unit& u, int wr, int wc, int fr, int fq) const {
;     ...
;           const float* bp = base + (size_t)(row0 + ai * HALF + m * 16) * 2048 + col0 + bj * HALF;
;           bv[m][bj][0] = *(const f32x4*)bp; bv[m][bj][1] = *(const f32x4*)(bp + 4);
;         }
; #pragma unroll
;       for (int m = 0; m < 4; ++m) {
;         const int row = row0 + ai * HALF + m * 16;
;         const size_t off = (size_t)row * 2048 + col0;
;         float ss = 0.f;
; #pragma unroll
;         for (int bj = 0; bj < 2; ++bj) {
;           const f32x4 v0 = acc[ai][bj][m][0] + bv[m][bj][0], v1 = acc[ai][bj][m][1] + bv[m][bj][1];
;           *(f32x4*)(C + off + bj * HALF) = v0; *(f32x4*)(C + off + bj * HALF + 4) = v1;
; template <class Epi, class Sched = StaticOrder>
; DI void gemm_phase(LAS unsigned char* lds, const Gemm g, const Sched& S, const Epi& E) {
;     ...
;     if (!has_next) break;
; #pragma unroll
;     for (int a = 0; a < 2; ++a)
; #pragma unroll
;       for (int b = 0; b < 2; ++b)
; #pragma unroll
;         for (int m = 0; m < 4; ++m)
; #pragma unroll
;           for (int n = 0; n < 2; ++n) acc[a][b][m][n] = (f32x4){0.f, 0.f, 0.f, 0.f};
;     cur = nxt; cA = nA; cB = nB; ++ui;
;   }
;   PG8_WAIT_V(0);
;   if (wr == 0) PG8_BAR;
;   PG8_BAR;
	v_pk_add_f32 v[56:57], v[56:57], v[108:109]
	v_lshl_add_u64 v[108:109], s[54:55], 0, v[154:155]
	v_pk_add_f32 v[62:63], v[62:63], v[122:123]
	v_pk_add_f32 v[60:61], v[60:61], v[120:121]
	v_lshl_add_u64 v[108:109], v[108:109], 0, v[144:145]
	v_pk_add_f32 v[50:51], v[50:51], v[102:103]
	v_pk_add_f32 v[48:49], v[48:49], v[100:101]
	v_pk_add_f32 v[58:59], v[58:59], v[110:111]
	global_store_dwordx4 v[108:109], v[60:63], off
	global_store_dwordx4 v[108:109], v[56:59], off offset:16
	v_pk_add_f32 v[42:43], v[42:43], v[94:95]
	v_pk_add_f32 v[40:41], v[40:41], v[92:93]
	global_store_dwordx4 v[108:109], v[48:51], off offset:512
	global_store_dwordx4 v[108:109], v[40:43], off offset:528
	v_pk_add_f32 v[34:35], v[34:35], v[86:87]
	v_lshl_add_u64 v[48:49], s[54:55], 0, v[152:153]
	v_pk_add_f32 v[42:43], v[54:55], v[98:99]
	v_pk_add_f32 v[40:41], v[52:53], v[96:97]
	v_lshl_add_u64 v[48:49], v[48:49], 0, v[144:145]
	v_pk_add_f32 v[32:33], v[32:33], v[84:85]
	v_pk_add_f32 v[46:47], v[46:47], v[90:91]
	v_pk_add_f32 v[44:45], v[44:45], v[88:89]
	global_store_dwordx4 v[48:49], v[40:43], off
	global_store_dwordx4 v[48:49], v[44:47], off offset:16
	v_pk_add_f32 v[26:27], v[26:27], v[78:79]
	v_pk_add_f32 v[24:25], v[24:25], v[76:77]
	global_store_dwordx4 v[48:49], v[32:35], off offset:512
	global_store_dwordx4 v[48:49], v[24:27], off offset:528
	v_pk_add_f32 v[18:19], v[18:19], v[70:71]
	v_lshl_add_u64 v[32:33], s[54:55], 0, v[150:151]
	v_pk_add_f32 v[26:27], v[38:39], v[82:83]
	v_pk_add_f32 v[24:25], v[36:37], v[80:81]
	v_lshl_add_u64 v[32:33], v[32:33], 0, v[144:145]
	v_pk_add_f32 v[16:17], v[16:17], v[68:69]
	v_pk_add_f32 v[30:31], v[30:31], v[74:75]
	v_pk_add_f32 v[28:29], v[28:29], v[72:73]
	global_store_dwordx4 v[32:33], v[24:27], off
	global_store_dwordx4 v[32:33], v[28:31], off offset:16
	v_pk_add_f32 v[10:11], v[10:11], v[66:67]
	v_pk_add_f32 v[8:9], v[8:9], v[64:65]
	global_store_dwordx4 v[32:33], v[16:19], off offset:512
	global_store_dwordx4 v[32:33], v[8:11], off offset:528
	v_pk_add_f32 v[6:7], v[6:7], v[114:115]
	v_lshl_add_u64 v[16:17], s[54:55], 0, v[148:149]
	v_pk_add_f32 v[10:11], v[22:23], v[126:127]
	v_pk_add_f32 v[8:9], v[20:21], v[124:125]
	v_lshl_add_u64 v[16:17], v[16:17], 0, v[144:145]
	v_pk_add_f32 v[4:5], v[4:5], v[112:113]
	v_pk_add_f32 v[14:15], v[14:15], v[118:119]
	v_pk_add_f32 v[12:13], v[12:13], v[116:117]
	global_store_dwordx4 v[16:17], v[8:11], off
	global_store_dwordx4 v[16:17], v[12:15], off offset:16
	v_pk_add_f32 v[2:3], v[2:3], v[106:107]
	v_pk_add_f32 v[0:1], v[0:1], v[104:105]
	global_store_dwordx4 v[16:17], v[4:7], off offset:512
	global_store_dwordx4 v[16:17], v[0:3], off offset:528
	s_cbranch_vccz .LBB0_1417
	s_waitcnt vmcnt(0)
	s_cmpk_gt_u32 s23, 0xff
	s_cbranch_scc1 .LBB0_1428
	s_barrier
